# non-temporal (nt) policy on the one-time streaming reads of phase A (f32 weights) and phase B (x rows) so the GEMM operands stay cache-resident
# speedup vs baseline: 1.0086x; 1.0086x over previous
.LBB0_39:
	s_lshl_b32 s4, s0, 6
	s_cmp_gt_i32 s10, -1
	s_cselect_b64 vcc, -1, 0
	v_add_u32_e32 v19, s10, v59
	v_add_u32_e32 v21, s9, v9
	s_and_b64 s[40:41], vcc, s[38:39]
	v_cndmask_b32_e64 v26, v21, v19, s[40:41]
	v_or_b32_e32 v19, s4, v11
	v_ashrrev_i32_e32 v27, 31, v26
	v_lshl_add_u64 v[32:33], v[26:27], 2, s[42:43]
	v_or_b32_e32 v21, 4, v19
	v_mad_i64_i32 v[64:65], s[10:11], v21, s24, v[32:33]
	v_or_b32_e32 v21, 8, v19
	v_mad_i64_i32 v[68:69], s[10:11], v21, s24, v[32:33]
	v_or_b32_e32 v21, 12, v19
	v_mad_i64_i32 v[72:73], s[10:11], v21, s24, v[32:33]
	v_or_b32_e32 v21, 16, v19
	v_mad_i64_i32 v[76:77], s[10:11], v21, s24, v[32:33]
	v_or_b32_e32 v21, 20, v19
	v_mad_i64_i32 v[80:81], s[10:11], v21, s24, v[32:33]
	v_or_b32_e32 v21, 24, v19
	v_mad_i64_i32 v[84:85], s[10:11], v21, s24, v[32:33]
	v_or_b32_e32 v21, 28, v19
	v_mad_i64_i32 v[88:89], s[10:11], v21, s24, v[32:33]
	v_or_b32_e32 v21, 32, v19
	v_mad_i64_i32 v[92:93], s[10:11], v21, s24, v[32:33]
	v_or_b32_e32 v21, 36, v19
	v_mad_i64_i32 v[96:97], s[10:11], v21, s24, v[32:33]
	v_or_b32_e32 v21, 40, v19
	v_mad_i64_i32 v[100:101], s[10:11], v21, s24, v[32:33]
	v_or_b32_e32 v21, 44, v19
	v_mad_i64_i32 v[104:105], s[10:11], v21, s24, v[32:33]
	v_or_b32_e32 v21, 48, v19
	v_mad_i64_i32 v[26:27], s[10:11], v19, s24, v[32:33]
	v_mad_i64_i32 v[108:109], s[10:11], v21, s24, v[32:33]
	v_or_b32_e32 v21, 52, v19
	global_load_dwordx4 v[26:29], v[26:27], off nt
	s_nop 0
	global_load_dwordx4 v[64:67], v[64:65], off nt
	s_nop 0
	global_load_dwordx4 v[68:71], v[68:69], off nt
	s_nop 0
	global_load_dwordx4 v[72:75], v[72:73], off nt
	s_nop 0
	global_load_dwordx4 v[76:79], v[76:77], off nt
	s_nop 0
	global_load_dwordx4 v[80:83], v[80:81], off nt
	s_nop 0
	global_load_dwordx4 v[84:87], v[84:85], off nt
	s_nop 0
	global_load_dwordx4 v[88:91], v[88:89], off nt
	s_nop 0
	global_load_dwordx4 v[92:95], v[92:93], off nt
	s_nop 0
	global_load_dwordx4 v[96:99], v[96:97], off nt
	s_nop 0
	global_load_dwordx4 v[100:103], v[100:101], off nt
	s_nop 0
	global_load_dwordx4 v[104:107], v[104:105], off nt
	v_mad_i64_i32 v[112:113], s[10:11], v21, s24, v[32:33]
	v_or_b32_e32 v21, 56, v19
	global_load_dwordx4 v[108:111], v[108:109], off nt
	s_nop 0
	global_load_dwordx4 v[112:115], v[112:113], off nt
	v_mad_i64_i32 v[116:117], s[10:11], v21, s24, v[32:33]
	v_or_b32_e32 v19, 60, v19
	v_mad_i64_i32 v[32:33], s[10:11], v19, s24, v[32:33]
	global_load_dwordx4 v[116:119], v[116:117], off nt
	s_nop 0
	global_load_dwordx4 v[120:123], v[32:33], off nt
	v_add_u32_e32 v19, v31, v34
	v_add_u32_e32 v21, v31, v35
	v_add_u32_e32 v23, v31, v36
	v_add_u32_e32 v25, v31, v37
	v_add_u32_e32 v30, v31, v38
	v_add_u32_e32 v32, v31, v39
	s_ashr_i32 s5, s4, 31
	s_waitcnt vmcnt(15)
	ds_write_b128 v19, v[26:29]
	s_waitcnt vmcnt(14)
	ds_write_b128 v19, v[64:67] offset:1088
	s_waitcnt vmcnt(13)
	ds_write_b128 v21, v[68:71] offset:2176
	s_waitcnt vmcnt(12)
	ds_write_b128 v21, v[72:75] offset:3264
	s_waitcnt vmcnt(11)
	ds_write_b128 v23, v[76:79] offset:4352
	s_waitcnt vmcnt(10)
	ds_write_b128 v23, v[80:83] offset:5440
	s_waitcnt vmcnt(9)
	ds_write_b128 v25, v[84:87] offset:6528
	s_waitcnt vmcnt(8)
	ds_write_b128 v25, v[88:91] offset:7616
	s_waitcnt vmcnt(7)
	ds_write_b128 v30, v[92:95] offset:8704
	s_waitcnt vmcnt(6)
	ds_write_b128 v30, v[96:99] offset:9792
	s_waitcnt vmcnt(5)
	ds_write_b128 v32, v[100:103] offset:10880
	s_waitcnt vmcnt(4)
	ds_write_b128 v32, v[104:107] offset:11968
	v_add_u32_e32 v19, v31, v40
	s_waitcnt vmcnt(3)
	ds_write_b128 v19, v[108:111] offset:13056
	s_waitcnt vmcnt(2)
	ds_write_b128 v19, v[112:115] offset:14144
	v_add_u32_e32 v19, v31, v41
	s_waitcnt vmcnt(1)
	ds_write_b128 v19, v[116:119] offset:15232
	s_waitcnt vmcnt(0)
	ds_write_b128 v19, v[120:123] offset:16320
	s_waitcnt lgkmcnt(0)
	ds_read2_b32 v[28:29], v43 offset1:68
	ds_read2_b32 v[26:27], v43 offset0:136 offset1:204
	v_cndmask_b32_e32 v30, v24, v17, vcc
	v_add_u32_e32 v17, 0x400, v43
	ds_read2_b32 v[66:67], v17 offset0:16 offset1:84
	ds_read2_b32 v[68:69], v17 offset0:152 offset1:220
	s_waitcnt lgkmcnt(3)
	v_mov_b32_e32 v64, v28
	s_waitcnt lgkmcnt(2)
	v_mov_b32_e32 v65, v26
	v_mov_b32_e32 v26, v29
	v_pk_mul_f32 v[64:65], v[24:25], v[64:65] op_sel_hi:[0,1]
	v_pk_mul_f32 v[26:27], v[24:25], v[26:27] op_sel_hi:[0,1]
	s_waitcnt lgkmcnt(1)
	v_mov_b32_e32 v28, v66
	s_waitcnt lgkmcnt(0)
	v_mov_b32_e32 v29, v68
	v_mov_b32_e32 v68, v67
	v_pk_mul_f32 v[28:29], v[24:25], v[28:29] op_sel_hi:[0,1]
	v_pk_mul_f32 v[66:67], v[24:25], v[68:69] op_sel_hi:[0,1]
	v_bfe_u32 v21, v27, 16, 1
	v_bfe_u32 v23, v26, 16, 1
	v_bfe_u32 v25, v64, 16, 1
	v_add3_u32 v23, v26, v23, s22
	v_add3_u32 v21, v27, v21, s22
	v_bfe_u32 v26, v65, 16, 1
	v_bfe_u32 v27, v28, 16, 1
	v_bfe_u32 v63, v29, 16, 1
	v_add3_u32 v25, v64, v25, s22
	v_or_b32_e32 v64, s6, v42
	v_bfe_u32 v17, v67, 16, 1
	v_bfe_u32 v19, v66, 16, 1
	v_add3_u32 v29, v29, v63, s22
	v_add3_u32 v27, v28, v27, s22
	v_add3_u32 v26, v65, v26, s22
	v_ashrrev_i32_e32 v65, 31, v64
	v_lshl_add_u64 v[32:33], s[4:5], 1, v[14:15]
	v_add3_u32 v19, v66, v19, s22
	v_add3_u32 v17, v67, v17, s22
	v_lshrrev_b32_e32 v25, 16, v25
	v_lshrrev_b32_e32 v26, 16, v26
	v_lshrrev_b32_e32 v27, 16, v27
	v_lshrrev_b32_e32 v28, 16, v29
	v_lshlrev_b64 v[64:65], 13, v[64:65]
	v_and_or_b32 v29, v17, s23, v28
	v_and_or_b32 v28, v19, s23, v27
	v_and_or_b32 v27, v21, s23, v26
	v_and_or_b32 v26, v23, s23, v25
	v_lshl_add_u64 v[64:65], v[32:33], 0, v[64:65]
	ds_read2_b32 v[66:67], v45 offset1:68
	ds_read2_b32 v[68:69], v45 offset0:136 offset1:204
	global_store_dwordx4 v[64:65], v[26:29], off
	v_add_u32_e32 v17, 0x400, v45
	ds_read2_b32 v[28:29], v17 offset0:16 offset1:84
	ds_read2_b32 v[64:65], v17 offset0:152 offset1:220
	s_waitcnt lgkmcnt(3)
	v_mov_b32_e32 v26, v66
	s_waitcnt lgkmcnt(2)
	v_mov_b32_e32 v27, v68
	v_mov_b32_e32 v68, v67
	v_pk_mul_f32 v[66:67], v[24:25], v[68:69] op_sel_hi:[0,1]
	s_waitcnt lgkmcnt(0)
	v_mov_b32_e32 v69, v64
	v_mov_b32_e32 v64, v29
	v_mov_b32_e32 v68, v28
	v_pk_mul_f32 v[28:29], v[24:25], v[64:65] op_sel_hi:[0,1]
	v_pk_mul_f32 v[26:27], v[24:25], v[26:27] op_sel_hi:[0,1]
	v_pk_mul_f32 v[68:69], v[24:25], v[68:69] op_sel_hi:[0,1]
	v_bfe_u32 v17, v29, 16, 1
	v_bfe_u32 v19, v28, 16, 1
	v_add3_u32 v19, v28, v19, s22
	v_add3_u32 v17, v29, v17, s22
	v_bfe_u32 v25, v26, 16, 1
	v_bfe_u32 v28, v27, 16, 1
	v_bfe_u32 v29, v68, 16, 1
	v_bfe_u32 v63, v69, 16, 1
	v_or_b32_e32 v64, s6, v44
	v_bfe_u32 v21, v67, 16, 1
	v_bfe_u32 v23, v66, 16, 1
	v_add3_u32 v63, v69, v63, s22
	v_add3_u32 v29, v68, v29, s22
	v_add3_u32 v27, v27, v28, s22
	v_add3_u32 v25, v26, v25, s22
	v_ashrrev_i32_e32 v65, 31, v64
	v_add3_u32 v23, v66, v23, s22
	v_add3_u32 v21, v67, v21, s22
	v_lshrrev_b32_e32 v25, 16, v25
	v_lshrrev_b32_e32 v26, 16, v27
	v_lshrrev_b32_e32 v27, 16, v29
	v_lshrrev_b32_e32 v28, 16, v63
	v_lshlrev_b64 v[64:65], 13, v[64:65]
	v_and_or_b32 v29, v17, s23, v28
	v_and_or_b32 v28, v19, s23, v27
	v_and_or_b32 v27, v21, s23, v26
	v_and_or_b32 v26, v23, s23, v25
	v_lshl_add_u64 v[64:65], v[32:33], 0, v[64:65]
	ds_read2_b32 v[66:67], v47 offset1:68
	ds_read2_b32 v[68:69], v47 offset0:136 offset1:204
	global_store_dwordx4 v[64:65], v[26:29], off
	v_add_u32_e32 v17, 0x400, v47
	ds_read2_b32 v[28:29], v17 offset0:16 offset1:84
	ds_read2_b32 v[64:65], v17 offset0:152 offset1:220
	s_waitcnt lgkmcnt(3)
	v_mov_b32_e32 v26, v66
	s_waitcnt lgkmcnt(2)
	v_mov_b32_e32 v27, v68
	v_mov_b32_e32 v68, v67
	v_pk_mul_f32 v[66:67], v[24:25], v[68:69] op_sel_hi:[0,1]
	s_waitcnt lgkmcnt(0)
	v_mov_b32_e32 v69, v64
	v_mov_b32_e32 v64, v29
	v_mov_b32_e32 v68, v28
	v_pk_mul_f32 v[28:29], v[24:25], v[64:65] op_sel_hi:[0,1]
	v_pk_mul_f32 v[26:27], v[24:25], v[26:27] op_sel_hi:[0,1]
	v_pk_mul_f32 v[68:69], v[24:25], v[68:69] op_sel_hi:[0,1]
	v_bfe_u32 v17, v29, 16, 1
	v_bfe_u32 v19, v28, 16, 1
	v_add3_u32 v19, v28, v19, s22
	v_add3_u32 v17, v29, v17, s22
	v_bfe_u32 v25, v26, 16, 1
	v_bfe_u32 v28, v27, 16, 1
	v_bfe_u32 v29, v68, 16, 1
	v_bfe_u32 v63, v69, 16, 1
	v_or_b32_e32 v64, s6, v46
	v_bfe_u32 v21, v67, 16, 1
	v_bfe_u32 v23, v66, 16, 1
	v_add3_u32 v63, v69, v63, s22
	v_add3_u32 v29, v68, v29, s22
	v_add3_u32 v27, v27, v28, s22
	v_add3_u32 v25, v26, v25, s22
	v_ashrrev_i32_e32 v65, 31, v64
	v_add3_u32 v23, v66, v23, s22
	v_add3_u32 v21, v67, v21, s22
	v_lshrrev_b32_e32 v25, 16, v25
	v_lshrrev_b32_e32 v26, 16, v27
	v_lshrrev_b32_e32 v27, 16, v29
	v_lshrrev_b32_e32 v28, 16, v63
	v_lshlrev_b64 v[64:65], 13, v[64:65]
	v_and_or_b32 v29, v17, s23, v28
	v_and_or_b32 v28, v19, s23, v27
	v_and_or_b32 v27, v21, s23, v26
	v_and_or_b32 v26, v23, s23, v25
	v_lshl_add_u64 v[64:65], v[32:33], 0, v[64:65]
	ds_read2_b32 v[66:67], v49 offset1:68
	ds_read2_b32 v[68:69], v49 offset0:136 offset1:204
	global_store_dwordx4 v[64:65], v[26:29], off
	v_add_u32_e32 v17, 0x400, v49
	ds_read2_b32 v[28:29], v17 offset0:16 offset1:84
	ds_read2_b32 v[64:65], v17 offset0:152 offset1:220
	s_waitcnt lgkmcnt(3)
	v_mov_b32_e32 v26, v66
	s_waitcnt lgkmcnt(2)
	v_mov_b32_e32 v27, v68
	v_mov_b32_e32 v68, v67
	v_pk_mul_f32 v[66:67], v[24:25], v[68:69] op_sel_hi:[0,1]
	s_waitcnt lgkmcnt(1)
	v_mov_b32_e32 v68, v28
	s_waitcnt lgkmcnt(0)
	v_mov_b32_e32 v69, v64
	v_mov_b32_e32 v64, v29
	v_pk_mul_f32 v[26:27], v[24:25], v[26:27] op_sel_hi:[0,1]
	v_pk_mul_f32 v[68:69], v[24:25], v[68:69] op_sel_hi:[0,1]
	v_pk_mul_f32 v[24:25], v[24:25], v[64:65] op_sel_hi:[0,1]
	v_bfe_u32 v19, v24, 16, 1
	v_bfe_u32 v28, v68, 16, 1
	v_bfe_u32 v17, v25, 16, 1
	v_add3_u32 v19, v24, v19, s22
	v_bfe_u32 v24, v26, 16, 1
	v_bfe_u32 v29, v69, 16, 1
	v_add3_u32 v28, v68, v28, s22
	v_add3_u32 v17, v25, v17, s22
	v_bfe_u32 v25, v27, 16, 1
	v_add3_u32 v29, v69, v29, s22
	v_add3_u32 v24, v26, v24, s22
	v_lshrrev_b32_e32 v26, 16, v28
	v_or_b32_e32 v28, s6, v48
	v_bfe_u32 v21, v67, 16, 1
	v_bfe_u32 v23, v66, 16, 1
	v_add3_u32 v25, v27, v25, s22
	v_lshrrev_b32_e32 v27, 16, v29
	v_ashrrev_i32_e32 v29, 31, v28
	v_add3_u32 v23, v66, v23, s22
	v_add3_u32 v21, v67, v21, s22
	v_lshrrev_b32_e32 v24, 16, v24
	v_lshrrev_b32_e32 v25, 16, v25
	v_lshlrev_b64 v[28:29], 13, v[28:29]
	v_and_or_b32 v27, v17, s23, v27
	v_and_or_b32 v26, v19, s23, v26
	v_and_or_b32 v25, v21, s23, v25
	v_and_or_b32 v24, v23, s23, v24
	v_lshl_add_u64 v[28:29], v[32:33], 0, v[28:29]
	ds_read2_b32 v[64:65], v51 offset1:68
	ds_read2_b32 v[66:67], v51 offset0:136 offset1:204
	global_store_dwordx4 v[28:29], v[24:27], off
	v_add_u32_e32 v17, 0x400, v51
	ds_read2_b32 v[26:27], v17 offset0:16 offset1:84
	ds_read2_b32 v[28:29], v17 offset0:152 offset1:220
	s_waitcnt lgkmcnt(3)
	v_mov_b32_e32 v24, v64
	s_waitcnt lgkmcnt(2)
	v_mov_b32_e32 v25, v66
	v_mov_b32_e32 v66, v65
	v_pk_mul_f32 v[64:65], v[30:31], v[66:67] op_sel_hi:[0,1]
	s_waitcnt lgkmcnt(1)
	v_mov_b32_e32 v66, v26
	s_waitcnt lgkmcnt(0)
	v_mov_b32_e32 v67, v28
	v_mov_b32_e32 v28, v27
	v_pk_mul_f32 v[66:67], v[30:31], v[66:67] op_sel_hi:[0,1]
	v_pk_mul_f32 v[26:27], v[30:31], v[28:29] op_sel_hi:[0,1]
	v_pk_mul_f32 v[24:25], v[30:31], v[24:25] op_sel_hi:[0,1]
	v_bfe_u32 v19, v26, 16, 1
	v_bfe_u32 v28, v66, 16, 1
	v_bfe_u32 v17, v27, 16, 1
	v_add3_u32 v19, v26, v19, s22
	v_bfe_u32 v26, v24, 16, 1
	v_bfe_u32 v29, v67, 16, 1
	v_add3_u32 v28, v66, v28, s22
	v_add3_u32 v17, v27, v17, s22
	v_bfe_u32 v27, v25, 16, 1
	v_add3_u32 v29, v67, v29, s22
	v_add3_u32 v24, v24, v26, s22
	v_lshrrev_b32_e32 v26, 16, v28
	v_or_b32_e32 v28, s6, v50
	v_bfe_u32 v21, v65, 16, 1
	v_bfe_u32 v23, v64, 16, 1
	v_add3_u32 v25, v25, v27, s22
	v_lshrrev_b32_e32 v27, 16, v29
	v_ashrrev_i32_e32 v29, 31, v28
	v_add3_u32 v23, v64, v23, s22
	v_add3_u32 v21, v65, v21, s22
	v_lshrrev_b32_e32 v24, 16, v24
	v_lshrrev_b32_e32 v25, 16, v25
	v_lshlrev_b64 v[28:29], 13, v[28:29]
	v_and_or_b32 v27, v17, s23, v27
	v_and_or_b32 v26, v19, s23, v26
	v_and_or_b32 v25, v21, s23, v25
	v_and_or_b32 v24, v23, s23, v24
	v_lshl_add_u64 v[28:29], v[32:33], 0, v[28:29]
	ds_read2_b32 v[64:65], v53 offset1:68
	ds_read2_b32 v[66:67], v53 offset0:136 offset1:204
	global_store_dwordx4 v[28:29], v[24:27], off
	v_add_u32_e32 v17, 0x400, v53
	ds_read2_b32 v[26:27], v17 offset0:16 offset1:84
	ds_read2_b32 v[28:29], v17 offset0:152 offset1:220
	s_waitcnt lgkmcnt(3)
	v_mov_b32_e32 v24, v64
	s_waitcnt lgkmcnt(2)
	v_mov_b32_e32 v25, v66
	v_mov_b32_e32 v66, v65
	v_pk_mul_f32 v[64:65], v[30:31], v[66:67] op_sel_hi:[0,1]
	s_waitcnt lgkmcnt(1)
	v_mov_b32_e32 v66, v26
	s_waitcnt lgkmcnt(0)
	v_mov_b32_e32 v67, v28
	v_mov_b32_e32 v28, v27
	v_pk_mul_f32 v[66:67], v[30:31], v[66:67] op_sel_hi:[0,1]
	v_pk_mul_f32 v[26:27], v[30:31], v[28:29] op_sel_hi:[0,1]
	v_pk_mul_f32 v[24:25], v[30:31], v[24:25] op_sel_hi:[0,1]
	v_bfe_u32 v19, v26, 16, 1
	v_bfe_u32 v28, v66, 16, 1
	v_bfe_u32 v17, v27, 16, 1
	v_add3_u32 v19, v26, v19, s22
	v_bfe_u32 v26, v24, 16, 1
	v_bfe_u32 v29, v67, 16, 1
	v_add3_u32 v28, v66, v28, s22
	v_add3_u32 v17, v27, v17, s22
	v_bfe_u32 v27, v25, 16, 1
	v_add3_u32 v29, v67, v29, s22
	v_add3_u32 v24, v24, v26, s22
	v_lshrrev_b32_e32 v26, 16, v28
	v_or_b32_e32 v28, s6, v52
	v_bfe_u32 v21, v65, 16, 1
	v_bfe_u32 v23, v64, 16, 1
	v_add3_u32 v25, v25, v27, s22
	v_lshrrev_b32_e32 v27, 16, v29
	v_ashrrev_i32_e32 v29, 31, v28
	v_add3_u32 v23, v64, v23, s22
	v_add3_u32 v21, v65, v21, s22
	v_lshrrev_b32_e32 v24, 16, v24
	v_lshrrev_b32_e32 v25, 16, v25
	v_lshlrev_b64 v[28:29], 13, v[28:29]
	v_and_or_b32 v27, v17, s23, v27
	v_and_or_b32 v26, v19, s23, v26
	v_and_or_b32 v25, v21, s23, v25
	v_and_or_b32 v24, v23, s23, v24
	v_lshl_add_u64 v[28:29], v[32:33], 0, v[28:29]
	ds_read2_b32 v[64:65], v55 offset1:68
	ds_read2_b32 v[66:67], v55 offset0:136 offset1:204
	global_store_dwordx4 v[28:29], v[24:27], off
	v_add_u32_e32 v17, 0x400, v55
	ds_read2_b32 v[26:27], v17 offset0:16 offset1:84
	ds_read2_b32 v[28:29], v17 offset0:152 offset1:220
	s_waitcnt lgkmcnt(3)
	v_mov_b32_e32 v24, v64
	s_waitcnt lgkmcnt(2)
	v_mov_b32_e32 v25, v66
	v_mov_b32_e32 v66, v65
	v_pk_mul_f32 v[64:65], v[30:31], v[66:67] op_sel_hi:[0,1]
	s_waitcnt lgkmcnt(1)
	v_mov_b32_e32 v66, v26
	s_waitcnt lgkmcnt(0)
	v_mov_b32_e32 v67, v28
	v_mov_b32_e32 v28, v27
	v_pk_mul_f32 v[66:67], v[30:31], v[66:67] op_sel_hi:[0,1]
	v_pk_mul_f32 v[26:27], v[30:31], v[28:29] op_sel_hi:[0,1]
	v_pk_mul_f32 v[24:25], v[30:31], v[24:25] op_sel_hi:[0,1]
	v_bfe_u32 v19, v26, 16, 1
	v_bfe_u32 v28, v66, 16, 1
	v_bfe_u32 v17, v27, 16, 1
	v_add3_u32 v19, v26, v19, s22
	v_bfe_u32 v26, v24, 16, 1
	v_bfe_u32 v29, v67, 16, 1
	v_add3_u32 v28, v66, v28, s22
	v_add3_u32 v17, v27, v17, s22
	v_bfe_u32 v27, v25, 16, 1
	v_add3_u32 v29, v67, v29, s22
	v_add3_u32 v24, v24, v26, s22
	v_lshrrev_b32_e32 v26, 16, v28
	v_or_b32_e32 v28, s6, v54
	v_bfe_u32 v21, v65, 16, 1
	v_bfe_u32 v23, v64, 16, 1
	v_add3_u32 v25, v25, v27, s22
	v_lshrrev_b32_e32 v27, 16, v29
	v_ashrrev_i32_e32 v29, 31, v28
	v_add3_u32 v23, v64, v23, s22
	v_add3_u32 v21, v65, v21, s22
	v_lshrrev_b32_e32 v24, 16, v24
	v_lshrrev_b32_e32 v25, 16, v25
	v_lshlrev_b64 v[28:29], 13, v[28:29]
	v_and_or_b32 v27, v17, s23, v27
	v_and_or_b32 v26, v19, s23, v26
	v_and_or_b32 v25, v21, s23, v25
	v_and_or_b32 v24, v23, s23, v24
	v_lshl_add_u64 v[28:29], v[32:33], 0, v[28:29]
	ds_read2_b32 v[64:65], v57 offset1:68
	ds_read2_b32 v[66:67], v57 offset0:136 offset1:204
	global_store_dwordx4 v[28:29], v[24:27], off
	v_add_u32_e32 v17, 0x400, v57
	ds_read2_b32 v[26:27], v17 offset0:16 offset1:84
	ds_read2_b32 v[28:29], v17 offset0:152 offset1:220
	s_waitcnt lgkmcnt(3)
	v_mov_b32_e32 v24, v64
	s_waitcnt lgkmcnt(2)
	v_mov_b32_e32 v25, v66
	v_mov_b32_e32 v66, v65
	v_pk_mul_f32 v[64:65], v[30:31], v[66:67] op_sel_hi:[0,1]
	s_waitcnt lgkmcnt(1)
	v_mov_b32_e32 v66, v26
	s_waitcnt lgkmcnt(0)
	v_mov_b32_e32 v67, v28
	v_mov_b32_e32 v28, v27
	v_pk_mul_f32 v[66:67], v[30:31], v[66:67] op_sel_hi:[0,1]
	v_pk_mul_f32 v[26:27], v[30:31], v[28:29] op_sel_hi:[0,1]
	v_pk_mul_f32 v[24:25], v[30:31], v[24:25] op_sel_hi:[0,1]
	v_bfe_u32 v19, v26, 16, 1
	v_bfe_u32 v28, v66, 16, 1
	v_bfe_u32 v17, v27, 16, 1
	v_add3_u32 v19, v26, v19, s22
	v_bfe_u32 v26, v24, 16, 1
	v_bfe_u32 v29, v67, 16, 1
	v_add3_u32 v28, v66, v28, s22
	v_add3_u32 v17, v27, v17, s22
	v_bfe_u32 v27, v25, 16, 1
	v_add3_u32 v29, v67, v29, s22
	v_add3_u32 v24, v24, v26, s22
	v_lshrrev_b32_e32 v26, 16, v28
	v_or_b32_e32 v28, s6, v56
	v_bfe_u32 v21, v65, 16, 1
	v_bfe_u32 v23, v64, 16, 1
	v_add3_u32 v25, v25, v27, s22
	v_lshrrev_b32_e32 v27, 16, v29
	v_ashrrev_i32_e32 v29, 31, v28
	v_add3_u32 v23, v64, v23, s22
	v_add3_u32 v21, v65, v21, s22
	v_lshrrev_b32_e32 v24, 16, v24
	v_lshrrev_b32_e32 v25, 16, v25
	v_lshlrev_b64 v[28:29], 13, v[28:29]
	v_and_or_b32 v27, v17, s23, v27
	v_and_or_b32 v26, v19, s23, v26
	v_and_or_b32 v25, v21, s23, v25
	v_and_or_b32 v24, v23, s23, v24
	v_lshl_add_u64 v[28:29], v[32:33], 0, v[28:29]
	global_store_dwordx4 v[28:29], v[24:27], off
	s_waitcnt lgkmcnt(0)

.LBB0_41:
	s_cmpk_gt_i32 s2, 0x33ff
	s_mov_b64 s[4:5], -1
	s_cbranch_scc0 .LBB0_57
	s_cmpk_gt_u32 s2, 0x343f
	s_cbranch_scc0 .LBB0_48
	s_cmpk_gt_u32 s2, 0x443f
	s_cbranch_scc0 .LBB0_45
	s_lshl_b32 s0, s2, 6
	s_lshl_b32 s4, s2, 2
	s_and_b32 s0, s0, 0x3c0
	s_and_b32 s4, s4, 0x7fffffc0
	s_add_i32 s88, s4, 0xfffeef00
	v_or_b32_e32 v17, s0, v9
	v_or_b32_e32 v28, s88, v11
	v_lshlrev_b32_e32 v194, 2, v17
	v_lshl_add_u64 v[32:33], s[46:47], 0, v[194:195]
	v_or_b32_e32 v194, 4, v28
	v_lshlrev_b64 v[26:27], 12, v[194:195]
	v_or_b32_e32 v194, 8, v28
	v_lshlrev_b64 v[68:69], 12, v[194:195]
	v_or_b32_e32 v194, 12, v28
	v_lshlrev_b64 v[70:71], 12, v[194:195]
	v_or_b32_e32 v194, 16, v28
	v_lshlrev_b64 v[76:77], 12, v[194:195]
	v_or_b32_e32 v194, 20, v28
	v_lshlrev_b64 v[78:79], 12, v[194:195]
	v_or_b32_e32 v194, 24, v28
	v_lshlrev_b64 v[84:85], 12, v[194:195]
	v_or_b32_e32 v194, 28, v28
	v_lshlrev_b64 v[86:87], 12, v[194:195]
	v_or_b32_e32 v194, 32, v28
	v_lshlrev_b64 v[92:93], 12, v[194:195]
	v_or_b32_e32 v194, 36, v28
	v_lshlrev_b64 v[94:95], 12, v[194:195]
	v_or_b32_e32 v194, 40, v28
	v_lshlrev_b64 v[100:101], 12, v[194:195]
	v_or_b32_e32 v194, 44, v28
	v_lshlrev_b64 v[102:103], 12, v[194:195]
	v_or_b32_e32 v194, 48, v28
	v_lshlrev_b64 v[108:109], 12, v[194:195]
	v_or_b32_e32 v194, 52, v28
	v_mov_b32_e32 v29, v195
	v_lshlrev_b64 v[110:111], 12, v[194:195]
	v_or_b32_e32 v194, 56, v28
	v_lshlrev_b64 v[24:25], 12, v[28:29]
	v_lshlrev_b64 v[116:117], 12, v[194:195]
	v_or_b32_e32 v194, 60, v28
	v_lshl_add_u64 v[24:25], v[32:33], 0, v[24:25]
	v_lshl_add_u64 v[64:65], v[32:33], 0, v[26:27]
	v_lshl_add_u64 v[68:69], v[32:33], 0, v[68:69]
	v_lshl_add_u64 v[72:73], v[32:33], 0, v[70:71]
	v_lshl_add_u64 v[76:77], v[32:33], 0, v[76:77]
	v_lshl_add_u64 v[80:81], v[32:33], 0, v[78:79]
	v_lshl_add_u64 v[84:85], v[32:33], 0, v[84:85]
	v_lshl_add_u64 v[88:89], v[32:33], 0, v[86:87]
	v_lshl_add_u64 v[92:93], v[32:33], 0, v[92:93]
	v_lshl_add_u64 v[96:97], v[32:33], 0, v[94:95]
	v_lshl_add_u64 v[100:101], v[32:33], 0, v[100:101]
	v_lshl_add_u64 v[104:105], v[32:33], 0, v[102:103]
	v_lshl_add_u64 v[108:109], v[32:33], 0, v[108:109]
	v_lshl_add_u64 v[112:113], v[32:33], 0, v[110:111]
	v_lshl_add_u64 v[116:117], v[32:33], 0, v[116:117]
	v_lshlrev_b64 v[28:29], 12, v[194:195]
	global_load_dwordx4 v[24:27], v[24:25], off nt
	s_nop 0
	global_load_dwordx4 v[64:67], v[64:65], off nt
	s_nop 0
	global_load_dwordx4 v[68:71], v[68:69], off nt
	s_nop 0
	global_load_dwordx4 v[72:75], v[72:73], off nt
	s_nop 0
	global_load_dwordx4 v[76:79], v[76:77], off nt
	s_nop 0
	global_load_dwordx4 v[80:83], v[80:81], off nt
	s_nop 0
	global_load_dwordx4 v[84:87], v[84:85], off nt
	s_nop 0
	global_load_dwordx4 v[88:91], v[88:89], off nt
	s_nop 0
	global_load_dwordx4 v[92:95], v[92:93], off nt
	s_nop 0
	global_load_dwordx4 v[96:99], v[96:97], off nt
	s_nop 0
	global_load_dwordx4 v[100:103], v[100:101], off nt
	s_nop 0
	global_load_dwordx4 v[104:107], v[104:105], off nt
	s_nop 0
	global_load_dwordx4 v[108:111], v[108:109], off nt
	s_nop 0
	global_load_dwordx4 v[112:115], v[112:113], off nt
	v_lshl_add_u64 v[28:29], v[32:33], 0, v[28:29]
	global_load_dwordx4 v[116:119], v[116:117], off nt
	s_nop 0
	global_load_dwordx4 v[120:123], v[28:29], off nt
	v_add_u32_e32 v17, v31, v34
	v_add_u32_e32 v19, v31, v35
	v_add_u32_e32 v21, v31, v36
	v_add_u32_e32 v23, v31, v37
	v_add_u32_e32 v28, v31, v38
	v_add_u32_e32 v29, v31, v39
	v_add_u32_e32 v30, v31, v40
	v_add_u32_e32 v32, v31, v41
	s_mov_b64 s[4:5], 0
	s_waitcnt vmcnt(15)
	ds_write_b128 v17, v[24:27]
	s_waitcnt vmcnt(14)
	ds_write_b128 v17, v[64:67] offset:1088
	s_waitcnt vmcnt(13)
	ds_write_b128 v19, v[68:71] offset:2176
	s_waitcnt vmcnt(12)
	ds_write_b128 v19, v[72:75] offset:3264
	s_waitcnt vmcnt(11)
	ds_write_b128 v21, v[76:79] offset:4352
	s_waitcnt vmcnt(10)
	ds_write_b128 v21, v[80:83] offset:5440
	s_waitcnt vmcnt(9)
	ds_write_b128 v23, v[84:87] offset:6528
	s_waitcnt vmcnt(8)
	ds_write_b128 v23, v[88:91] offset:7616
	s_waitcnt vmcnt(7)
	ds_write_b128 v28, v[92:95] offset:8704
	s_waitcnt vmcnt(6)
	ds_write_b128 v28, v[96:99] offset:9792
	s_waitcnt vmcnt(5)
	ds_write_b128 v29, v[100:103] offset:10880
	s_waitcnt vmcnt(4)
	ds_write_b128 v29, v[104:107] offset:11968
	s_waitcnt vmcnt(3)
	ds_write_b128 v30, v[108:111] offset:13056
	s_waitcnt vmcnt(2)
	ds_write_b128 v30, v[112:115] offset:14144
	s_waitcnt vmcnt(1)
	ds_write_b128 v32, v[116:119] offset:15232
	s_waitcnt vmcnt(0)
	ds_write_b128 v32, v[120:123] offset:16320
	s_waitcnt lgkmcnt(0)
	ds_read2_b32 v[26:27], v43 offset1:68
	ds_read2_b32 v[28:29], v43 offset0:136 offset1:204
	v_add_u32_e32 v17, 0x400, v43
	ds_read2_b32 v[32:33], v17 offset0:16 offset1:84
	ds_read2_b32 v[64:65], v17 offset0:152 offset1:220
	s_waitcnt lgkmcnt(3)
	v_bfe_u32 v19, v26, 16, 1
	v_bfe_u32 v21, v27, 16, 1
	v_add3_u32 v19, v26, v19, s22
	s_waitcnt lgkmcnt(2)
	v_bfe_u32 v23, v28, 16, 1
	v_add3_u32 v21, v27, v21, s22
	v_lshrrev_b32_e32 v19, 16, v19
	v_add3_u32 v23, v28, v23, s22
	v_and_or_b32 v26, v21, s23, v19
	v_bfe_u32 v19, v29, 16, 1
	v_lshrrev_b32_e32 v23, 16, v23
	v_add3_u32 v19, v29, v19, s22
	v_and_or_b32 v27, v19, s23, v23
	s_waitcnt lgkmcnt(1)
	v_bfe_u32 v19, v32, 16, 1
	v_add3_u32 v19, v32, v19, s22
	v_lshrrev_b32_e32 v17, 16, v19
	v_bfe_u32 v19, v33, 16, 1
	v_add3_u32 v19, v33, v19, s22
	v_and_or_b32 v28, v19, s23, v17
	s_waitcnt lgkmcnt(0)
	v_bfe_u32 v17, v64, 16, 1
	ds_read2_b32 v[32:33], v45 offset1:68
	v_add3_u32 v17, v64, v17, s22
	v_bfe_u32 v19, v65, 16, 1
	v_lshrrev_b32_e32 v17, 16, v17
	v_add3_u32 v19, v65, v19, s22
	v_and_or_b32 v29, v19, s23, v17
	v_or_b32_e32 v17, s0, v42
	v_lshl_add_u64 v[24:25], s[88:89], 1, v[2:3]
	v_lshlrev_b32_e32 v194, 11, v17
	v_lshl_add_u64 v[64:65], v[24:25], 0, v[194:195]
	s_waitcnt lgkmcnt(0)
	v_bfe_u32 v17, v32, 16, 1
	global_store_dwordx4 v[64:65], v[26:29], off
	v_add3_u32 v17, v32, v17, s22
	ds_read2_b32 v[28:29], v45 offset0:136 offset1:204
	v_bfe_u32 v19, v33, 16, 1
	v_lshrrev_b32_e32 v17, 16, v17
	v_add3_u32 v19, v33, v19, s22
	v_and_or_b32 v26, v19, s23, v17
	v_add_u32_e32 v19, 0x400, v45
	ds_read2_b32 v[32:33], v19 offset0:16 offset1:84
	s_waitcnt lgkmcnt(1)
	v_bfe_u32 v17, v28, 16, 1
	v_add3_u32 v17, v28, v17, s22
	v_bfe_u32 v21, v29, 16, 1
	ds_read2_b32 v[64:65], v19 offset0:152 offset1:220
	v_lshrrev_b32_e32 v17, 16, v17
	v_add3_u32 v21, v29, v21, s22
	v_and_or_b32 v27, v21, s23, v17
	s_waitcnt lgkmcnt(1)
	v_bfe_u32 v17, v32, 16, 1
	v_add3_u32 v17, v32, v17, s22
	v_bfe_u32 v19, v33, 16, 1
	v_lshrrev_b32_e32 v17, 16, v17
	v_add3_u32 v19, v33, v19, s22
	v_and_or_b32 v28, v19, s23, v17
	s_waitcnt lgkmcnt(0)
	v_bfe_u32 v17, v64, 16, 1
	ds_read2_b32 v[32:33], v47 offset1:68
	v_add3_u32 v17, v64, v17, s22
	v_bfe_u32 v19, v65, 16, 1
	v_lshrrev_b32_e32 v17, 16, v17
	v_add3_u32 v19, v65, v19, s22
	v_and_or_b32 v29, v19, s23, v17
	v_or_b32_e32 v17, s0, v44
	v_lshlrev_b32_e32 v194, 11, v17
	v_lshl_add_u64 v[64:65], v[24:25], 0, v[194:195]
	s_waitcnt lgkmcnt(0)
	v_bfe_u32 v17, v32, 16, 1
	global_store_dwordx4 v[64:65], v[26:29], off
	v_add3_u32 v17, v32, v17, s22
	ds_read2_b32 v[28:29], v47 offset0:136 offset1:204
	v_bfe_u32 v19, v33, 16, 1
	v_lshrrev_b32_e32 v17, 16, v17
	v_add3_u32 v19, v33, v19, s22
	v_and_or_b32 v26, v19, s23, v17
	v_add_u32_e32 v19, 0x400, v47
	ds_read2_b32 v[32:33], v19 offset0:16 offset1:84
	s_waitcnt lgkmcnt(1)
	v_bfe_u32 v17, v28, 16, 1
	v_add3_u32 v17, v28, v17, s22
	v_bfe_u32 v21, v29, 16, 1
	ds_read2_b32 v[64:65], v19 offset0:152 offset1:220
	v_lshrrev_b32_e32 v17, 16, v17
	v_add3_u32 v21, v29, v21, s22
	v_and_or_b32 v27, v21, s23, v17
	s_waitcnt lgkmcnt(1)
	v_bfe_u32 v17, v32, 16, 1
	v_add3_u32 v17, v32, v17, s22
	v_bfe_u32 v19, v33, 16, 1
	v_lshrrev_b32_e32 v17, 16, v17
	v_add3_u32 v19, v33, v19, s22
	v_and_or_b32 v28, v19, s23, v17
	s_waitcnt lgkmcnt(0)
	v_bfe_u32 v17, v64, 16, 1
	ds_read2_b32 v[32:33], v49 offset1:68
	v_add3_u32 v17, v64, v17, s22
	v_bfe_u32 v19, v65, 16, 1
	v_lshrrev_b32_e32 v17, 16, v17
	v_add3_u32 v19, v65, v19, s22
	v_and_or_b32 v29, v19, s23, v17
	v_or_b32_e32 v17, s0, v46
	v_lshlrev_b32_e32 v194, 11, v17
	v_lshl_add_u64 v[64:65], v[24:25], 0, v[194:195]
	s_waitcnt lgkmcnt(0)
	v_bfe_u32 v17, v32, 16, 1
	global_store_dwordx4 v[64:65], v[26:29], off
	v_add3_u32 v17, v32, v17, s22
	ds_read2_b32 v[28:29], v49 offset0:136 offset1:204
	v_bfe_u32 v19, v33, 16, 1
	v_lshrrev_b32_e32 v17, 16, v17
	v_add3_u32 v19, v33, v19, s22
	v_and_or_b32 v26, v19, s23, v17
	v_add_u32_e32 v19, 0x400, v49
	ds_read2_b32 v[32:33], v19 offset0:16 offset1:84
	s_waitcnt lgkmcnt(1)
	v_bfe_u32 v17, v28, 16, 1
	v_add3_u32 v17, v28, v17, s22
	v_bfe_u32 v21, v29, 16, 1
	ds_read2_b32 v[64:65], v19 offset0:152 offset1:220
	v_lshrrev_b32_e32 v17, 16, v17
	v_add3_u32 v21, v29, v21, s22
	v_and_or_b32 v27, v21, s23, v17
	s_waitcnt lgkmcnt(1)
	v_bfe_u32 v17, v32, 16, 1
	v_add3_u32 v17, v32, v17, s22
	v_bfe_u32 v19, v33, 16, 1
	v_lshrrev_b32_e32 v17, 16, v17
	v_add3_u32 v19, v33, v19, s22
	v_and_or_b32 v28, v19, s23, v17
	s_waitcnt lgkmcnt(0)
	v_bfe_u32 v17, v64, 16, 1
	ds_read2_b32 v[32:33], v51 offset1:68
	v_add3_u32 v17, v64, v17, s22
	v_bfe_u32 v19, v65, 16, 1
	v_lshrrev_b32_e32 v17, 16, v17
	v_add3_u32 v19, v65, v19, s22
	v_and_or_b32 v29, v19, s23, v17
	v_or_b32_e32 v17, s0, v48
	v_lshlrev_b32_e32 v194, 11, v17
	v_lshl_add_u64 v[64:65], v[24:25], 0, v[194:195]
	s_waitcnt lgkmcnt(0)
	v_bfe_u32 v17, v32, 16, 1
	global_store_dwordx4 v[64:65], v[26:29], off
	v_add3_u32 v17, v32, v17, s22
	ds_read2_b32 v[28:29], v51 offset0:136 offset1:204
	v_bfe_u32 v19, v33, 16, 1
	v_lshrrev_b32_e32 v17, 16, v17
	v_add3_u32 v19, v33, v19, s22
	v_and_or_b32 v26, v19, s23, v17
	v_add_u32_e32 v19, 0x400, v51
	ds_read2_b32 v[32:33], v19 offset0:16 offset1:84
	s_waitcnt lgkmcnt(1)
	v_bfe_u32 v17, v28, 16, 1
	v_add3_u32 v17, v28, v17, s22
	v_bfe_u32 v21, v29, 16, 1
	ds_read2_b32 v[64:65], v19 offset0:152 offset1:220
	v_lshrrev_b32_e32 v17, 16, v17
	v_add3_u32 v21, v29, v21, s22
	v_and_or_b32 v27, v21, s23, v17
	s_waitcnt lgkmcnt(1)
	v_bfe_u32 v17, v32, 16, 1
	v_add3_u32 v17, v32, v17, s22
	v_bfe_u32 v19, v33, 16, 1
	v_lshrrev_b32_e32 v17, 16, v17
	v_add3_u32 v19, v33, v19, s22
	v_and_or_b32 v28, v19, s23, v17
	s_waitcnt lgkmcnt(0)
	v_bfe_u32 v17, v64, 16, 1
	ds_read2_b32 v[32:33], v53 offset1:68
	v_add3_u32 v17, v64, v17, s22
	v_bfe_u32 v19, v65, 16, 1
	v_lshrrev_b32_e32 v17, 16, v17
	v_add3_u32 v19, v65, v19, s22
	v_and_or_b32 v29, v19, s23, v17
	v_or_b32_e32 v17, s0, v50
	v_lshlrev_b32_e32 v194, 11, v17
	v_lshl_add_u64 v[64:65], v[24:25], 0, v[194:195]
	s_waitcnt lgkmcnt(0)
	v_bfe_u32 v17, v32, 16, 1
	global_store_dwordx4 v[64:65], v[26:29], off
	v_add3_u32 v17, v32, v17, s22
	ds_read2_b32 v[28:29], v53 offset0:136 offset1:204
	v_bfe_u32 v19, v33, 16, 1
	v_lshrrev_b32_e32 v17, 16, v17
	v_add3_u32 v19, v33, v19, s22
	v_and_or_b32 v26, v19, s23, v17
	v_add_u32_e32 v19, 0x400, v53
	ds_read2_b32 v[32:33], v19 offset0:16 offset1:84
	s_waitcnt lgkmcnt(1)
	v_bfe_u32 v17, v28, 16, 1
	v_add3_u32 v17, v28, v17, s22
	v_bfe_u32 v21, v29, 16, 1
	ds_read2_b32 v[64:65], v19 offset0:152 offset1:220
	v_lshrrev_b32_e32 v17, 16, v17
	v_add3_u32 v21, v29, v21, s22
	v_and_or_b32 v27, v21, s23, v17
	s_waitcnt lgkmcnt(1)
	v_bfe_u32 v17, v32, 16, 1
	v_add3_u32 v17, v32, v17, s22
	v_bfe_u32 v19, v33, 16, 1
	v_lshrrev_b32_e32 v17, 16, v17
	v_add3_u32 v19, v33, v19, s22
	v_and_or_b32 v28, v19, s23, v17
	s_waitcnt lgkmcnt(0)
	v_bfe_u32 v17, v64, 16, 1
	ds_read2_b32 v[32:33], v55 offset1:68
	v_add3_u32 v17, v64, v17, s22
	v_bfe_u32 v19, v65, 16, 1
	v_lshrrev_b32_e32 v17, 16, v17
	v_add3_u32 v19, v65, v19, s22
	v_and_or_b32 v29, v19, s23, v17
	v_or_b32_e32 v17, s0, v52
	v_lshlrev_b32_e32 v194, 11, v17
	v_lshl_add_u64 v[64:65], v[24:25], 0, v[194:195]
	s_waitcnt lgkmcnt(0)
	v_bfe_u32 v17, v32, 16, 1
	global_store_dwordx4 v[64:65], v[26:29], off
	v_add3_u32 v17, v32, v17, s22
	ds_read2_b32 v[28:29], v55 offset0:136 offset1:204
	v_bfe_u32 v19, v33, 16, 1
	v_lshrrev_b32_e32 v17, 16, v17
	v_add3_u32 v19, v33, v19, s22
	v_and_or_b32 v26, v19, s23, v17
	v_add_u32_e32 v19, 0x400, v55
	ds_read2_b32 v[32:33], v19 offset0:16 offset1:84
	s_waitcnt lgkmcnt(1)
	v_bfe_u32 v17, v28, 16, 1
	v_add3_u32 v17, v28, v17, s22
	v_bfe_u32 v21, v29, 16, 1
	ds_read2_b32 v[64:65], v19 offset0:152 offset1:220
	v_lshrrev_b32_e32 v17, 16, v17
	v_add3_u32 v21, v29, v21, s22
	v_and_or_b32 v27, v21, s23, v17
	s_waitcnt lgkmcnt(1)
	v_bfe_u32 v17, v32, 16, 1
	v_add3_u32 v17, v32, v17, s22
	v_bfe_u32 v19, v33, 16, 1
	v_lshrrev_b32_e32 v17, 16, v17
	v_add3_u32 v19, v33, v19, s22
	v_and_or_b32 v28, v19, s23, v17
	s_waitcnt lgkmcnt(0)
	v_bfe_u32 v17, v64, 16, 1
	ds_read2_b32 v[32:33], v57 offset1:68
	v_add3_u32 v17, v64, v17, s22
	v_bfe_u32 v19, v65, 16, 1
	v_lshrrev_b32_e32 v17, 16, v17
	v_add3_u32 v19, v65, v19, s22
	v_and_or_b32 v29, v19, s23, v17
	v_or_b32_e32 v17, s0, v54
	v_lshlrev_b32_e32 v194, 11, v17
	v_lshl_add_u64 v[64:65], v[24:25], 0, v[194:195]
	s_waitcnt lgkmcnt(0)
	v_bfe_u32 v17, v32, 16, 1
	global_store_dwordx4 v[64:65], v[26:29], off
	v_add3_u32 v17, v32, v17, s22
	ds_read2_b32 v[28:29], v57 offset0:136 offset1:204
	v_bfe_u32 v19, v33, 16, 1
	v_lshrrev_b32_e32 v17, 16, v17
	v_add3_u32 v19, v33, v19, s22
	v_and_or_b32 v26, v19, s23, v17
	v_add_u32_e32 v19, 0x400, v57
	ds_read2_b32 v[32:33], v19 offset0:16 offset1:84
	s_waitcnt lgkmcnt(1)
	v_bfe_u32 v17, v28, 16, 1
	v_add3_u32 v17, v28, v17, s22
	v_bfe_u32 v21, v29, 16, 1
	ds_read2_b32 v[64:65], v19 offset0:152 offset1:220
	v_lshrrev_b32_e32 v17, 16, v17
	v_add3_u32 v21, v29, v21, s22
	v_and_or_b32 v27, v21, s23, v17
	s_waitcnt lgkmcnt(1)
	v_bfe_u32 v17, v32, 16, 1
	v_add3_u32 v17, v32, v17, s22
	v_bfe_u32 v19, v33, 16, 1
	v_lshrrev_b32_e32 v17, 16, v17
	v_add3_u32 v19, v33, v19, s22
	v_and_or_b32 v28, v19, s23, v17
	s_waitcnt lgkmcnt(0)
	v_bfe_u32 v17, v64, 16, 1
	v_add3_u32 v17, v64, v17, s22
	v_bfe_u32 v19, v65, 16, 1
	v_lshrrev_b32_e32 v17, 16, v17
	v_add3_u32 v19, v65, v19, s22
	v_and_or_b32 v29, v19, s23, v17
	v_or_b32_e32 v17, s0, v56
	v_lshlrev_b32_e32 v194, 11, v17
	v_lshl_add_u64 v[24:25], v[24:25], 0, v[194:195]
	global_store_dwordx4 v[24:25], v[26:29], off
	s_waitcnt lgkmcnt(0)
.LBB0_45:
	s_andn2_b64 vcc, exec, s[4:5]
	s_cbranch_vccnz .LBB0_47
	s_and_b32 s0, s2, 0x7fc0
	s_add_i32 s88, s0, 0xffffcbc0
	s_lshl_b32 s0, s2, 6
	s_and_b32 s0, s0, 0xfc0
	v_or_b32_e32 v17, s0, v9
	v_or_b32_e32 v28, s88, v11
	v_lshlrev_b32_e32 v194, 2, v17
	v_lshl_add_u64 v[32:33], s[44:45], 0, v[194:195]
	v_or_b32_e32 v194, 4, v28
	v_lshlrev_b64 v[26:27], 14, v[194:195]
	v_or_b32_e32 v194, 8, v28
	v_lshlrev_b64 v[68:69], 14, v[194:195]
	v_or_b32_e32 v194, 12, v28
	v_lshlrev_b64 v[70:71], 14, v[194:195]
	v_or_b32_e32 v194, 16, v28
	v_lshlrev_b64 v[76:77], 14, v[194:195]
	v_or_b32_e32 v194, 20, v28
	v_lshlrev_b64 v[78:79], 14, v[194:195]
	v_or_b32_e32 v194, 24, v28
	v_lshlrev_b64 v[84:85], 14, v[194:195]
	v_or_b32_e32 v194, 28, v28
	v_lshlrev_b64 v[86:87], 14, v[194:195]
	v_or_b32_e32 v194, 32, v28
	v_lshlrev_b64 v[92:93], 14, v[194:195]
	v_or_b32_e32 v194, 36, v28
	v_lshlrev_b64 v[94:95], 14, v[194:195]
	v_or_b32_e32 v194, 40, v28
	v_lshlrev_b64 v[100:101], 14, v[194:195]
	v_or_b32_e32 v194, 44, v28
	v_lshlrev_b64 v[102:103], 14, v[194:195]
	v_or_b32_e32 v194, 48, v28
	v_lshlrev_b64 v[108:109], 14, v[194:195]
	v_or_b32_e32 v194, 52, v28
	v_mov_b32_e32 v29, v195
	v_lshlrev_b64 v[110:111], 14, v[194:195]
	v_or_b32_e32 v194, 56, v28
	v_lshlrev_b64 v[24:25], 14, v[28:29]
	v_lshlrev_b64 v[116:117], 14, v[194:195]
	v_or_b32_e32 v194, 60, v28
	v_lshl_add_u64 v[24:25], v[32:33], 0, v[24:25]
	v_lshl_add_u64 v[64:65], v[32:33], 0, v[26:27]
	v_lshl_add_u64 v[68:69], v[32:33], 0, v[68:69]
	v_lshl_add_u64 v[72:73], v[32:33], 0, v[70:71]
	v_lshl_add_u64 v[76:77], v[32:33], 0, v[76:77]
	v_lshl_add_u64 v[80:81], v[32:33], 0, v[78:79]
	v_lshl_add_u64 v[84:85], v[32:33], 0, v[84:85]
	v_lshl_add_u64 v[88:89], v[32:33], 0, v[86:87]
	v_lshl_add_u64 v[92:93], v[32:33], 0, v[92:93]
	v_lshl_add_u64 v[96:97], v[32:33], 0, v[94:95]
	v_lshl_add_u64 v[100:101], v[32:33], 0, v[100:101]
	v_lshl_add_u64 v[104:105], v[32:33], 0, v[102:103]
	v_lshl_add_u64 v[108:109], v[32:33], 0, v[108:109]
	v_lshl_add_u64 v[112:113], v[32:33], 0, v[110:111]
	v_lshl_add_u64 v[116:117], v[32:33], 0, v[116:117]
	v_lshlrev_b64 v[28:29], 14, v[194:195]
	global_load_dwordx4 v[24:27], v[24:25], off nt
	s_nop 0
	global_load_dwordx4 v[64:67], v[64:65], off nt
	s_nop 0
	global_load_dwordx4 v[68:71], v[68:69], off nt
	s_nop 0
	global_load_dwordx4 v[72:75], v[72:73], off nt
	s_nop 0
	global_load_dwordx4 v[76:79], v[76:77], off nt
	s_nop 0
	global_load_dwordx4 v[80:83], v[80:81], off nt
	s_nop 0
	global_load_dwordx4 v[84:87], v[84:85], off nt
	s_nop 0
	global_load_dwordx4 v[88:91], v[88:89], off nt
	s_nop 0
	global_load_dwordx4 v[92:95], v[92:93], off nt
	s_nop 0
	global_load_dwordx4 v[96:99], v[96:97], off nt
	s_nop 0
	global_load_dwordx4 v[100:103], v[100:101], off nt
	s_nop 0
	global_load_dwordx4 v[104:107], v[104:105], off nt
	s_nop 0
	global_load_dwordx4 v[108:111], v[108:109], off nt
	s_nop 0
	global_load_dwordx4 v[112:115], v[112:113], off nt
	v_lshl_add_u64 v[28:29], v[32:33], 0, v[28:29]
	global_load_dwordx4 v[116:119], v[116:117], off nt
	s_nop 0
	global_load_dwordx4 v[120:123], v[28:29], off nt
	v_add_u32_e32 v17, v31, v34
	v_add_u32_e32 v19, v31, v35
	v_add_u32_e32 v21, v31, v36
	v_add_u32_e32 v23, v31, v37
	v_add_u32_e32 v28, v31, v38
	v_add_u32_e32 v29, v31, v39
	v_add_u32_e32 v30, v31, v40
	v_add_u32_e32 v32, v31, v41
	s_waitcnt vmcnt(15)
	ds_write_b128 v17, v[24:27]
	s_waitcnt vmcnt(14)
	ds_write_b128 v17, v[64:67] offset:1088
	s_waitcnt vmcnt(13)
	ds_write_b128 v19, v[68:71] offset:2176
	s_waitcnt vmcnt(12)
	ds_write_b128 v19, v[72:75] offset:3264
	s_waitcnt vmcnt(11)
	ds_write_b128 v21, v[76:79] offset:4352
	s_waitcnt vmcnt(10)
	ds_write_b128 v21, v[80:83] offset:5440
	s_waitcnt vmcnt(9)
	ds_write_b128 v23, v[84:87] offset:6528
	s_waitcnt vmcnt(8)
	ds_write_b128 v23, v[88:91] offset:7616
	s_waitcnt vmcnt(7)
	ds_write_b128 v28, v[92:95] offset:8704
	s_waitcnt vmcnt(6)
	ds_write_b128 v28, v[96:99] offset:9792
	s_waitcnt vmcnt(5)
	ds_write_b128 v29, v[100:103] offset:10880
	s_waitcnt vmcnt(4)
	ds_write_b128 v29, v[104:107] offset:11968
	s_waitcnt vmcnt(3)
	ds_write_b128 v30, v[108:111] offset:13056
	s_waitcnt vmcnt(2)
	ds_write_b128 v30, v[112:115] offset:14144
	s_waitcnt vmcnt(1)
	ds_write_b128 v32, v[116:119] offset:15232
	s_waitcnt vmcnt(0)
	ds_write_b128 v32, v[120:123] offset:16320
	s_waitcnt lgkmcnt(0)
	ds_read2_b32 v[26:27], v43 offset1:68
	ds_read2_b32 v[28:29], v43 offset0:136 offset1:204
	v_add_u32_e32 v17, 0x400, v43
	ds_read2_b32 v[32:33], v17 offset0:16 offset1:84
	ds_read2_b32 v[64:65], v17 offset0:152 offset1:220
	s_waitcnt lgkmcnt(3)
	v_bfe_u32 v19, v26, 16, 1
	v_bfe_u32 v21, v27, 16, 1
	s_waitcnt lgkmcnt(2)
	v_bfe_u32 v23, v28, 16, 1
	v_add3_u32 v19, v26, v19, s22
	v_bfe_u32 v30, v29, 16, 1
	v_add3_u32 v21, v27, v21, s22
	v_add3_u32 v23, v28, v23, s22
	v_lshrrev_b32_e32 v19, 16, v19
	v_lshrrev_b32_e32 v23, 16, v23
	v_and_or_b32 v26, v21, s23, v19
	v_add3_u32 v19, v29, v30, s22
	v_and_or_b32 v27, v19, s23, v23
	s_waitcnt lgkmcnt(1)
	v_bfe_u32 v19, v32, 16, 1
	v_add3_u32 v19, v32, v19, s22
	v_lshrrev_b32_e32 v17, 16, v19
	v_bfe_u32 v19, v33, 16, 1
	v_add3_u32 v19, v33, v19, s22
	v_and_or_b32 v28, v19, s23, v17
	s_waitcnt lgkmcnt(0)
	v_bfe_u32 v17, v64, 16, 1
	ds_read2_b32 v[32:33], v45 offset1:68
	v_add3_u32 v17, v64, v17, s22
	v_bfe_u32 v19, v65, 16, 1
	v_lshrrev_b32_e32 v17, 16, v17
	v_add3_u32 v19, v65, v19, s22
	v_and_or_b32 v29, v19, s23, v17
	v_or_b32_e32 v17, s0, v42
	v_lshl_add_u64 v[24:25], s[88:89], 1, v[4:5]
	v_lshlrev_b32_e32 v194, 13, v17
	v_lshl_add_u64 v[64:65], v[24:25], 0, v[194:195]
	s_waitcnt lgkmcnt(0)
	v_bfe_u32 v17, v32, 16, 1
	global_store_dwordx4 v[64:65], v[26:29], off
	v_add3_u32 v17, v32, v17, s22
	ds_read2_b32 v[28:29], v45 offset0:136 offset1:204
	v_bfe_u32 v19, v33, 16, 1
	v_lshrrev_b32_e32 v17, 16, v17
	v_add3_u32 v19, v33, v19, s22
	v_and_or_b32 v26, v19, s23, v17
	v_add_u32_e32 v19, 0x400, v45
	ds_read2_b32 v[32:33], v19 offset0:16 offset1:84
	s_waitcnt lgkmcnt(1)
	v_bfe_u32 v17, v28, 16, 1
	v_add3_u32 v17, v28, v17, s22
	v_bfe_u32 v21, v29, 16, 1
	ds_read2_b32 v[64:65], v19 offset0:152 offset1:220
	v_lshrrev_b32_e32 v17, 16, v17
	v_add3_u32 v21, v29, v21, s22
	v_and_or_b32 v27, v21, s23, v17
	s_waitcnt lgkmcnt(1)
	v_bfe_u32 v17, v32, 16, 1
	v_add3_u32 v17, v32, v17, s22
	v_bfe_u32 v19, v33, 16, 1
	v_lshrrev_b32_e32 v17, 16, v17
	v_add3_u32 v19, v33, v19, s22
	v_and_or_b32 v28, v19, s23, v17
	s_waitcnt lgkmcnt(0)
	v_bfe_u32 v17, v64, 16, 1
	ds_read2_b32 v[32:33], v47 offset1:68
	v_add3_u32 v17, v64, v17, s22
	v_bfe_u32 v19, v65, 16, 1
	v_lshrrev_b32_e32 v17, 16, v17
	v_add3_u32 v19, v65, v19, s22
	v_and_or_b32 v29, v19, s23, v17
	v_or_b32_e32 v17, s0, v44
	v_lshlrev_b32_e32 v194, 13, v17
	v_lshl_add_u64 v[64:65], v[24:25], 0, v[194:195]
	s_waitcnt lgkmcnt(0)
	v_bfe_u32 v17, v32, 16, 1
	global_store_dwordx4 v[64:65], v[26:29], off
	v_add3_u32 v17, v32, v17, s22
	ds_read2_b32 v[28:29], v47 offset0:136 offset1:204
	v_bfe_u32 v19, v33, 16, 1
	v_lshrrev_b32_e32 v17, 16, v17
	v_add3_u32 v19, v33, v19, s22
	v_and_or_b32 v26, v19, s23, v17
	v_add_u32_e32 v19, 0x400, v47
	ds_read2_b32 v[32:33], v19 offset0:16 offset1:84
	s_waitcnt lgkmcnt(1)
	v_bfe_u32 v17, v28, 16, 1
	v_add3_u32 v17, v28, v17, s22
	v_bfe_u32 v21, v29, 16, 1
	ds_read2_b32 v[64:65], v19 offset0:152 offset1:220
	v_lshrrev_b32_e32 v17, 16, v17
	v_add3_u32 v21, v29, v21, s22
	v_and_or_b32 v27, v21, s23, v17
	s_waitcnt lgkmcnt(1)
	v_bfe_u32 v17, v32, 16, 1
	v_add3_u32 v17, v32, v17, s22
	v_bfe_u32 v19, v33, 16, 1
	v_lshrrev_b32_e32 v17, 16, v17
	v_add3_u32 v19, v33, v19, s22
	v_and_or_b32 v28, v19, s23, v17
	s_waitcnt lgkmcnt(0)
	v_bfe_u32 v17, v64, 16, 1
	ds_read2_b32 v[32:33], v49 offset1:68
	v_add3_u32 v17, v64, v17, s22
	v_bfe_u32 v19, v65, 16, 1
	v_lshrrev_b32_e32 v17, 16, v17
	v_add3_u32 v19, v65, v19, s22
	v_and_or_b32 v29, v19, s23, v17
	v_or_b32_e32 v17, s0, v46
	v_lshlrev_b32_e32 v194, 13, v17
	v_lshl_add_u64 v[64:65], v[24:25], 0, v[194:195]
	s_waitcnt lgkmcnt(0)
	v_bfe_u32 v17, v32, 16, 1
	global_store_dwordx4 v[64:65], v[26:29], off
	v_add3_u32 v17, v32, v17, s22
	ds_read2_b32 v[28:29], v49 offset0:136 offset1:204
	v_bfe_u32 v19, v33, 16, 1
	v_lshrrev_b32_e32 v17, 16, v17
	v_add3_u32 v19, v33, v19, s22
	v_and_or_b32 v26, v19, s23, v17
	v_add_u32_e32 v19, 0x400, v49
	ds_read2_b32 v[32:33], v19 offset0:16 offset1:84
	s_waitcnt lgkmcnt(1)
	v_bfe_u32 v17, v28, 16, 1
	v_add3_u32 v17, v28, v17, s22
	v_bfe_u32 v21, v29, 16, 1
	ds_read2_b32 v[64:65], v19 offset0:152 offset1:220
	v_lshrrev_b32_e32 v17, 16, v17
	v_add3_u32 v21, v29, v21, s22
	v_and_or_b32 v27, v21, s23, v17
	s_waitcnt lgkmcnt(1)
	v_bfe_u32 v17, v32, 16, 1
	v_add3_u32 v17, v32, v17, s22
	v_bfe_u32 v19, v33, 16, 1
	v_lshrrev_b32_e32 v17, 16, v17
	v_add3_u32 v19, v33, v19, s22
	v_and_or_b32 v28, v19, s23, v17
	s_waitcnt lgkmcnt(0)
	v_bfe_u32 v17, v64, 16, 1
	ds_read2_b32 v[32:33], v51 offset1:68
	v_add3_u32 v17, v64, v17, s22
	v_bfe_u32 v19, v65, 16, 1
	v_lshrrev_b32_e32 v17, 16, v17
	v_add3_u32 v19, v65, v19, s22
	v_and_or_b32 v29, v19, s23, v17
	v_or_b32_e32 v17, s0, v48
	v_lshlrev_b32_e32 v194, 13, v17
	v_lshl_add_u64 v[64:65], v[24:25], 0, v[194:195]
	s_waitcnt lgkmcnt(0)
	v_bfe_u32 v17, v32, 16, 1
	global_store_dwordx4 v[64:65], v[26:29], off
	v_add3_u32 v17, v32, v17, s22
	ds_read2_b32 v[28:29], v51 offset0:136 offset1:204
	v_bfe_u32 v19, v33, 16, 1
	v_lshrrev_b32_e32 v17, 16, v17
	v_add3_u32 v19, v33, v19, s22
	v_and_or_b32 v26, v19, s23, v17
	v_add_u32_e32 v19, 0x400, v51
	ds_read2_b32 v[32:33], v19 offset0:16 offset1:84
	s_waitcnt lgkmcnt(1)
	v_bfe_u32 v17, v28, 16, 1
	v_add3_u32 v17, v28, v17, s22
	v_bfe_u32 v21, v29, 16, 1
	ds_read2_b32 v[64:65], v19 offset0:152 offset1:220
	v_lshrrev_b32_e32 v17, 16, v17
	v_add3_u32 v21, v29, v21, s22
	v_and_or_b32 v27, v21, s23, v17
	s_waitcnt lgkmcnt(1)
	v_bfe_u32 v17, v32, 16, 1
	v_add3_u32 v17, v32, v17, s22
	v_bfe_u32 v19, v33, 16, 1
	v_lshrrev_b32_e32 v17, 16, v17
	v_add3_u32 v19, v33, v19, s22
	v_and_or_b32 v28, v19, s23, v17
	s_waitcnt lgkmcnt(0)
	v_bfe_u32 v17, v64, 16, 1
	ds_read2_b32 v[32:33], v53 offset1:68
	v_add3_u32 v17, v64, v17, s22
	v_bfe_u32 v19, v65, 16, 1
	v_lshrrev_b32_e32 v17, 16, v17
	v_add3_u32 v19, v65, v19, s22
	v_and_or_b32 v29, v19, s23, v17
	v_or_b32_e32 v17, s0, v50
	v_lshlrev_b32_e32 v194, 13, v17
	v_lshl_add_u64 v[64:65], v[24:25], 0, v[194:195]
	s_waitcnt lgkmcnt(0)
	v_bfe_u32 v17, v32, 16, 1
	global_store_dwordx4 v[64:65], v[26:29], off
	v_add3_u32 v17, v32, v17, s22
	ds_read2_b32 v[28:29], v53 offset0:136 offset1:204
	v_bfe_u32 v19, v33, 16, 1
	v_lshrrev_b32_e32 v17, 16, v17
	v_add3_u32 v19, v33, v19, s22
	v_and_or_b32 v26, v19, s23, v17
	v_add_u32_e32 v19, 0x400, v53
	ds_read2_b32 v[32:33], v19 offset0:16 offset1:84
	s_waitcnt lgkmcnt(1)
	v_bfe_u32 v17, v28, 16, 1
	v_add3_u32 v17, v28, v17, s22
	v_bfe_u32 v21, v29, 16, 1
	ds_read2_b32 v[64:65], v19 offset0:152 offset1:220
	v_lshrrev_b32_e32 v17, 16, v17
	v_add3_u32 v21, v29, v21, s22
	v_and_or_b32 v27, v21, s23, v17
	s_waitcnt lgkmcnt(1)
	v_bfe_u32 v17, v32, 16, 1
	v_add3_u32 v17, v32, v17, s22
	v_bfe_u32 v19, v33, 16, 1
	v_lshrrev_b32_e32 v17, 16, v17
	v_add3_u32 v19, v33, v19, s22
	v_and_or_b32 v28, v19, s23, v17
	s_waitcnt lgkmcnt(0)
	v_bfe_u32 v17, v64, 16, 1
	ds_read2_b32 v[32:33], v55 offset1:68
	v_add3_u32 v17, v64, v17, s22
	v_bfe_u32 v19, v65, 16, 1
	v_lshrrev_b32_e32 v17, 16, v17
	v_add3_u32 v19, v65, v19, s22
	v_and_or_b32 v29, v19, s23, v17
	v_or_b32_e32 v17, s0, v52
	v_lshlrev_b32_e32 v194, 13, v17
	v_lshl_add_u64 v[64:65], v[24:25], 0, v[194:195]
	s_waitcnt lgkmcnt(0)
	v_bfe_u32 v17, v32, 16, 1
	global_store_dwordx4 v[64:65], v[26:29], off
	v_add3_u32 v17, v32, v17, s22
	ds_read2_b32 v[28:29], v55 offset0:136 offset1:204
	v_bfe_u32 v19, v33, 16, 1
	v_lshrrev_b32_e32 v17, 16, v17
	v_add3_u32 v19, v33, v19, s22
	v_and_or_b32 v26, v19, s23, v17
	v_add_u32_e32 v19, 0x400, v55
	ds_read2_b32 v[32:33], v19 offset0:16 offset1:84
	s_waitcnt lgkmcnt(1)
	v_bfe_u32 v17, v28, 16, 1
	v_add3_u32 v17, v28, v17, s22
	v_bfe_u32 v21, v29, 16, 1
	ds_read2_b32 v[64:65], v19 offset0:152 offset1:220
	v_lshrrev_b32_e32 v17, 16, v17
	v_add3_u32 v21, v29, v21, s22
	v_and_or_b32 v27, v21, s23, v17
	s_waitcnt lgkmcnt(1)
	v_bfe_u32 v17, v32, 16, 1
	v_add3_u32 v17, v32, v17, s22
	v_bfe_u32 v19, v33, 16, 1
	v_lshrrev_b32_e32 v17, 16, v17
	v_add3_u32 v19, v33, v19, s22
	v_and_or_b32 v28, v19, s23, v17
	s_waitcnt lgkmcnt(0)
	v_bfe_u32 v17, v64, 16, 1
	ds_read2_b32 v[32:33], v57 offset1:68
	v_add3_u32 v17, v64, v17, s22
	v_bfe_u32 v19, v65, 16, 1
	v_lshrrev_b32_e32 v17, 16, v17
	v_add3_u32 v19, v65, v19, s22
	v_and_or_b32 v29, v19, s23, v17
	v_or_b32_e32 v17, s0, v54
	v_lshlrev_b32_e32 v194, 13, v17
	v_lshl_add_u64 v[64:65], v[24:25], 0, v[194:195]
	s_waitcnt lgkmcnt(0)
	v_bfe_u32 v17, v32, 16, 1
	global_store_dwordx4 v[64:65], v[26:29], off
	v_add3_u32 v17, v32, v17, s22
	ds_read2_b32 v[28:29], v57 offset0:136 offset1:204
	v_bfe_u32 v19, v33, 16, 1
	v_lshrrev_b32_e32 v17, 16, v17
	v_add3_u32 v19, v33, v19, s22
	v_and_or_b32 v26, v19, s23, v17
	v_add_u32_e32 v19, 0x400, v57
	ds_read2_b32 v[32:33], v19 offset0:16 offset1:84
	s_waitcnt lgkmcnt(1)
	v_bfe_u32 v17, v28, 16, 1
	v_add3_u32 v17, v28, v17, s22
	v_bfe_u32 v21, v29, 16, 1
	ds_read2_b32 v[64:65], v19 offset0:152 offset1:220
	v_lshrrev_b32_e32 v17, 16, v17
	v_add3_u32 v21, v29, v21, s22
	v_and_or_b32 v27, v21, s23, v17
	s_waitcnt lgkmcnt(1)
	v_bfe_u32 v17, v32, 16, 1
	v_add3_u32 v17, v32, v17, s22
	v_bfe_u32 v19, v33, 16, 1
	v_lshrrev_b32_e32 v17, 16, v17
	v_add3_u32 v19, v33, v19, s22
	v_and_or_b32 v28, v19, s23, v17
	s_waitcnt lgkmcnt(0)
	v_bfe_u32 v17, v64, 16, 1
	v_add3_u32 v17, v64, v17, s22
	v_bfe_u32 v19, v65, 16, 1
	v_lshrrev_b32_e32 v17, 16, v17
	v_add3_u32 v19, v65, v19, s22
	v_and_or_b32 v29, v19, s23, v17
	v_or_b32_e32 v17, s0, v56
	v_lshlrev_b32_e32 v194, 13, v17
	v_lshl_add_u64 v[24:25], v[24:25], 0, v[194:195]
	global_store_dwordx4 v[24:25], v[26:29], off
	s_waitcnt lgkmcnt(0)

.Lpb_adone:
	s_add_u32 s6, s4, 0x4000
	s_addc_u32 s7, s5, 0
	s_add_u32 s66, s40, 0x2000
	s_addc_u32 s67, s41, 0
	s_add_u32 s12, s52, s69
	s_addc_u32 s13, s53, 0
	s_add_u32 s38, s12, 0x4000
	s_addc_u32 s39, s13, 0
	s_cmp_eq_u32 s62, 0
	s_cbranch_scc1 .Lpb_l0
	s_and_b32 s68, s64, s88
	s_cmp_eq_u32 s68, 1
	s_cbranch_scc1 .Lpb_l1c
	s_sub_u32 s68, 0, s88
	s_subb_u32 s69, 0, 0
	s_not_b64 s[68:69], s[68:69]
	global_load_dwordx4 v[2:5], v178, s[4:5] nt
	global_load_dwordx4 v[6:9], v178, s[4:5] offset:1024 nt
	global_load_dwordx4 v[10:13], v178, s[4:5] offset:2048 nt
	global_load_dwordx4 v[14:17], v178, s[4:5] offset:3072 nt
	global_load_dwordx4 v[18:21], v179, s[4:5] nt
	global_load_dwordx4 v[22:25], v179, s[4:5] offset:1024 nt
	global_load_dwordx4 v[26:29], v179, s[4:5] offset:2048 nt
	global_load_dwordx4 v[30:33], v179, s[4:5] offset:3072 nt
	global_load_dwordx4 v[34:37], v180, s[4:5] nt
	global_load_dwordx4 v[38:41], v180, s[4:5] offset:1024 nt
	global_load_dwordx4 v[42:45], v180, s[4:5] offset:2048 nt
	global_load_dwordx4 v[46:49], v180, s[4:5] offset:3072 nt
	global_load_dwordx4 v[50:53], v181, s[4:5] nt
	global_load_dwordx4 v[54:57], v181, s[4:5] offset:1024 nt
	global_load_dwordx4 v[58:61], v181, s[4:5] offset:2048 nt
	global_load_dwordx4 v[62:65], v181, s[4:5] offset:3072 nt
	global_load_dwordx2 v[130:131], v182, s[40:41]
	global_load_dwordx2 v[132:133], v182, s[40:41] offset:512
	global_load_dwordx2 v[134:135], v182, s[40:41] offset:1024
	global_load_dwordx2 v[136:137], v182, s[40:41] offset:1536
	global_load_dwordx2 v[138:139], v182, s[40:41] offset:2048
	global_load_dwordx2 v[140:141], v182, s[40:41] offset:2560
	global_load_dwordx2 v[142:143], v182, s[40:41] offset:3072
	global_load_dwordx2 v[144:145], v182, s[40:41] offset:3584
	global_load_dwordx2 v[146:147], v183, s[40:41]
	global_load_dwordx2 v[148:149], v183, s[40:41] offset:512
	global_load_dwordx2 v[150:151], v183, s[40:41] offset:1024
	global_load_dwordx2 v[152:153], v183, s[40:41] offset:1536
	global_load_dwordx2 v[154:155], v183, s[40:41] offset:2048
	global_load_dwordx2 v[156:157], v183, s[40:41] offset:2560
	global_load_dwordx2 v[158:159], v183, s[40:41] offset:3072
	global_load_dwordx2 v[160:161], v183, s[40:41] offset:3584
	global_load_dwordx2 v[162:163], v182, s[66:67]
	global_load_dwordx2 v[164:165], v182, s[66:67] offset:512
	global_load_dwordx2 v[166:167], v182, s[66:67] offset:1024
	global_load_dwordx2 v[168:169], v182, s[66:67] offset:1536
	global_load_dwordx2 v[170:171], v182, s[66:67] offset:2048
	global_load_dwordx2 v[172:173], v182, s[66:67] offset:2560
	global_load_dwordx2 v[174:175], v182, s[66:67] offset:3072
	global_load_dwordx2 v[176:177], v182, s[66:67] offset:3584
	global_load_dwordx2 v[236:237], v183, s[66:67]
	global_load_dwordx2 v[238:239], v183, s[66:67] offset:512
	global_load_dwordx2 v[240:241], v183, s[66:67] offset:1024
	global_load_dwordx2 v[242:243], v183, s[66:67] offset:1536
	global_load_dwordx2 v[244:245], v183, s[66:67] offset:2048
	global_load_dwordx2 v[246:247], v183, s[66:67] offset:2560
	global_load_dwordx2 v[248:249], v183, s[66:67] offset:3072
	global_load_dwordx2 v[250:251], v183, s[66:67] offset:3584
	global_load_dwordx4 v[66:69], v178, s[6:7] nt
	s_waitcnt vmcnt(48)
	s_waitcnt vmcnt(32)
	v_lshlrev_b32_e32 v228, 16, v130
	v_and_b32_e32 v229, 0xffff0000, v130
	v_lshlrev_b32_e32 v230, 16, v131
	v_and_b32_e32 v231, 0xffff0000, v131
	v_pk_add_f32 v[2:3], v[2:3], v[228:229]
	v_pk_add_f32 v[4:5], v[4:5], v[230:231]
	v_pk_mul_f32 v[218:219], v[2:3], v[2:3]
	v_pk_fma_f32 v[218:219], v[4:5], v[4:5], v[218:219]
	v_cvt_pk_bf16_f32 v130, v2, v3
	v_cvt_pk_bf16_f32 v131, v4, v5
	s_mov_b64 exec, s[68:69]
	global_store_dwordx2 v182, v[130:131], s[40:41]
	s_mov_b64 exec, -1
	global_load_dwordx4 v[70:73], v178, s[6:7] offset:1024 nt
	s_waitcnt vmcnt(33)
	v_lshlrev_b32_e32 v228, 16, v132
	v_and_b32_e32 v229, 0xffff0000, v132
	v_lshlrev_b32_e32 v230, 16, v133
	v_and_b32_e32 v231, 0xffff0000, v133
	v_pk_add_f32 v[6:7], v[6:7], v[228:229]
	v_pk_add_f32 v[8:9], v[8:9], v[230:231]
	v_pk_fma_f32 v[218:219], v[6:7], v[6:7], v[218:219]
	v_pk_fma_f32 v[218:219], v[8:9], v[8:9], v[218:219]
	v_cvt_pk_bf16_f32 v132, v6, v7
	v_cvt_pk_bf16_f32 v133, v8, v9
	s_mov_b64 exec, s[68:69]
	global_store_dwordx2 v182, v[132:133], s[40:41] offset:512
	s_mov_b64 exec, -1
	global_load_dwordx4 v[74:77], v178, s[6:7] offset:2048 nt
	s_waitcnt vmcnt(34)
	v_lshlrev_b32_e32 v228, 16, v134
	v_and_b32_e32 v229, 0xffff0000, v134
	v_lshlrev_b32_e32 v230, 16, v135
	v_and_b32_e32 v231, 0xffff0000, v135
	v_pk_add_f32 v[10:11], v[10:11], v[228:229]
	v_pk_add_f32 v[12:13], v[12:13], v[230:231]
	v_pk_fma_f32 v[218:219], v[10:11], v[10:11], v[218:219]
	v_pk_fma_f32 v[218:219], v[12:13], v[12:13], v[218:219]
	v_cvt_pk_bf16_f32 v134, v10, v11
	v_cvt_pk_bf16_f32 v135, v12, v13
	s_mov_b64 exec, s[68:69]
	global_store_dwordx2 v182, v[134:135], s[40:41] offset:1024
	s_mov_b64 exec, -1
	global_load_dwordx4 v[78:81], v178, s[6:7] offset:3072 nt
	s_waitcnt vmcnt(35)
	v_lshlrev_b32_e32 v228, 16, v136
	v_and_b32_e32 v229, 0xffff0000, v136
	v_lshlrev_b32_e32 v230, 16, v137
	v_and_b32_e32 v231, 0xffff0000, v137
	v_pk_add_f32 v[14:15], v[14:15], v[228:229]
	v_pk_add_f32 v[16:17], v[16:17], v[230:231]
	v_pk_fma_f32 v[218:219], v[14:15], v[14:15], v[218:219]
	v_pk_fma_f32 v[218:219], v[16:17], v[16:17], v[218:219]
	v_cvt_pk_bf16_f32 v136, v14, v15
	v_cvt_pk_bf16_f32 v137, v16, v17
	s_mov_b64 exec, s[68:69]
	global_store_dwordx2 v182, v[136:137], s[40:41] offset:1536
	s_mov_b64 exec, -1
	global_load_dwordx4 v[82:85], v179, s[6:7] nt
	s_waitcnt vmcnt(36)
	v_lshlrev_b32_e32 v228, 16, v138
	v_and_b32_e32 v229, 0xffff0000, v138
	v_lshlrev_b32_e32 v230, 16, v139
	v_and_b32_e32 v231, 0xffff0000, v139
	v_pk_add_f32 v[18:19], v[18:19], v[228:229]
	v_pk_add_f32 v[20:21], v[20:21], v[230:231]
	v_pk_fma_f32 v[218:219], v[18:19], v[18:19], v[218:219]
	v_pk_fma_f32 v[218:219], v[20:21], v[20:21], v[218:219]
	v_cvt_pk_bf16_f32 v138, v18, v19
	v_cvt_pk_bf16_f32 v139, v20, v21
	s_mov_b64 exec, s[68:69]
	global_store_dwordx2 v182, v[138:139], s[40:41] offset:2048
	s_mov_b64 exec, -1
	global_load_dwordx4 v[86:89], v179, s[6:7] offset:1024 nt
	s_waitcnt vmcnt(37)
	v_lshlrev_b32_e32 v228, 16, v140
	v_and_b32_e32 v229, 0xffff0000, v140
	v_lshlrev_b32_e32 v230, 16, v141
	v_and_b32_e32 v231, 0xffff0000, v141
	v_pk_add_f32 v[22:23], v[22:23], v[228:229]
	v_pk_add_f32 v[24:25], v[24:25], v[230:231]
	v_pk_fma_f32 v[218:219], v[22:23], v[22:23], v[218:219]
	v_pk_fma_f32 v[218:219], v[24:25], v[24:25], v[218:219]
	v_cvt_pk_bf16_f32 v140, v22, v23
	v_cvt_pk_bf16_f32 v141, v24, v25
	s_mov_b64 exec, s[68:69]
	global_store_dwordx2 v182, v[140:141], s[40:41] offset:2560
	s_mov_b64 exec, -1
	global_load_dwordx4 v[90:93], v179, s[6:7] offset:2048 nt
	s_waitcnt vmcnt(38)
	v_lshlrev_b32_e32 v228, 16, v142
	v_and_b32_e32 v229, 0xffff0000, v142
	v_lshlrev_b32_e32 v230, 16, v143
	v_and_b32_e32 v231, 0xffff0000, v143
	v_pk_add_f32 v[26:27], v[26:27], v[228:229]
	v_pk_add_f32 v[28:29], v[28:29], v[230:231]
	v_pk_fma_f32 v[218:219], v[26:27], v[26:27], v[218:219]
	v_pk_fma_f32 v[218:219], v[28:29], v[28:29], v[218:219]
	v_cvt_pk_bf16_f32 v142, v26, v27
	v_cvt_pk_bf16_f32 v143, v28, v29
	s_mov_b64 exec, s[68:69]
	global_store_dwordx2 v182, v[142:143], s[40:41] offset:3072
	s_mov_b64 exec, -1
	global_load_dwordx4 v[94:97], v179, s[6:7] offset:3072 nt
	s_waitcnt vmcnt(39)
	v_lshlrev_b32_e32 v228, 16, v144
	v_and_b32_e32 v229, 0xffff0000, v144
	v_lshlrev_b32_e32 v230, 16, v145
	v_and_b32_e32 v231, 0xffff0000, v145
	v_pk_add_f32 v[30:31], v[30:31], v[228:229]
	v_pk_add_f32 v[32:33], v[32:33], v[230:231]
	v_pk_fma_f32 v[218:219], v[30:31], v[30:31], v[218:219]
	v_pk_fma_f32 v[218:219], v[32:33], v[32:33], v[218:219]
	v_cvt_pk_bf16_f32 v144, v30, v31
	v_cvt_pk_bf16_f32 v145, v32, v33
	s_mov_b64 exec, s[68:69]
	global_store_dwordx2 v182, v[144:145], s[40:41] offset:3584
	s_mov_b64 exec, -1
	global_load_dwordx4 v[98:101], v180, s[6:7] nt
	s_waitcnt vmcnt(40)
	v_lshlrev_b32_e32 v228, 16, v146
	v_and_b32_e32 v229, 0xffff0000, v146
	v_lshlrev_b32_e32 v230, 16, v147
	v_and_b32_e32 v231, 0xffff0000, v147
	v_pk_add_f32 v[34:35], v[34:35], v[228:229]
	v_pk_add_f32 v[36:37], v[36:37], v[230:231]
	v_pk_fma_f32 v[218:219], v[34:35], v[34:35], v[218:219]
	v_pk_fma_f32 v[218:219], v[36:37], v[36:37], v[218:219]
	v_cvt_pk_bf16_f32 v146, v34, v35
	v_cvt_pk_bf16_f32 v147, v36, v37
	s_mov_b64 exec, s[68:69]
	global_store_dwordx2 v183, v[146:147], s[40:41]
	s_mov_b64 exec, -1
	global_load_dwordx4 v[102:105], v180, s[6:7] offset:1024 nt
	s_waitcnt vmcnt(41)
	v_lshlrev_b32_e32 v228, 16, v148
	v_and_b32_e32 v229, 0xffff0000, v148
	v_lshlrev_b32_e32 v230, 16, v149
	v_and_b32_e32 v231, 0xffff0000, v149
	v_pk_add_f32 v[38:39], v[38:39], v[228:229]
	v_pk_add_f32 v[40:41], v[40:41], v[230:231]
	v_pk_fma_f32 v[218:219], v[38:39], v[38:39], v[218:219]
	v_pk_fma_f32 v[218:219], v[40:41], v[40:41], v[218:219]
	v_cvt_pk_bf16_f32 v148, v38, v39
	v_cvt_pk_bf16_f32 v149, v40, v41
	s_mov_b64 exec, s[68:69]
	global_store_dwordx2 v183, v[148:149], s[40:41] offset:512
	s_mov_b64 exec, -1
	global_load_dwordx4 v[106:109], v180, s[6:7] offset:2048 nt
	s_waitcnt vmcnt(42)
	v_lshlrev_b32_e32 v228, 16, v150
	v_and_b32_e32 v229, 0xffff0000, v150
	v_lshlrev_b32_e32 v230, 16, v151
	v_and_b32_e32 v231, 0xffff0000, v151
	v_pk_add_f32 v[42:43], v[42:43], v[228:229]
	v_pk_add_f32 v[44:45], v[44:45], v[230:231]
	v_pk_fma_f32 v[218:219], v[42:43], v[42:43], v[218:219]
	v_pk_fma_f32 v[218:219], v[44:45], v[44:45], v[218:219]
	v_cvt_pk_bf16_f32 v150, v42, v43
	v_cvt_pk_bf16_f32 v151, v44, v45
	s_mov_b64 exec, s[68:69]
	global_store_dwordx2 v183, v[150:151], s[40:41] offset:1024
	s_mov_b64 exec, -1
	global_load_dwordx4 v[110:113], v180, s[6:7] offset:3072 nt
	s_waitcnt vmcnt(43)
	v_lshlrev_b32_e32 v228, 16, v152
	v_and_b32_e32 v229, 0xffff0000, v152
	v_lshlrev_b32_e32 v230, 16, v153
	v_and_b32_e32 v231, 0xffff0000, v153
	v_pk_add_f32 v[46:47], v[46:47], v[228:229]
	v_pk_add_f32 v[48:49], v[48:49], v[230:231]
	v_pk_fma_f32 v[218:219], v[46:47], v[46:47], v[218:219]
	v_pk_fma_f32 v[218:219], v[48:49], v[48:49], v[218:219]
	v_cvt_pk_bf16_f32 v152, v46, v47
	v_cvt_pk_bf16_f32 v153, v48, v49
	s_mov_b64 exec, s[68:69]
	global_store_dwordx2 v183, v[152:153], s[40:41] offset:1536
	s_mov_b64 exec, -1
	global_load_dwordx4 v[114:117], v181, s[6:7] nt
	s_waitcnt vmcnt(44)
	v_lshlrev_b32_e32 v228, 16, v154
	v_and_b32_e32 v229, 0xffff0000, v154
	v_lshlrev_b32_e32 v230, 16, v155
	v_and_b32_e32 v231, 0xffff0000, v155
	v_pk_add_f32 v[50:51], v[50:51], v[228:229]
	v_pk_add_f32 v[52:53], v[52:53], v[230:231]
	v_pk_fma_f32 v[218:219], v[50:51], v[50:51], v[218:219]
	v_pk_fma_f32 v[218:219], v[52:53], v[52:53], v[218:219]
	v_cvt_pk_bf16_f32 v154, v50, v51
	v_cvt_pk_bf16_f32 v155, v52, v53
	s_mov_b64 exec, s[68:69]
	global_store_dwordx2 v183, v[154:155], s[40:41] offset:2048
	s_mov_b64 exec, -1
	global_load_dwordx4 v[118:121], v181, s[6:7] offset:1024 nt
	s_waitcnt vmcnt(45)
	v_lshlrev_b32_e32 v228, 16, v156
	v_and_b32_e32 v229, 0xffff0000, v156
	v_lshlrev_b32_e32 v230, 16, v157
	v_and_b32_e32 v231, 0xffff0000, v157
	v_pk_add_f32 v[54:55], v[54:55], v[228:229]
	v_pk_add_f32 v[56:57], v[56:57], v[230:231]
	v_pk_fma_f32 v[218:219], v[54:55], v[54:55], v[218:219]
	v_pk_fma_f32 v[218:219], v[56:57], v[56:57], v[218:219]
	v_cvt_pk_bf16_f32 v156, v54, v55
	v_cvt_pk_bf16_f32 v157, v56, v57
	s_mov_b64 exec, s[68:69]
	global_store_dwordx2 v183, v[156:157], s[40:41] offset:2560
	s_mov_b64 exec, -1
	global_load_dwordx4 v[122:125], v181, s[6:7] offset:2048 nt
	s_waitcnt vmcnt(46)
	v_lshlrev_b32_e32 v228, 16, v158
	v_and_b32_e32 v229, 0xffff0000, v158
	v_lshlrev_b32_e32 v230, 16, v159
	v_and_b32_e32 v231, 0xffff0000, v159
	v_pk_add_f32 v[58:59], v[58:59], v[228:229]
	v_pk_add_f32 v[60:61], v[60:61], v[230:231]
	v_pk_fma_f32 v[218:219], v[58:59], v[58:59], v[218:219]
	v_pk_fma_f32 v[218:219], v[60:61], v[60:61], v[218:219]
	v_cvt_pk_bf16_f32 v158, v58, v59
	v_cvt_pk_bf16_f32 v159, v60, v61
	s_mov_b64 exec, s[68:69]
	global_store_dwordx2 v183, v[158:159], s[40:41] offset:3072
	s_mov_b64 exec, -1
	global_load_dwordx4 v[126:129], v181, s[6:7] offset:3072 nt
	s_waitcnt vmcnt(47)
	v_lshlrev_b32_e32 v228, 16, v160
	v_and_b32_e32 v229, 0xffff0000, v160
	v_lshlrev_b32_e32 v230, 16, v161
	v_and_b32_e32 v231, 0xffff0000, v161
	v_pk_add_f32 v[62:63], v[62:63], v[228:229]
	v_pk_add_f32 v[64:65], v[64:65], v[230:231]
	v_pk_fma_f32 v[218:219], v[62:63], v[62:63], v[218:219]
	v_pk_fma_f32 v[218:219], v[64:65], v[64:65], v[218:219]
	v_cvt_pk_bf16_f32 v160, v62, v63
	v_cvt_pk_bf16_f32 v161, v64, v65
	s_mov_b64 exec, s[68:69]
	global_store_dwordx2 v183, v[160:161], s[40:41] offset:3584
	s_mov_b64 exec, -1
	s_waitcnt vmcnt(31)
	v_lshlrev_b32_e32 v228, 16, v162
	v_and_b32_e32 v229, 0xffff0000, v162
	v_lshlrev_b32_e32 v230, 16, v163
	v_and_b32_e32 v231, 0xffff0000, v163
	v_pk_add_f32 v[66:67], v[66:67], v[228:229]
	v_pk_add_f32 v[68:69], v[68:69], v[230:231]
	v_pk_mul_f32 v[220:221], v[66:67], v[66:67]
	v_pk_fma_f32 v[220:221], v[68:69], v[68:69], v[220:221]
	v_cvt_pk_bf16_f32 v162, v66, v67
	v_cvt_pk_bf16_f32 v163, v68, v69
	s_mov_b64 exec, s[68:69]
	global_store_dwordx2 v182, v[162:163], s[66:67]
	s_mov_b64 exec, -1
	s_waitcnt vmcnt(30)
	v_lshlrev_b32_e32 v228, 16, v164
	v_and_b32_e32 v229, 0xffff0000, v164
	v_lshlrev_b32_e32 v230, 16, v165
	v_and_b32_e32 v231, 0xffff0000, v165
	v_pk_add_f32 v[70:71], v[70:71], v[228:229]
	v_pk_add_f32 v[72:73], v[72:73], v[230:231]
	v_pk_fma_f32 v[220:221], v[70:71], v[70:71], v[220:221]
	v_pk_fma_f32 v[220:221], v[72:73], v[72:73], v[220:221]
	v_cvt_pk_bf16_f32 v164, v70, v71
	v_cvt_pk_bf16_f32 v165, v72, v73
	s_mov_b64 exec, s[68:69]
	global_store_dwordx2 v182, v[164:165], s[66:67] offset:512
	s_mov_b64 exec, -1
	s_waitcnt vmcnt(29)
	v_lshlrev_b32_e32 v228, 16, v166
	v_and_b32_e32 v229, 0xffff0000, v166
	v_lshlrev_b32_e32 v230, 16, v167
	v_and_b32_e32 v231, 0xffff0000, v167
	v_pk_add_f32 v[74:75], v[74:75], v[228:229]
	v_pk_add_f32 v[76:77], v[76:77], v[230:231]
	v_pk_fma_f32 v[220:221], v[74:75], v[74:75], v[220:221]
	v_pk_fma_f32 v[220:221], v[76:77], v[76:77], v[220:221]
	v_cvt_pk_bf16_f32 v166, v74, v75
	v_cvt_pk_bf16_f32 v167, v76, v77
	s_mov_b64 exec, s[68:69]
	global_store_dwordx2 v182, v[166:167], s[66:67] offset:1024
	s_mov_b64 exec, -1
	s_waitcnt vmcnt(28)
	v_lshlrev_b32_e32 v228, 16, v168
	v_and_b32_e32 v229, 0xffff0000, v168
	v_lshlrev_b32_e32 v230, 16, v169
	v_and_b32_e32 v231, 0xffff0000, v169
	v_pk_add_f32 v[78:79], v[78:79], v[228:229]
	v_pk_add_f32 v[80:81], v[80:81], v[230:231]
	v_pk_fma_f32 v[220:221], v[78:79], v[78:79], v[220:221]
	v_pk_fma_f32 v[220:221], v[80:81], v[80:81], v[220:221]
	v_cvt_pk_bf16_f32 v168, v78, v79
	v_cvt_pk_bf16_f32 v169, v80, v81
	s_mov_b64 exec, s[68:69]
	global_store_dwordx2 v182, v[168:169], s[66:67] offset:1536
	s_mov_b64 exec, -1
	s_waitcnt vmcnt(27)
	v_lshlrev_b32_e32 v228, 16, v170
	v_and_b32_e32 v229, 0xffff0000, v170
	v_lshlrev_b32_e32 v230, 16, v171
	v_and_b32_e32 v231, 0xffff0000, v171
	v_pk_add_f32 v[82:83], v[82:83], v[228:229]
	v_pk_add_f32 v[84:85], v[84:85], v[230:231]
	v_pk_fma_f32 v[220:221], v[82:83], v[82:83], v[220:221]
	v_pk_fma_f32 v[220:221], v[84:85], v[84:85], v[220:221]
	v_cvt_pk_bf16_f32 v170, v82, v83
	v_cvt_pk_bf16_f32 v171, v84, v85
	s_mov_b64 exec, s[68:69]
	global_store_dwordx2 v182, v[170:171], s[66:67] offset:2048
	s_mov_b64 exec, -1
	s_waitcnt vmcnt(26)
	v_lshlrev_b32_e32 v228, 16, v172
	v_and_b32_e32 v229, 0xffff0000, v172
	v_lshlrev_b32_e32 v230, 16, v173
	v_and_b32_e32 v231, 0xffff0000, v173
	v_pk_add_f32 v[86:87], v[86:87], v[228:229]
	v_pk_add_f32 v[88:89], v[88:89], v[230:231]
	v_pk_fma_f32 v[220:221], v[86:87], v[86:87], v[220:221]
	v_pk_fma_f32 v[220:221], v[88:89], v[88:89], v[220:221]
	v_cvt_pk_bf16_f32 v172, v86, v87
	v_cvt_pk_bf16_f32 v173, v88, v89
	s_mov_b64 exec, s[68:69]
	global_store_dwordx2 v182, v[172:173], s[66:67] offset:2560
	s_mov_b64 exec, -1
	s_waitcnt vmcnt(25)
	v_lshlrev_b32_e32 v228, 16, v174
	v_and_b32_e32 v229, 0xffff0000, v174
	v_lshlrev_b32_e32 v230, 16, v175
	v_and_b32_e32 v231, 0xffff0000, v175
	v_pk_add_f32 v[90:91], v[90:91], v[228:229]
	v_pk_add_f32 v[92:93], v[92:93], v[230:231]
	v_pk_fma_f32 v[220:221], v[90:91], v[90:91], v[220:221]
	v_pk_fma_f32 v[220:221], v[92:93], v[92:93], v[220:221]
	v_cvt_pk_bf16_f32 v174, v90, v91
	v_cvt_pk_bf16_f32 v175, v92, v93
	s_mov_b64 exec, s[68:69]
	global_store_dwordx2 v182, v[174:175], s[66:67] offset:3072
	s_mov_b64 exec, -1
	s_waitcnt vmcnt(24)
	v_lshlrev_b32_e32 v228, 16, v176
	v_and_b32_e32 v229, 0xffff0000, v176
	v_lshlrev_b32_e32 v230, 16, v177
	v_and_b32_e32 v231, 0xffff0000, v177
	v_pk_add_f32 v[94:95], v[94:95], v[228:229]
	v_pk_add_f32 v[96:97], v[96:97], v[230:231]
	v_pk_fma_f32 v[220:221], v[94:95], v[94:95], v[220:221]
	v_pk_fma_f32 v[220:221], v[96:97], v[96:97], v[220:221]
	v_cvt_pk_bf16_f32 v176, v94, v95
	v_cvt_pk_bf16_f32 v177, v96, v97
	s_mov_b64 exec, s[68:69]
	global_store_dwordx2 v182, v[176:177], s[66:67] offset:3584
	s_mov_b64 exec, -1
	s_waitcnt vmcnt(23)
	v_lshlrev_b32_e32 v228, 16, v236
	v_and_b32_e32 v229, 0xffff0000, v236
	v_lshlrev_b32_e32 v230, 16, v237
	v_and_b32_e32 v231, 0xffff0000, v237
	v_pk_add_f32 v[98:99], v[98:99], v[228:229]
	v_pk_add_f32 v[100:101], v[100:101], v[230:231]
	v_pk_fma_f32 v[220:221], v[98:99], v[98:99], v[220:221]
	v_pk_fma_f32 v[220:221], v[100:101], v[100:101], v[220:221]
	v_cvt_pk_bf16_f32 v236, v98, v99
	v_cvt_pk_bf16_f32 v237, v100, v101
	s_mov_b64 exec, s[68:69]
	global_store_dwordx2 v183, v[236:237], s[66:67]
	s_mov_b64 exec, -1
	s_waitcnt vmcnt(22)
	v_lshlrev_b32_e32 v228, 16, v238
	v_and_b32_e32 v229, 0xffff0000, v238
	v_lshlrev_b32_e32 v230, 16, v239
	v_and_b32_e32 v231, 0xffff0000, v239
	v_pk_add_f32 v[102:103], v[102:103], v[228:229]
	v_pk_add_f32 v[104:105], v[104:105], v[230:231]
	v_pk_fma_f32 v[220:221], v[102:103], v[102:103], v[220:221]
	v_pk_fma_f32 v[220:221], v[104:105], v[104:105], v[220:221]
	v_cvt_pk_bf16_f32 v238, v102, v103
	v_cvt_pk_bf16_f32 v239, v104, v105
	s_mov_b64 exec, s[68:69]
	global_store_dwordx2 v183, v[238:239], s[66:67] offset:512
	s_mov_b64 exec, -1
	s_waitcnt vmcnt(21)
	v_lshlrev_b32_e32 v228, 16, v240
	v_and_b32_e32 v229, 0xffff0000, v240
	v_lshlrev_b32_e32 v230, 16, v241
	v_and_b32_e32 v231, 0xffff0000, v241
	v_pk_add_f32 v[106:107], v[106:107], v[228:229]
	v_pk_add_f32 v[108:109], v[108:109], v[230:231]
	v_pk_fma_f32 v[220:221], v[106:107], v[106:107], v[220:221]
	v_pk_fma_f32 v[220:221], v[108:109], v[108:109], v[220:221]
	v_cvt_pk_bf16_f32 v240, v106, v107
	v_cvt_pk_bf16_f32 v241, v108, v109
	s_mov_b64 exec, s[68:69]
	global_store_dwordx2 v183, v[240:241], s[66:67] offset:1024
	s_mov_b64 exec, -1
	s_waitcnt vmcnt(20)
	v_lshlrev_b32_e32 v228, 16, v242
	v_and_b32_e32 v229, 0xffff0000, v242
	v_lshlrev_b32_e32 v230, 16, v243
	v_and_b32_e32 v231, 0xffff0000, v243
	v_pk_add_f32 v[110:111], v[110:111], v[228:229]
	v_pk_add_f32 v[112:113], v[112:113], v[230:231]
	v_pk_fma_f32 v[220:221], v[110:111], v[110:111], v[220:221]
	v_pk_fma_f32 v[220:221], v[112:113], v[112:113], v[220:221]
	v_cvt_pk_bf16_f32 v242, v110, v111
	v_cvt_pk_bf16_f32 v243, v112, v113
	s_mov_b64 exec, s[68:69]
	global_store_dwordx2 v183, v[242:243], s[66:67] offset:1536
	s_mov_b64 exec, -1
	s_waitcnt vmcnt(19)
	v_lshlrev_b32_e32 v228, 16, v244
	v_and_b32_e32 v229, 0xffff0000, v244
	v_lshlrev_b32_e32 v230, 16, v245
	v_and_b32_e32 v231, 0xffff0000, v245
	v_pk_add_f32 v[114:115], v[114:115], v[228:229]
	v_pk_add_f32 v[116:117], v[116:117], v[230:231]
	v_pk_fma_f32 v[220:221], v[114:115], v[114:115], v[220:221]
	v_pk_fma_f32 v[220:221], v[116:117], v[116:117], v[220:221]
	v_cvt_pk_bf16_f32 v244, v114, v115
	v_cvt_pk_bf16_f32 v245, v116, v117
	s_mov_b64 exec, s[68:69]
	global_store_dwordx2 v183, v[244:245], s[66:67] offset:2048
	s_mov_b64 exec, -1
	s_waitcnt vmcnt(18)
	v_lshlrev_b32_e32 v228, 16, v246
	v_and_b32_e32 v229, 0xffff0000, v246
	v_lshlrev_b32_e32 v230, 16, v247
	v_and_b32_e32 v231, 0xffff0000, v247
	v_pk_add_f32 v[118:119], v[118:119], v[228:229]
	v_pk_add_f32 v[120:121], v[120:121], v[230:231]
	v_pk_fma_f32 v[220:221], v[118:119], v[118:119], v[220:221]
	v_pk_fma_f32 v[220:221], v[120:121], v[120:121], v[220:221]
	v_cvt_pk_bf16_f32 v246, v118, v119
	v_cvt_pk_bf16_f32 v247, v120, v121
	s_mov_b64 exec, s[68:69]
	global_store_dwordx2 v183, v[246:247], s[66:67] offset:2560
	s_mov_b64 exec, -1
	s_waitcnt vmcnt(17)
	v_lshlrev_b32_e32 v228, 16, v248
	v_and_b32_e32 v229, 0xffff0000, v248
	v_lshlrev_b32_e32 v230, 16, v249
	v_and_b32_e32 v231, 0xffff0000, v249
	v_pk_add_f32 v[122:123], v[122:123], v[228:229]
	v_pk_add_f32 v[124:125], v[124:125], v[230:231]
	v_pk_fma_f32 v[220:221], v[122:123], v[122:123], v[220:221]
	v_pk_fma_f32 v[220:221], v[124:125], v[124:125], v[220:221]
	v_cvt_pk_bf16_f32 v248, v122, v123
	v_cvt_pk_bf16_f32 v249, v124, v125
	s_mov_b64 exec, s[68:69]
	global_store_dwordx2 v183, v[248:249], s[66:67] offset:3072
	s_mov_b64 exec, -1
	s_waitcnt vmcnt(16)
	v_lshlrev_b32_e32 v228, 16, v250
	v_and_b32_e32 v229, 0xffff0000, v250
	v_lshlrev_b32_e32 v230, 16, v251
	v_and_b32_e32 v231, 0xffff0000, v251
	v_pk_add_f32 v[126:127], v[126:127], v[228:229]
	v_pk_add_f32 v[128:129], v[128:129], v[230:231]
	v_pk_fma_f32 v[220:221], v[126:127], v[126:127], v[220:221]
	v_pk_fma_f32 v[220:221], v[128:129], v[128:129], v[220:221]
	v_cvt_pk_bf16_f32 v250, v126, v127
	v_cvt_pk_bf16_f32 v251, v128, v129
	s_mov_b64 exec, s[68:69]
	global_store_dwordx2 v183, v[250:251], s[66:67] offset:3584
	s_mov_b64 exec, -1
	s_branch .Lpb_sums
.Lpb_l0:
	global_load_dwordx4 v[2:5], v178, s[4:5] nt
	global_load_dwordx4 v[6:9], v178, s[4:5] offset:1024 nt
	global_load_dwordx4 v[10:13], v178, s[4:5] offset:2048 nt
	global_load_dwordx4 v[14:17], v178, s[4:5] offset:3072 nt
	global_load_dwordx4 v[18:21], v179, s[4:5] nt
	global_load_dwordx4 v[22:25], v179, s[4:5] offset:1024 nt
	global_load_dwordx4 v[26:29], v179, s[4:5] offset:2048 nt
	global_load_dwordx4 v[30:33], v179, s[4:5] offset:3072 nt
	global_load_dwordx4 v[34:37], v180, s[4:5] nt
	global_load_dwordx4 v[38:41], v180, s[4:5] offset:1024 nt
	global_load_dwordx4 v[42:45], v180, s[4:5] offset:2048 nt
	global_load_dwordx4 v[46:49], v180, s[4:5] offset:3072 nt
	global_load_dwordx4 v[50:53], v181, s[4:5] nt
	global_load_dwordx4 v[54:57], v181, s[4:5] offset:1024 nt
	global_load_dwordx4 v[58:61], v181, s[4:5] offset:2048 nt
	global_load_dwordx4 v[62:65], v181, s[4:5] offset:3072 nt
	global_load_dwordx4 v[66:69], v178, s[6:7] nt
	global_load_dwordx4 v[70:73], v178, s[6:7] offset:1024 nt
	global_load_dwordx4 v[74:77], v178, s[6:7] offset:2048 nt
	global_load_dwordx4 v[78:81], v178, s[6:7] offset:3072 nt
	global_load_dwordx4 v[82:85], v179, s[6:7] nt
	global_load_dwordx4 v[86:89], v179, s[6:7] offset:1024 nt
	global_load_dwordx4 v[90:93], v179, s[6:7] offset:2048 nt
	global_load_dwordx4 v[94:97], v179, s[6:7] offset:3072 nt
	global_load_dwordx4 v[98:101], v180, s[6:7] nt
	global_load_dwordx4 v[102:105], v180, s[6:7] offset:1024 nt
	global_load_dwordx4 v[106:109], v180, s[6:7] offset:2048 nt
	global_load_dwordx4 v[110:113], v180, s[6:7] offset:3072 nt
	global_load_dwordx4 v[114:117], v181, s[6:7] nt
	global_load_dwordx4 v[118:121], v181, s[6:7] offset:1024 nt
	global_load_dwordx4 v[122:125], v181, s[6:7] offset:2048 nt
	global_load_dwordx4 v[126:129], v181, s[6:7] offset:3072 nt
	s_waitcnt vmcnt(31)
	v_pk_mul_f32 v[218:219], v[2:3], v[2:3]
	v_pk_fma_f32 v[218:219], v[4:5], v[4:5], v[218:219]
	s_waitcnt vmcnt(30)
	v_pk_fma_f32 v[218:219], v[6:7], v[6:7], v[218:219]
	v_pk_fma_f32 v[218:219], v[8:9], v[8:9], v[218:219]
	s_waitcnt vmcnt(29)
	v_pk_fma_f32 v[218:219], v[10:11], v[10:11], v[218:219]
	v_pk_fma_f32 v[218:219], v[12:13], v[12:13], v[218:219]
	s_waitcnt vmcnt(28)
	v_pk_fma_f32 v[218:219], v[14:15], v[14:15], v[218:219]
	v_pk_fma_f32 v[218:219], v[16:17], v[16:17], v[218:219]
	s_waitcnt vmcnt(27)
	v_pk_fma_f32 v[218:219], v[18:19], v[18:19], v[218:219]
	v_pk_fma_f32 v[218:219], v[20:21], v[20:21], v[218:219]
	s_waitcnt vmcnt(26)
	v_pk_fma_f32 v[218:219], v[22:23], v[22:23], v[218:219]
	v_pk_fma_f32 v[218:219], v[24:25], v[24:25], v[218:219]
	s_waitcnt vmcnt(25)
	v_pk_fma_f32 v[218:219], v[26:27], v[26:27], v[218:219]
	v_pk_fma_f32 v[218:219], v[28:29], v[28:29], v[218:219]
	s_waitcnt vmcnt(24)
	v_pk_fma_f32 v[218:219], v[30:31], v[30:31], v[218:219]
	v_pk_fma_f32 v[218:219], v[32:33], v[32:33], v[218:219]
	s_waitcnt vmcnt(23)
	v_pk_fma_f32 v[218:219], v[34:35], v[34:35], v[218:219]
	v_pk_fma_f32 v[218:219], v[36:37], v[36:37], v[218:219]
	s_waitcnt vmcnt(22)
	v_pk_fma_f32 v[218:219], v[38:39], v[38:39], v[218:219]
	v_pk_fma_f32 v[218:219], v[40:41], v[40:41], v[218:219]
	s_waitcnt vmcnt(21)
	v_pk_fma_f32 v[218:219], v[42:43], v[42:43], v[218:219]
	v_pk_fma_f32 v[218:219], v[44:45], v[44:45], v[218:219]
	s_waitcnt vmcnt(20)
	v_pk_fma_f32 v[218:219], v[46:47], v[46:47], v[218:219]
	v_pk_fma_f32 v[218:219], v[48:49], v[48:49], v[218:219]
	s_waitcnt vmcnt(19)
	v_pk_fma_f32 v[218:219], v[50:51], v[50:51], v[218:219]
	v_pk_fma_f32 v[218:219], v[52:53], v[52:53], v[218:219]
	s_waitcnt vmcnt(18)
	v_pk_fma_f32 v[218:219], v[54:55], v[54:55], v[218:219]
	v_pk_fma_f32 v[218:219], v[56:57], v[56:57], v[218:219]
	s_waitcnt vmcnt(17)
	v_pk_fma_f32 v[218:219], v[58:59], v[58:59], v[218:219]
	v_pk_fma_f32 v[218:219], v[60:61], v[60:61], v[218:219]
	s_waitcnt vmcnt(16)
	v_pk_fma_f32 v[218:219], v[62:63], v[62:63], v[218:219]
	v_pk_fma_f32 v[218:219], v[64:65], v[64:65], v[218:219]
	s_waitcnt vmcnt(15)
	v_pk_mul_f32 v[220:221], v[66:67], v[66:67]
	v_pk_fma_f32 v[220:221], v[68:69], v[68:69], v[220:221]
	s_waitcnt vmcnt(14)
	v_pk_fma_f32 v[220:221], v[70:71], v[70:71], v[220:221]
	v_pk_fma_f32 v[220:221], v[72:73], v[72:73], v[220:221]
	s_waitcnt vmcnt(13)
	v_pk_fma_f32 v[220:221], v[74:75], v[74:75], v[220:221]
	v_pk_fma_f32 v[220:221], v[76:77], v[76:77], v[220:221]
	s_waitcnt vmcnt(12)
	v_pk_fma_f32 v[220:221], v[78:79], v[78:79], v[220:221]
	v_pk_fma_f32 v[220:221], v[80:81], v[80:81], v[220:221]
	s_waitcnt vmcnt(11)
	v_pk_fma_f32 v[220:221], v[82:83], v[82:83], v[220:221]
	v_pk_fma_f32 v[220:221], v[84:85], v[84:85], v[220:221]
	s_waitcnt vmcnt(10)
	v_pk_fma_f32 v[220:221], v[86:87], v[86:87], v[220:221]
	v_pk_fma_f32 v[220:221], v[88:89], v[88:89], v[220:221]
	s_waitcnt vmcnt(9)
	v_pk_fma_f32 v[220:221], v[90:91], v[90:91], v[220:221]
	v_pk_fma_f32 v[220:221], v[92:93], v[92:93], v[220:221]
	s_waitcnt vmcnt(8)
	v_pk_fma_f32 v[220:221], v[94:95], v[94:95], v[220:221]
	v_pk_fma_f32 v[220:221], v[96:97], v[96:97], v[220:221]
	s_waitcnt vmcnt(7)
	v_pk_fma_f32 v[220:221], v[98:99], v[98:99], v[220:221]
	v_pk_fma_f32 v[220:221], v[100:101], v[100:101], v[220:221]
	s_waitcnt vmcnt(6)
	v_pk_fma_f32 v[220:221], v[102:103], v[102:103], v[220:221]
	v_pk_fma_f32 v[220:221], v[104:105], v[104:105], v[220:221]
	s_waitcnt vmcnt(5)
	v_pk_fma_f32 v[220:221], v[106:107], v[106:107], v[220:221]
	v_pk_fma_f32 v[220:221], v[108:109], v[108:109], v[220:221]
	s_waitcnt vmcnt(4)
	v_pk_fma_f32 v[220:221], v[110:111], v[110:111], v[220:221]
	v_pk_fma_f32 v[220:221], v[112:113], v[112:113], v[220:221]
	s_waitcnt vmcnt(3)
	v_pk_fma_f32 v[220:221], v[114:115], v[114:115], v[220:221]
	v_pk_fma_f32 v[220:221], v[116:117], v[116:117], v[220:221]
	s_waitcnt vmcnt(2)
	v_pk_fma_f32 v[220:221], v[118:119], v[118:119], v[220:221]
	v_pk_fma_f32 v[220:221], v[120:121], v[120:121], v[220:221]
	s_waitcnt vmcnt(1)
	v_pk_fma_f32 v[220:221], v[122:123], v[122:123], v[220:221]
	v_pk_fma_f32 v[220:221], v[124:125], v[124:125], v[220:221]
	s_waitcnt vmcnt(0)
	v_pk_fma_f32 v[220:221], v[126:127], v[126:127], v[220:221]
	v_pk_fma_f32 v[220:221], v[128:129], v[128:129], v[220:221]

.Lpb_l1c:
	s_add_u32 s40, s50, 0xaf78000
	s_addc_u32 s41, s51, 0
	global_load_dwordx4 v[2:5], v178, s[4:5] nt
	global_load_dwordx4 v[6:9], v178, s[4:5] offset:1024 nt
	global_load_dwordx4 v[10:13], v178, s[4:5] offset:2048 nt
	global_load_dwordx4 v[14:17], v178, s[4:5] offset:3072 nt
	global_load_dwordx4 v[18:21], v179, s[4:5] nt
	global_load_dwordx4 v[22:25], v179, s[4:5] offset:1024 nt
	global_load_dwordx4 v[26:29], v179, s[4:5] offset:2048 nt
	global_load_dwordx4 v[30:33], v179, s[4:5] offset:3072 nt
	global_load_dwordx4 v[34:37], v180, s[4:5] nt
	global_load_dwordx4 v[38:41], v180, s[4:5] offset:1024 nt
	global_load_dwordx4 v[42:45], v180, s[4:5] offset:2048 nt
	global_load_dwordx4 v[46:49], v180, s[4:5] offset:3072 nt
	global_load_dwordx4 v[50:53], v181, s[4:5] nt
	global_load_dwordx4 v[54:57], v181, s[4:5] offset:1024 nt
	global_load_dwordx4 v[58:61], v181, s[4:5] offset:2048 nt
	global_load_dwordx4 v[62:65], v181, s[4:5] offset:3072 nt
	global_load_dwordx4 v[130:133], v178, s[40:41]
	global_load_dwordx4 v[134:137], v178, s[40:41] offset:1024
	global_load_dwordx4 v[138:141], v178, s[40:41] offset:2048
	global_load_dwordx4 v[142:145], v178, s[40:41] offset:3072
	s_mov_b64 s[68:69], s[70:71]
	global_load_dwordx4 v[146:149], v178, s[68:69] nt
	global_load_dwordx4 v[150:153], v178, s[68:69] offset:1024 nt
	global_load_dwordx4 v[154:157], v178, s[68:69] offset:2048 nt
	global_load_dwordx4 v[158:161], v178, s[68:69] offset:3072 nt
	s_add_u32 s68, s68, 0x1000000
	s_addc_u32 s69, s69, 0
	global_load_dwordx4 v[162:165], v178, s[68:69] nt
	global_load_dwordx4 v[166:169], v178, s[68:69] offset:1024 nt
	global_load_dwordx4 v[170:173], v178, s[68:69] offset:2048 nt
	global_load_dwordx4 v[174:177], v178, s[68:69] offset:3072 nt
	s_add_u32 s68, s68, 0x1000000
	s_addc_u32 s69, s69, 0
	global_load_dwordx4 v[66:69], v178, s[68:69] nt
	global_load_dwordx4 v[70:73], v178, s[68:69] offset:1024 nt
	global_load_dwordx4 v[74:77], v178, s[68:69] offset:2048 nt
	global_load_dwordx4 v[78:81], v178, s[68:69] offset:3072 nt
	s_add_u32 s68, s68, 0x1000000
	s_addc_u32 s69, s69, 0
	global_load_dwordx4 v[82:85], v178, s[68:69] nt
	global_load_dwordx4 v[86:89], v178, s[68:69] offset:1024 nt
	global_load_dwordx4 v[90:93], v178, s[68:69] offset:2048 nt
	global_load_dwordx4 v[94:97], v178, s[68:69] offset:3072 nt
	s_waitcnt vmcnt(35)
	s_waitcnt vmcnt(3)
	v_pk_add_f32 v[146:147], v[146:147], v[162:163]
	v_pk_add_f32 v[66:67], v[66:67], v[82:83]
	v_pk_add_f32 v[146:147], v[146:147], v[66:67]
	v_pk_fma_f32 v[2:3], v[130:131], v[146:147], v[2:3]
	v_pk_add_f32 v[148:149], v[148:149], v[164:165]
	v_pk_add_f32 v[68:69], v[68:69], v[84:85]
	v_pk_add_f32 v[148:149], v[148:149], v[68:69]
	v_pk_fma_f32 v[4:5], v[132:133], v[148:149], v[4:5]
	v_pk_mul_f32 v[218:219], v[2:3], v[2:3]
	v_pk_fma_f32 v[218:219], v[4:5], v[4:5], v[218:219]
	s_waitcnt vmcnt(2)
	v_pk_add_f32 v[150:151], v[150:151], v[166:167]
	v_pk_add_f32 v[70:71], v[70:71], v[86:87]
	v_pk_add_f32 v[150:151], v[150:151], v[70:71]
	v_pk_fma_f32 v[6:7], v[134:135], v[150:151], v[6:7]
	v_pk_add_f32 v[152:153], v[152:153], v[168:169]
	v_pk_add_f32 v[72:73], v[72:73], v[88:89]
	v_pk_add_f32 v[152:153], v[152:153], v[72:73]
	v_pk_fma_f32 v[8:9], v[136:137], v[152:153], v[8:9]
	v_pk_fma_f32 v[218:219], v[6:7], v[6:7], v[218:219]
	v_pk_fma_f32 v[218:219], v[8:9], v[8:9], v[218:219]
	s_waitcnt vmcnt(1)
	v_pk_add_f32 v[154:155], v[154:155], v[170:171]
	v_pk_add_f32 v[74:75], v[74:75], v[90:91]
	v_pk_add_f32 v[154:155], v[154:155], v[74:75]
	v_pk_fma_f32 v[10:11], v[138:139], v[154:155], v[10:11]
	v_pk_add_f32 v[156:157], v[156:157], v[172:173]
	v_pk_add_f32 v[76:77], v[76:77], v[92:93]
	v_pk_add_f32 v[156:157], v[156:157], v[76:77]
	v_pk_fma_f32 v[12:13], v[140:141], v[156:157], v[12:13]
	v_pk_fma_f32 v[218:219], v[10:11], v[10:11], v[218:219]
	v_pk_fma_f32 v[218:219], v[12:13], v[12:13], v[218:219]
	s_waitcnt vmcnt(0)
	v_pk_add_f32 v[158:159], v[158:159], v[174:175]
	v_pk_add_f32 v[78:79], v[78:79], v[94:95]
	v_pk_add_f32 v[158:159], v[158:159], v[78:79]
	v_pk_fma_f32 v[14:15], v[142:143], v[158:159], v[14:15]
	v_pk_add_f32 v[160:161], v[160:161], v[176:177]
	v_pk_add_f32 v[80:81], v[80:81], v[96:97]
	v_pk_add_f32 v[160:161], v[160:161], v[80:81]
	v_pk_fma_f32 v[16:17], v[144:145], v[160:161], v[16:17]
	v_pk_fma_f32 v[218:219], v[14:15], v[14:15], v[218:219]
	v_pk_fma_f32 v[218:219], v[16:17], v[16:17], v[218:219]
	global_load_dwordx4 v[130:133], v179, s[40:41]
	global_load_dwordx4 v[134:137], v179, s[40:41] offset:1024
	global_load_dwordx4 v[138:141], v179, s[40:41] offset:2048
	global_load_dwordx4 v[142:145], v179, s[40:41] offset:3072
	s_mov_b64 s[68:69], s[70:71]
	global_load_dwordx4 v[146:149], v179, s[68:69] nt
	global_load_dwordx4 v[150:153], v179, s[68:69] offset:1024 nt
	global_load_dwordx4 v[154:157], v179, s[68:69] offset:2048 nt
	global_load_dwordx4 v[158:161], v179, s[68:69] offset:3072 nt
	s_add_u32 s68, s68, 0x1000000
	s_addc_u32 s69, s69, 0
	global_load_dwordx4 v[162:165], v179, s[68:69] nt
	global_load_dwordx4 v[166:169], v179, s[68:69] offset:1024 nt
	global_load_dwordx4 v[170:173], v179, s[68:69] offset:2048 nt
	global_load_dwordx4 v[174:177], v179, s[68:69] offset:3072 nt
	s_add_u32 s68, s68, 0x1000000
	s_addc_u32 s69, s69, 0
	global_load_dwordx4 v[66:69], v179, s[68:69] nt
	global_load_dwordx4 v[70:73], v179, s[68:69] offset:1024 nt
	global_load_dwordx4 v[74:77], v179, s[68:69] offset:2048 nt
	global_load_dwordx4 v[78:81], v179, s[68:69] offset:3072 nt
	s_add_u32 s68, s68, 0x1000000
	s_addc_u32 s69, s69, 0
	global_load_dwordx4 v[82:85], v179, s[68:69] nt
	global_load_dwordx4 v[86:89], v179, s[68:69] offset:1024 nt
	global_load_dwordx4 v[90:93], v179, s[68:69] offset:2048 nt
	global_load_dwordx4 v[94:97], v179, s[68:69] offset:3072 nt
	s_waitcnt vmcnt(3)
	v_pk_add_f32 v[146:147], v[146:147], v[162:163]
	v_pk_add_f32 v[66:67], v[66:67], v[82:83]
	v_pk_add_f32 v[146:147], v[146:147], v[66:67]
	v_pk_fma_f32 v[18:19], v[130:131], v[146:147], v[18:19]
	v_pk_add_f32 v[148:149], v[148:149], v[164:165]
	v_pk_add_f32 v[68:69], v[68:69], v[84:85]
	v_pk_add_f32 v[148:149], v[148:149], v[68:69]
	v_pk_fma_f32 v[20:21], v[132:133], v[148:149], v[20:21]
	v_pk_fma_f32 v[218:219], v[18:19], v[18:19], v[218:219]
	v_pk_fma_f32 v[218:219], v[20:21], v[20:21], v[218:219]
	s_waitcnt vmcnt(2)
	v_pk_add_f32 v[150:151], v[150:151], v[166:167]
	v_pk_add_f32 v[70:71], v[70:71], v[86:87]
	v_pk_add_f32 v[150:151], v[150:151], v[70:71]
	v_pk_fma_f32 v[22:23], v[134:135], v[150:151], v[22:23]
	v_pk_add_f32 v[152:153], v[152:153], v[168:169]
	v_pk_add_f32 v[72:73], v[72:73], v[88:89]
	v_pk_add_f32 v[152:153], v[152:153], v[72:73]
	v_pk_fma_f32 v[24:25], v[136:137], v[152:153], v[24:25]
	v_pk_fma_f32 v[218:219], v[22:23], v[22:23], v[218:219]
	v_pk_fma_f32 v[218:219], v[24:25], v[24:25], v[218:219]
	s_waitcnt vmcnt(1)
	v_pk_add_f32 v[154:155], v[154:155], v[170:171]
	v_pk_add_f32 v[74:75], v[74:75], v[90:91]
	v_pk_add_f32 v[154:155], v[154:155], v[74:75]
	v_pk_fma_f32 v[26:27], v[138:139], v[154:155], v[26:27]
	v_pk_add_f32 v[156:157], v[156:157], v[172:173]
	v_pk_add_f32 v[76:77], v[76:77], v[92:93]
	v_pk_add_f32 v[156:157], v[156:157], v[76:77]
	v_pk_fma_f32 v[28:29], v[140:141], v[156:157], v[28:29]
	v_pk_fma_f32 v[218:219], v[26:27], v[26:27], v[218:219]
	v_pk_fma_f32 v[218:219], v[28:29], v[28:29], v[218:219]
	s_waitcnt vmcnt(0)
	v_pk_add_f32 v[158:159], v[158:159], v[174:175]
	v_pk_add_f32 v[78:79], v[78:79], v[94:95]
	v_pk_add_f32 v[158:159], v[158:159], v[78:79]
	v_pk_fma_f32 v[30:31], v[142:143], v[158:159], v[30:31]
	v_pk_add_f32 v[160:161], v[160:161], v[176:177]
	v_pk_add_f32 v[80:81], v[80:81], v[96:97]
	v_pk_add_f32 v[160:161], v[160:161], v[80:81]
	v_pk_fma_f32 v[32:33], v[144:145], v[160:161], v[32:33]
	v_pk_fma_f32 v[218:219], v[30:31], v[30:31], v[218:219]
	v_pk_fma_f32 v[218:219], v[32:33], v[32:33], v[218:219]
	global_load_dwordx4 v[130:133], v180, s[40:41]
	global_load_dwordx4 v[134:137], v180, s[40:41] offset:1024
	global_load_dwordx4 v[138:141], v180, s[40:41] offset:2048
	global_load_dwordx4 v[142:145], v180, s[40:41] offset:3072
	s_mov_b64 s[68:69], s[70:71]
	global_load_dwordx4 v[146:149], v180, s[68:69] nt
	global_load_dwordx4 v[150:153], v180, s[68:69] offset:1024 nt
	global_load_dwordx4 v[154:157], v180, s[68:69] offset:2048 nt
	global_load_dwordx4 v[158:161], v180, s[68:69] offset:3072 nt
	s_add_u32 s68, s68, 0x1000000
	s_addc_u32 s69, s69, 0
	global_load_dwordx4 v[162:165], v180, s[68:69] nt
	global_load_dwordx4 v[166:169], v180, s[68:69] offset:1024 nt
	global_load_dwordx4 v[170:173], v180, s[68:69] offset:2048 nt
	global_load_dwordx4 v[174:177], v180, s[68:69] offset:3072 nt
	s_add_u32 s68, s68, 0x1000000
	s_addc_u32 s69, s69, 0
	global_load_dwordx4 v[66:69], v180, s[68:69] nt
	global_load_dwordx4 v[70:73], v180, s[68:69] offset:1024 nt
	global_load_dwordx4 v[74:77], v180, s[68:69] offset:2048 nt
	global_load_dwordx4 v[78:81], v180, s[68:69] offset:3072 nt
	s_add_u32 s68, s68, 0x1000000
	s_addc_u32 s69, s69, 0
	global_load_dwordx4 v[82:85], v180, s[68:69] nt
	global_load_dwordx4 v[86:89], v180, s[68:69] offset:1024 nt
	global_load_dwordx4 v[90:93], v180, s[68:69] offset:2048 nt
	global_load_dwordx4 v[94:97], v180, s[68:69] offset:3072 nt
	s_waitcnt vmcnt(3)
	v_pk_add_f32 v[146:147], v[146:147], v[162:163]
	v_pk_add_f32 v[66:67], v[66:67], v[82:83]
	v_pk_add_f32 v[146:147], v[146:147], v[66:67]
	v_pk_fma_f32 v[34:35], v[130:131], v[146:147], v[34:35]
	v_pk_add_f32 v[148:149], v[148:149], v[164:165]
	v_pk_add_f32 v[68:69], v[68:69], v[84:85]
	v_pk_add_f32 v[148:149], v[148:149], v[68:69]
	v_pk_fma_f32 v[36:37], v[132:133], v[148:149], v[36:37]
	v_pk_fma_f32 v[218:219], v[34:35], v[34:35], v[218:219]
	v_pk_fma_f32 v[218:219], v[36:37], v[36:37], v[218:219]
	s_waitcnt vmcnt(2)
	v_pk_add_f32 v[150:151], v[150:151], v[166:167]
	v_pk_add_f32 v[70:71], v[70:71], v[86:87]
	v_pk_add_f32 v[150:151], v[150:151], v[70:71]
	v_pk_fma_f32 v[38:39], v[134:135], v[150:151], v[38:39]
	v_pk_add_f32 v[152:153], v[152:153], v[168:169]
	v_pk_add_f32 v[72:73], v[72:73], v[88:89]
	v_pk_add_f32 v[152:153], v[152:153], v[72:73]
	v_pk_fma_f32 v[40:41], v[136:137], v[152:153], v[40:41]
	v_pk_fma_f32 v[218:219], v[38:39], v[38:39], v[218:219]
	v_pk_fma_f32 v[218:219], v[40:41], v[40:41], v[218:219]
	s_waitcnt vmcnt(1)
	v_pk_add_f32 v[154:155], v[154:155], v[170:171]
	v_pk_add_f32 v[74:75], v[74:75], v[90:91]
	v_pk_add_f32 v[154:155], v[154:155], v[74:75]
	v_pk_fma_f32 v[42:43], v[138:139], v[154:155], v[42:43]
	v_pk_add_f32 v[156:157], v[156:157], v[172:173]
	v_pk_add_f32 v[76:77], v[76:77], v[92:93]
	v_pk_add_f32 v[156:157], v[156:157], v[76:77]
	v_pk_fma_f32 v[44:45], v[140:141], v[156:157], v[44:45]
	v_pk_fma_f32 v[218:219], v[42:43], v[42:43], v[218:219]
	v_pk_fma_f32 v[218:219], v[44:45], v[44:45], v[218:219]
	s_waitcnt vmcnt(0)
	v_pk_add_f32 v[158:159], v[158:159], v[174:175]
	v_pk_add_f32 v[78:79], v[78:79], v[94:95]
	v_pk_add_f32 v[158:159], v[158:159], v[78:79]
	v_pk_fma_f32 v[46:47], v[142:143], v[158:159], v[46:47]
	v_pk_add_f32 v[160:161], v[160:161], v[176:177]
	v_pk_add_f32 v[80:81], v[80:81], v[96:97]
	v_pk_add_f32 v[160:161], v[160:161], v[80:81]
	v_pk_fma_f32 v[48:49], v[144:145], v[160:161], v[48:49]
	v_pk_fma_f32 v[218:219], v[46:47], v[46:47], v[218:219]
	v_pk_fma_f32 v[218:219], v[48:49], v[48:49], v[218:219]
	global_load_dwordx4 v[130:133], v181, s[40:41]
	global_load_dwordx4 v[134:137], v181, s[40:41] offset:1024
	global_load_dwordx4 v[138:141], v181, s[40:41] offset:2048
	global_load_dwordx4 v[142:145], v181, s[40:41] offset:3072
	s_mov_b64 s[68:69], s[70:71]
	global_load_dwordx4 v[146:149], v181, s[68:69] nt
	global_load_dwordx4 v[150:153], v181, s[68:69] offset:1024 nt
	global_load_dwordx4 v[154:157], v181, s[68:69] offset:2048 nt
	global_load_dwordx4 v[158:161], v181, s[68:69] offset:3072 nt
	s_add_u32 s68, s68, 0x1000000
	s_addc_u32 s69, s69, 0
	global_load_dwordx4 v[162:165], v181, s[68:69] nt
	global_load_dwordx4 v[166:169], v181, s[68:69] offset:1024 nt
	global_load_dwordx4 v[170:173], v181, s[68:69] offset:2048 nt
	global_load_dwordx4 v[174:177], v181, s[68:69] offset:3072 nt
	s_add_u32 s68, s68, 0x1000000
	s_addc_u32 s69, s69, 0
	global_load_dwordx4 v[66:69], v181, s[68:69] nt
	global_load_dwordx4 v[70:73], v181, s[68:69] offset:1024 nt
	global_load_dwordx4 v[74:77], v181, s[68:69] offset:2048 nt
	global_load_dwordx4 v[78:81], v181, s[68:69] offset:3072 nt
	s_add_u32 s68, s68, 0x1000000
	s_addc_u32 s69, s69, 0
	global_load_dwordx4 v[82:85], v181, s[68:69] nt
	global_load_dwordx4 v[86:89], v181, s[68:69] offset:1024 nt
	global_load_dwordx4 v[90:93], v181, s[68:69] offset:2048 nt
	global_load_dwordx4 v[94:97], v181, s[68:69] offset:3072 nt
	s_waitcnt vmcnt(3)
	v_pk_add_f32 v[146:147], v[146:147], v[162:163]
	v_pk_add_f32 v[66:67], v[66:67], v[82:83]
	v_pk_add_f32 v[146:147], v[146:147], v[66:67]
	v_pk_fma_f32 v[50:51], v[130:131], v[146:147], v[50:51]
	v_pk_add_f32 v[148:149], v[148:149], v[164:165]
	v_pk_add_f32 v[68:69], v[68:69], v[84:85]
	v_pk_add_f32 v[148:149], v[148:149], v[68:69]
	v_pk_fma_f32 v[52:53], v[132:133], v[148:149], v[52:53]
	v_pk_fma_f32 v[218:219], v[50:51], v[50:51], v[218:219]
	v_pk_fma_f32 v[218:219], v[52:53], v[52:53], v[218:219]
	s_waitcnt vmcnt(2)
	v_pk_add_f32 v[150:151], v[150:151], v[166:167]
	v_pk_add_f32 v[70:71], v[70:71], v[86:87]
	v_pk_add_f32 v[150:151], v[150:151], v[70:71]
	v_pk_fma_f32 v[54:55], v[134:135], v[150:151], v[54:55]
	v_pk_add_f32 v[152:153], v[152:153], v[168:169]
	v_pk_add_f32 v[72:73], v[72:73], v[88:89]
	v_pk_add_f32 v[152:153], v[152:153], v[72:73]
	v_pk_fma_f32 v[56:57], v[136:137], v[152:153], v[56:57]
	v_pk_fma_f32 v[218:219], v[54:55], v[54:55], v[218:219]
	v_pk_fma_f32 v[218:219], v[56:57], v[56:57], v[218:219]
	s_waitcnt vmcnt(1)
	v_pk_add_f32 v[154:155], v[154:155], v[170:171]
	v_pk_add_f32 v[74:75], v[74:75], v[90:91]
	v_pk_add_f32 v[154:155], v[154:155], v[74:75]
	v_pk_fma_f32 v[58:59], v[138:139], v[154:155], v[58:59]
	v_pk_add_f32 v[156:157], v[156:157], v[172:173]
	v_pk_add_f32 v[76:77], v[76:77], v[92:93]
	v_pk_add_f32 v[156:157], v[156:157], v[76:77]
	v_pk_fma_f32 v[60:61], v[140:141], v[156:157], v[60:61]
	v_pk_fma_f32 v[218:219], v[58:59], v[58:59], v[218:219]
	v_pk_fma_f32 v[218:219], v[60:61], v[60:61], v[218:219]
	s_waitcnt vmcnt(0)
	v_pk_add_f32 v[158:159], v[158:159], v[174:175]
	v_pk_add_f32 v[78:79], v[78:79], v[94:95]
	v_pk_add_f32 v[158:159], v[158:159], v[78:79]
	v_pk_fma_f32 v[62:63], v[142:143], v[158:159], v[62:63]
	v_pk_add_f32 v[160:161], v[160:161], v[176:177]
	v_pk_add_f32 v[80:81], v[80:81], v[96:97]
	v_pk_add_f32 v[160:161], v[160:161], v[80:81]
	v_pk_fma_f32 v[64:65], v[144:145], v[160:161], v[64:65]
	v_pk_fma_f32 v[218:219], v[62:63], v[62:63], v[218:219]
	v_pk_fma_f32 v[218:219], v[64:65], v[64:65], v[218:219]
	v_add_f32_e32 v217, v218, v219
	s_nop 1
	v_add_f32_dpp v217, v217, v217 row_shr:1 row_mask:0xf bank_mask:0xf bound_ctrl:1
	s_nop 1
	v_add_f32_dpp v217, v217, v217 row_shr:2 row_mask:0xf bank_mask:0xf bound_ctrl:1
	s_nop 1
	v_add_f32_dpp v217, v217, v217 row_shr:4 row_mask:0xf bank_mask:0xf bound_ctrl:1
	s_nop 1
	v_add_f32_dpp v217, v217, v217 row_shr:8 row_mask:0xf bank_mask:0xf bound_ctrl:1
	v_mov_b32_e32 v222, v195
	s_nop 1
	v_mov_b32_dpp v222, v217 row_bcast:15 row_mask:0xa bank_mask:0xf bound_ctrl:1
	v_add_f32_e32 v217, v217, v222
	v_mov_b32_e32 v222, v195
	s_nop 1
	v_mov_b32_dpp v222, v217 row_bcast:31 row_mask:0xc bank_mask:0xf bound_ctrl:1
	v_add_f32_e32 v217, v217, v222
	s_nop 1
	v_readlane_b32 s0, v217, 63
	s_nop 3
	v_fma_f32 v217, s0, v209, v202
	v_cmp_gt_f32_e32 vcc, s25, v217
	v_mul_f32_e32 v222, 0x4f800000, v217
	s_nop 1
	v_cndmask_b32_e32 v217, v217, v222, vcc
	v_sqrt_f32_e32 v222, v217
	s_nop 1
	v_add_u32_e32 v223, -1, v222
	v_fma_f32 v226, -v223, v222, v217
	v_cmp_ge_f32_e64 s[68:69], 0, v226
	v_add_u32_e32 v226, 1, v222
	s_nop 1
	v_cndmask_b32_e64 v223, v222, v223, s[68:69]
	v_fma_f32 v222, -v226, v222, v217
	v_cmp_lt_f32_e64 s[68:69], 0, v222
	s_nop 1
	v_cndmask_b32_e64 v222, v223, v226, s[68:69]
	v_mul_f32_e32 v223, 0x37800000, v222
	v_cndmask_b32_e32 v222, v222, v223, vcc
	v_cmp_class_f32_e32 vcc, v217, v203
	s_nop 1
	v_cndmask_b32_e32 v217, v222, v217, vcc
	v_div_scale_f32 v222, s[68:69], v217, v217, 1.0
	v_rcp_f32_e32 v223, v222
	s_nop 1
	v_fma_f32 v226, -v222, v223, 1.0
	v_fmac_f32_e32 v223, v226, v223
	v_div_scale_f32 v226, vcc, 1.0, v217, 1.0
	v_mul_f32_e32 v227, v226, v223
	v_fma_f32 v194, -v222, v227, v226
	v_fmac_f32_e32 v227, v194, v223
	v_fma_f32 v222, -v222, v227, v226
	s_nop 1
	v_div_fmas_f32 v222, v222, v223, v227
	v_div_fixup_f32 v224, v222, v217, 1.0
	global_load_dwordx4 v[130:133], v178, s[48:49]
	global_load_dwordx4 v[134:137], v178, s[12:13]
	global_load_dwordx4 v[138:141], v178, s[38:39]
	global_load_dwordx4 v[142:145], v178, s[48:49] offset:1024
	global_load_dwordx4 v[146:149], v178, s[12:13] offset:1024
	global_load_dwordx4 v[150:153], v178, s[38:39] offset:1024
	global_load_dwordx4 v[154:157], v178, s[48:49] offset:2048
	global_load_dwordx4 v[158:161], v178, s[12:13] offset:2048
	global_load_dwordx4 v[162:165], v178, s[38:39] offset:2048
	global_load_dwordx4 v[166:169], v178, s[48:49] offset:3072
	global_load_dwordx4 v[170:173], v178, s[12:13] offset:3072
	global_load_dwordx4 v[174:177], v178, s[38:39] offset:3072
	v_pk_mul_f32 v[2:3], v[2:3], v[224:225] op_sel_hi:[1,0]
	v_pk_mul_f32 v[4:5], v[4:5], v[224:225] op_sel_hi:[1,0]
	s_waitcnt vmcnt(11)
	v_pk_mul_f32 v[2:3], v[130:131], v[2:3]
	v_pk_mul_f32 v[4:5], v[132:133], v[4:5]
	s_waitcnt vmcnt(9)
	v_pk_add_f32 v[138:139], v[138:139], 1.0 op_sel_hi:[1,0]
	v_pk_add_f32 v[140:141], v[140:141], 1.0 op_sel_hi:[1,0]
	v_pk_fma_f32 v[2:3], v[2:3], v[138:139], v[134:135]
	v_pk_fma_f32 v[4:5], v[4:5], v[140:141], v[136:137]
	s_nop 0
	v_cvt_pk_bf16_f32 v2, v2, v3
	v_cvt_pk_bf16_f32 v3, v4, v5
	global_load_dwordx4 v[130:133], v179, s[48:49]
	global_load_dwordx4 v[134:137], v179, s[12:13]
	global_load_dwordx4 v[138:141], v179, s[38:39]
	global_store_dwordx2 v182, v[2:3], s[8:9]
	s_waitcnt lgkmcnt(6)
	ds_write_b64 v184, v[2:3]
	v_pk_mul_f32 v[6:7], v[6:7], v[224:225] op_sel_hi:[1,0]
	v_pk_mul_f32 v[8:9], v[8:9], v[224:225] op_sel_hi:[1,0]
	s_waitcnt vmcnt(12)
	v_pk_mul_f32 v[6:7], v[142:143], v[6:7]
	v_pk_mul_f32 v[8:9], v[144:145], v[8:9]
	s_waitcnt vmcnt(10)
	v_pk_add_f32 v[150:151], v[150:151], 1.0 op_sel_hi:[1,0]
	v_pk_add_f32 v[152:153], v[152:153], 1.0 op_sel_hi:[1,0]
	v_pk_fma_f32 v[6:7], v[6:7], v[150:151], v[146:147]
	v_pk_fma_f32 v[8:9], v[8:9], v[152:153], v[148:149]
	s_nop 0
	v_cvt_pk_bf16_f32 v6, v6, v7
	v_cvt_pk_bf16_f32 v7, v8, v9
	global_load_dwordx4 v[142:145], v179, s[48:49] offset:1024
	global_load_dwordx4 v[146:149], v179, s[12:13] offset:1024
	global_load_dwordx4 v[150:153], v179, s[38:39] offset:1024
	global_store_dwordx2 v182, v[6:7], s[8:9] offset:512
	s_waitcnt lgkmcnt(6)
	ds_write_b64 v184, v[6:7] offset:512
	v_pk_mul_f32 v[10:11], v[10:11], v[224:225] op_sel_hi:[1,0]
	v_pk_mul_f32 v[12:13], v[12:13], v[224:225] op_sel_hi:[1,0]
	s_waitcnt vmcnt(13)
	v_pk_mul_f32 v[10:11], v[154:155], v[10:11]
	v_pk_mul_f32 v[12:13], v[156:157], v[12:13]
	s_waitcnt vmcnt(11)
	v_pk_add_f32 v[162:163], v[162:163], 1.0 op_sel_hi:[1,0]
	v_pk_add_f32 v[164:165], v[164:165], 1.0 op_sel_hi:[1,0]
	v_pk_fma_f32 v[10:11], v[10:11], v[162:163], v[158:159]
	v_pk_fma_f32 v[12:13], v[12:13], v[164:165], v[160:161]
	s_nop 0
	v_cvt_pk_bf16_f32 v10, v10, v11
	v_cvt_pk_bf16_f32 v11, v12, v13
	global_load_dwordx4 v[154:157], v179, s[48:49] offset:2048
	global_load_dwordx4 v[158:161], v179, s[12:13] offset:2048
	global_load_dwordx4 v[162:165], v179, s[38:39] offset:2048
	global_store_dwordx2 v182, v[10:11], s[8:9] offset:1024
	s_waitcnt lgkmcnt(6)
	ds_write_b64 v184, v[10:11] offset:1024
	v_pk_mul_f32 v[14:15], v[14:15], v[224:225] op_sel_hi:[1,0]
	v_pk_mul_f32 v[16:17], v[16:17], v[224:225] op_sel_hi:[1,0]
	s_waitcnt vmcnt(14)
	v_pk_mul_f32 v[14:15], v[166:167], v[14:15]
	v_pk_mul_f32 v[16:17], v[168:169], v[16:17]
	s_waitcnt vmcnt(12)
	v_pk_add_f32 v[174:175], v[174:175], 1.0 op_sel_hi:[1,0]
	v_pk_add_f32 v[176:177], v[176:177], 1.0 op_sel_hi:[1,0]
	v_pk_fma_f32 v[14:15], v[14:15], v[174:175], v[170:171]
	v_pk_fma_f32 v[16:17], v[16:17], v[176:177], v[172:173]
	s_nop 0
	v_cvt_pk_bf16_f32 v14, v14, v15
	v_cvt_pk_bf16_f32 v15, v16, v17
	global_load_dwordx4 v[166:169], v179, s[48:49] offset:3072
	global_load_dwordx4 v[170:173], v179, s[12:13] offset:3072
	global_load_dwordx4 v[174:177], v179, s[38:39] offset:3072
	global_store_dwordx2 v182, v[14:15], s[8:9] offset:1536
	s_waitcnt lgkmcnt(6)
	ds_write_b64 v184, v[14:15] offset:1536
	v_pk_mul_f32 v[18:19], v[18:19], v[224:225] op_sel_hi:[1,0]
	v_pk_mul_f32 v[20:21], v[20:21], v[224:225] op_sel_hi:[1,0]
	s_waitcnt vmcnt(15)
	v_pk_mul_f32 v[18:19], v[130:131], v[18:19]
	v_pk_mul_f32 v[20:21], v[132:133], v[20:21]
	s_waitcnt vmcnt(13)
	v_pk_add_f32 v[138:139], v[138:139], 1.0 op_sel_hi:[1,0]
	v_pk_add_f32 v[140:141], v[140:141], 1.0 op_sel_hi:[1,0]
	v_pk_fma_f32 v[18:19], v[18:19], v[138:139], v[134:135]
	v_pk_fma_f32 v[20:21], v[20:21], v[140:141], v[136:137]
	s_nop 0
	v_cvt_pk_bf16_f32 v18, v18, v19
	v_cvt_pk_bf16_f32 v19, v20, v21
	global_load_dwordx4 v[130:133], v180, s[48:49]
	global_load_dwordx4 v[134:137], v180, s[12:13]
	global_load_dwordx4 v[138:141], v180, s[38:39]
	global_store_dwordx2 v182, v[18:19], s[8:9] offset:2048
	s_waitcnt lgkmcnt(6)
	ds_write_b64 v184, v[18:19] offset:2048
	v_pk_mul_f32 v[22:23], v[22:23], v[224:225] op_sel_hi:[1,0]
	v_pk_mul_f32 v[24:25], v[24:25], v[224:225] op_sel_hi:[1,0]
	s_waitcnt vmcnt(15)
	v_pk_mul_f32 v[22:23], v[142:143], v[22:23]
	v_pk_mul_f32 v[24:25], v[144:145], v[24:25]
	s_waitcnt vmcnt(13)
	v_pk_add_f32 v[150:151], v[150:151], 1.0 op_sel_hi:[1,0]
	v_pk_add_f32 v[152:153], v[152:153], 1.0 op_sel_hi:[1,0]
	v_pk_fma_f32 v[22:23], v[22:23], v[150:151], v[146:147]
	v_pk_fma_f32 v[24:25], v[24:25], v[152:153], v[148:149]
	s_nop 0
	v_cvt_pk_bf16_f32 v22, v22, v23
	v_cvt_pk_bf16_f32 v23, v24, v25
	global_load_dwordx4 v[142:145], v180, s[48:49] offset:1024
	global_load_dwordx4 v[146:149], v180, s[12:13] offset:1024
	global_load_dwordx4 v[150:153], v180, s[38:39] offset:1024
	global_store_dwordx2 v182, v[22:23], s[8:9] offset:2560
	s_waitcnt lgkmcnt(6)
	ds_write_b64 v184, v[22:23] offset:2560
	v_pk_mul_f32 v[26:27], v[26:27], v[224:225] op_sel_hi:[1,0]
	v_pk_mul_f32 v[28:29], v[28:29], v[224:225] op_sel_hi:[1,0]
	s_waitcnt vmcnt(15)
	v_pk_mul_f32 v[26:27], v[154:155], v[26:27]
	v_pk_mul_f32 v[28:29], v[156:157], v[28:29]
	s_waitcnt vmcnt(13)
	v_pk_add_f32 v[162:163], v[162:163], 1.0 op_sel_hi:[1,0]
	v_pk_add_f32 v[164:165], v[164:165], 1.0 op_sel_hi:[1,0]
	v_pk_fma_f32 v[26:27], v[26:27], v[162:163], v[158:159]
	v_pk_fma_f32 v[28:29], v[28:29], v[164:165], v[160:161]
	s_nop 0
	v_cvt_pk_bf16_f32 v26, v26, v27
	v_cvt_pk_bf16_f32 v27, v28, v29
	global_load_dwordx4 v[154:157], v180, s[48:49] offset:2048
	global_load_dwordx4 v[158:161], v180, s[12:13] offset:2048
	global_load_dwordx4 v[162:165], v180, s[38:39] offset:2048
	global_store_dwordx2 v182, v[26:27], s[8:9] offset:3072
	s_waitcnt lgkmcnt(6)
	ds_write_b64 v184, v[26:27] offset:3072
	v_pk_mul_f32 v[30:31], v[30:31], v[224:225] op_sel_hi:[1,0]
	v_pk_mul_f32 v[32:33], v[32:33], v[224:225] op_sel_hi:[1,0]
	s_waitcnt vmcnt(15)
	v_pk_mul_f32 v[30:31], v[166:167], v[30:31]
	v_pk_mul_f32 v[32:33], v[168:169], v[32:33]
	s_waitcnt vmcnt(13)
	v_pk_add_f32 v[174:175], v[174:175], 1.0 op_sel_hi:[1,0]
	v_pk_add_f32 v[176:177], v[176:177], 1.0 op_sel_hi:[1,0]
	v_pk_fma_f32 v[30:31], v[30:31], v[174:175], v[170:171]
	v_pk_fma_f32 v[32:33], v[32:33], v[176:177], v[172:173]
	s_nop 0
	v_cvt_pk_bf16_f32 v30, v30, v31
	v_cvt_pk_bf16_f32 v31, v32, v33
	global_load_dwordx4 v[166:169], v180, s[48:49] offset:3072
	global_load_dwordx4 v[170:173], v180, s[12:13] offset:3072
	global_load_dwordx4 v[174:177], v180, s[38:39] offset:3072
	global_store_dwordx2 v182, v[30:31], s[8:9] offset:3584
	s_waitcnt lgkmcnt(6)
	ds_write_b64 v184, v[30:31] offset:3584
	v_pk_mul_f32 v[34:35], v[34:35], v[224:225] op_sel_hi:[1,0]
	v_pk_mul_f32 v[36:37], v[36:37], v[224:225] op_sel_hi:[1,0]
	s_waitcnt vmcnt(15)
	v_pk_mul_f32 v[34:35], v[130:131], v[34:35]
	v_pk_mul_f32 v[36:37], v[132:133], v[36:37]
	s_waitcnt vmcnt(13)
	v_pk_add_f32 v[138:139], v[138:139], 1.0 op_sel_hi:[1,0]
	v_pk_add_f32 v[140:141], v[140:141], 1.0 op_sel_hi:[1,0]
	v_pk_fma_f32 v[34:35], v[34:35], v[138:139], v[134:135]
	v_pk_fma_f32 v[36:37], v[36:37], v[140:141], v[136:137]
	s_nop 0
	v_cvt_pk_bf16_f32 v34, v34, v35
	v_cvt_pk_bf16_f32 v35, v36, v37
	global_load_dwordx4 v[130:133], v181, s[48:49]
	global_load_dwordx4 v[134:137], v181, s[12:13]
	global_load_dwordx4 v[138:141], v181, s[38:39]
	global_store_dwordx2 v183, v[34:35], s[8:9]
	s_waitcnt lgkmcnt(6)
	ds_write_b64 v184, v[34:35] offset:4096
	v_pk_mul_f32 v[38:39], v[38:39], v[224:225] op_sel_hi:[1,0]
	v_pk_mul_f32 v[40:41], v[40:41], v[224:225] op_sel_hi:[1,0]
	s_waitcnt vmcnt(15)
	v_pk_mul_f32 v[38:39], v[142:143], v[38:39]
	v_pk_mul_f32 v[40:41], v[144:145], v[40:41]
	s_waitcnt vmcnt(13)
	v_pk_add_f32 v[150:151], v[150:151], 1.0 op_sel_hi:[1,0]
	v_pk_add_f32 v[152:153], v[152:153], 1.0 op_sel_hi:[1,0]
	v_pk_fma_f32 v[38:39], v[38:39], v[150:151], v[146:147]
	v_pk_fma_f32 v[40:41], v[40:41], v[152:153], v[148:149]
	s_nop 0
	v_cvt_pk_bf16_f32 v38, v38, v39
	v_cvt_pk_bf16_f32 v39, v40, v41
	global_load_dwordx4 v[142:145], v181, s[48:49] offset:1024
	global_load_dwordx4 v[146:149], v181, s[12:13] offset:1024
	global_load_dwordx4 v[150:153], v181, s[38:39] offset:1024
	global_store_dwordx2 v183, v[38:39], s[8:9] offset:512
	s_waitcnt lgkmcnt(6)
	ds_write_b64 v184, v[38:39] offset:4608
	v_pk_mul_f32 v[42:43], v[42:43], v[224:225] op_sel_hi:[1,0]
	v_pk_mul_f32 v[44:45], v[44:45], v[224:225] op_sel_hi:[1,0]
	s_waitcnt vmcnt(15)
	v_pk_mul_f32 v[42:43], v[154:155], v[42:43]
	v_pk_mul_f32 v[44:45], v[156:157], v[44:45]
	s_waitcnt vmcnt(13)
	v_pk_add_f32 v[162:163], v[162:163], 1.0 op_sel_hi:[1,0]
	v_pk_add_f32 v[164:165], v[164:165], 1.0 op_sel_hi:[1,0]
	v_pk_fma_f32 v[42:43], v[42:43], v[162:163], v[158:159]
	v_pk_fma_f32 v[44:45], v[44:45], v[164:165], v[160:161]
	s_nop 0
	v_cvt_pk_bf16_f32 v42, v42, v43
	v_cvt_pk_bf16_f32 v43, v44, v45
	global_load_dwordx4 v[154:157], v181, s[48:49] offset:2048
	global_load_dwordx4 v[158:161], v181, s[12:13] offset:2048
	global_load_dwordx4 v[162:165], v181, s[38:39] offset:2048
	global_store_dwordx2 v183, v[42:43], s[8:9] offset:1024
	s_waitcnt lgkmcnt(6)
	ds_write_b64 v184, v[42:43] offset:5120
	v_pk_mul_f32 v[46:47], v[46:47], v[224:225] op_sel_hi:[1,0]
	v_pk_mul_f32 v[48:49], v[48:49], v[224:225] op_sel_hi:[1,0]
	s_waitcnt vmcnt(15)
	v_pk_mul_f32 v[46:47], v[166:167], v[46:47]
	v_pk_mul_f32 v[48:49], v[168:169], v[48:49]
	s_waitcnt vmcnt(13)
	v_pk_add_f32 v[174:175], v[174:175], 1.0 op_sel_hi:[1,0]
	v_pk_add_f32 v[176:177], v[176:177], 1.0 op_sel_hi:[1,0]
	v_pk_fma_f32 v[46:47], v[46:47], v[174:175], v[170:171]
	v_pk_fma_f32 v[48:49], v[48:49], v[176:177], v[172:173]
	s_nop 0
	v_cvt_pk_bf16_f32 v46, v46, v47
	v_cvt_pk_bf16_f32 v47, v48, v49
	global_load_dwordx4 v[166:169], v181, s[48:49] offset:3072
	global_load_dwordx4 v[170:173], v181, s[12:13] offset:3072
	global_load_dwordx4 v[174:177], v181, s[38:39] offset:3072
	global_store_dwordx2 v183, v[46:47], s[8:9] offset:1536
	s_waitcnt lgkmcnt(6)
	ds_write_b64 v184, v[46:47] offset:5632
	v_pk_mul_f32 v[50:51], v[50:51], v[224:225] op_sel_hi:[1,0]
	v_pk_mul_f32 v[52:53], v[52:53], v[224:225] op_sel_hi:[1,0]
	s_waitcnt vmcnt(15)
	v_pk_mul_f32 v[50:51], v[130:131], v[50:51]
	v_pk_mul_f32 v[52:53], v[132:133], v[52:53]
	s_waitcnt vmcnt(13)
	v_pk_add_f32 v[138:139], v[138:139], 1.0 op_sel_hi:[1,0]
	v_pk_add_f32 v[140:141], v[140:141], 1.0 op_sel_hi:[1,0]
	v_pk_fma_f32 v[50:51], v[50:51], v[138:139], v[134:135]
	v_pk_fma_f32 v[52:53], v[52:53], v[140:141], v[136:137]
	s_nop 0
	v_cvt_pk_bf16_f32 v50, v50, v51
	v_cvt_pk_bf16_f32 v51, v52, v53
	global_store_dwordx2 v183, v[50:51], s[8:9] offset:2048
	s_waitcnt lgkmcnt(6)
	ds_write_b64 v184, v[50:51] offset:6144
	v_pk_mul_f32 v[54:55], v[54:55], v[224:225] op_sel_hi:[1,0]
	v_pk_mul_f32 v[56:57], v[56:57], v[224:225] op_sel_hi:[1,0]
	s_waitcnt vmcnt(12)
	v_pk_mul_f32 v[54:55], v[142:143], v[54:55]
	v_pk_mul_f32 v[56:57], v[144:145], v[56:57]
	s_waitcnt vmcnt(10)
	v_pk_add_f32 v[150:151], v[150:151], 1.0 op_sel_hi:[1,0]
	v_pk_add_f32 v[152:153], v[152:153], 1.0 op_sel_hi:[1,0]
	v_pk_fma_f32 v[54:55], v[54:55], v[150:151], v[146:147]
	v_pk_fma_f32 v[56:57], v[56:57], v[152:153], v[148:149]
	s_nop 0
	v_cvt_pk_bf16_f32 v54, v54, v55
	v_cvt_pk_bf16_f32 v55, v56, v57
	global_store_dwordx2 v183, v[54:55], s[8:9] offset:2560
	s_waitcnt lgkmcnt(6)
	ds_write_b64 v184, v[54:55] offset:6656
	v_pk_mul_f32 v[58:59], v[58:59], v[224:225] op_sel_hi:[1,0]
	v_pk_mul_f32 v[60:61], v[60:61], v[224:225] op_sel_hi:[1,0]
	s_waitcnt vmcnt(9)
	v_pk_mul_f32 v[58:59], v[154:155], v[58:59]
	v_pk_mul_f32 v[60:61], v[156:157], v[60:61]
	s_waitcnt vmcnt(7)
	v_pk_add_f32 v[162:163], v[162:163], 1.0 op_sel_hi:[1,0]
	v_pk_add_f32 v[164:165], v[164:165], 1.0 op_sel_hi:[1,0]
	v_pk_fma_f32 v[58:59], v[58:59], v[162:163], v[158:159]
	v_pk_fma_f32 v[60:61], v[60:61], v[164:165], v[160:161]
	s_nop 0
	v_cvt_pk_bf16_f32 v58, v58, v59
	v_cvt_pk_bf16_f32 v59, v60, v61
	global_store_dwordx2 v183, v[58:59], s[8:9] offset:3072
	s_waitcnt lgkmcnt(6)
	ds_write_b64 v184, v[58:59] offset:7168
	v_pk_mul_f32 v[62:63], v[62:63], v[224:225] op_sel_hi:[1,0]
	v_pk_mul_f32 v[64:65], v[64:65], v[224:225] op_sel_hi:[1,0]
	s_waitcnt vmcnt(6)
	v_pk_mul_f32 v[62:63], v[166:167], v[62:63]
	v_pk_mul_f32 v[64:65], v[168:169], v[64:65]
	s_waitcnt vmcnt(4)
	v_pk_add_f32 v[174:175], v[174:175], 1.0 op_sel_hi:[1,0]
	v_pk_add_f32 v[176:177], v[176:177], 1.0 op_sel_hi:[1,0]
	v_pk_fma_f32 v[62:63], v[62:63], v[174:175], v[170:171]
	v_pk_fma_f32 v[64:65], v[64:65], v[176:177], v[172:173]
	s_nop 0
	v_cvt_pk_bf16_f32 v62, v62, v63
	v_cvt_pk_bf16_f32 v63, v64, v65
	global_store_dwordx2 v183, v[62:63], s[8:9] offset:3584
	s_waitcnt lgkmcnt(6)
	ds_write_b64 v184, v[62:63] offset:7680
	s_add_u32 s70, s70, 0x4000
	s_addc_u32 s71, s71, 0
	global_load_dwordx4 v[66:69], v178, s[6:7] nt
	global_load_dwordx4 v[70:73], v178, s[6:7] offset:1024 nt
	global_load_dwordx4 v[74:77], v178, s[6:7] offset:2048 nt
	global_load_dwordx4 v[78:81], v178, s[6:7] offset:3072 nt
	global_load_dwordx4 v[82:85], v179, s[6:7] nt
	global_load_dwordx4 v[86:89], v179, s[6:7] offset:1024 nt
	global_load_dwordx4 v[90:93], v179, s[6:7] offset:2048 nt
	global_load_dwordx4 v[94:97], v179, s[6:7] offset:3072 nt
	global_load_dwordx4 v[98:101], v180, s[6:7] nt
	global_load_dwordx4 v[102:105], v180, s[6:7] offset:1024 nt
	global_load_dwordx4 v[106:109], v180, s[6:7] offset:2048 nt
	global_load_dwordx4 v[110:113], v180, s[6:7] offset:3072 nt
	global_load_dwordx4 v[114:117], v181, s[6:7] nt
	global_load_dwordx4 v[118:121], v181, s[6:7] offset:1024 nt
	global_load_dwordx4 v[122:125], v181, s[6:7] offset:2048 nt
	global_load_dwordx4 v[126:129], v181, s[6:7] offset:3072 nt
	global_load_dwordx4 v[130:133], v178, s[40:41]
	global_load_dwordx4 v[134:137], v178, s[40:41] offset:1024
	global_load_dwordx4 v[138:141], v178, s[40:41] offset:2048
	global_load_dwordx4 v[142:145], v178, s[40:41] offset:3072
	s_mov_b64 s[68:69], s[70:71]
	global_load_dwordx4 v[146:149], v178, s[68:69] nt
	global_load_dwordx4 v[150:153], v178, s[68:69] offset:1024 nt
	global_load_dwordx4 v[154:157], v178, s[68:69] offset:2048 nt
	global_load_dwordx4 v[158:161], v178, s[68:69] offset:3072 nt
	s_add_u32 s68, s68, 0x1000000
	s_addc_u32 s69, s69, 0
	global_load_dwordx4 v[162:165], v178, s[68:69] nt
	global_load_dwordx4 v[166:169], v178, s[68:69] offset:1024 nt
	global_load_dwordx4 v[170:173], v178, s[68:69] offset:2048 nt
	global_load_dwordx4 v[174:177], v178, s[68:69] offset:3072 nt
	s_add_u32 s68, s68, 0x1000000
	s_addc_u32 s69, s69, 0
	global_load_dwordx4 v[2:5], v178, s[68:69] nt
	global_load_dwordx4 v[6:9], v178, s[68:69] offset:1024 nt
	global_load_dwordx4 v[10:13], v178, s[68:69] offset:2048 nt
	global_load_dwordx4 v[14:17], v178, s[68:69] offset:3072 nt
	s_add_u32 s68, s68, 0x1000000
	s_addc_u32 s69, s69, 0
	global_load_dwordx4 v[18:21], v178, s[68:69] nt
	global_load_dwordx4 v[22:25], v178, s[68:69] offset:1024 nt
	global_load_dwordx4 v[26:29], v178, s[68:69] offset:2048 nt
	global_load_dwordx4 v[30:33], v178, s[68:69] offset:3072 nt
	s_waitcnt vmcnt(35)
	s_waitcnt vmcnt(3)
	v_pk_add_f32 v[146:147], v[146:147], v[162:163]
	v_pk_add_f32 v[2:3], v[2:3], v[18:19]
	v_pk_add_f32 v[146:147], v[146:147], v[2:3]
	v_pk_fma_f32 v[66:67], v[130:131], v[146:147], v[66:67]
	v_pk_add_f32 v[148:149], v[148:149], v[164:165]
	v_pk_add_f32 v[4:5], v[4:5], v[20:21]
	v_pk_add_f32 v[148:149], v[148:149], v[4:5]
	v_pk_fma_f32 v[68:69], v[132:133], v[148:149], v[68:69]
	v_pk_mul_f32 v[220:221], v[66:67], v[66:67]
	v_pk_fma_f32 v[220:221], v[68:69], v[68:69], v[220:221]
	s_waitcnt vmcnt(2)
	v_pk_add_f32 v[150:151], v[150:151], v[166:167]
	v_pk_add_f32 v[6:7], v[6:7], v[22:23]
	v_pk_add_f32 v[150:151], v[150:151], v[6:7]
	v_pk_fma_f32 v[70:71], v[134:135], v[150:151], v[70:71]
	v_pk_add_f32 v[152:153], v[152:153], v[168:169]
	v_pk_add_f32 v[8:9], v[8:9], v[24:25]
	v_pk_add_f32 v[152:153], v[152:153], v[8:9]
	v_pk_fma_f32 v[72:73], v[136:137], v[152:153], v[72:73]
	v_pk_fma_f32 v[220:221], v[70:71], v[70:71], v[220:221]
	v_pk_fma_f32 v[220:221], v[72:73], v[72:73], v[220:221]
	s_waitcnt vmcnt(1)
	v_pk_add_f32 v[154:155], v[154:155], v[170:171]
	v_pk_add_f32 v[10:11], v[10:11], v[26:27]
	v_pk_add_f32 v[154:155], v[154:155], v[10:11]
	v_pk_fma_f32 v[74:75], v[138:139], v[154:155], v[74:75]
	v_pk_add_f32 v[156:157], v[156:157], v[172:173]
	v_pk_add_f32 v[12:13], v[12:13], v[28:29]
	v_pk_add_f32 v[156:157], v[156:157], v[12:13]
	v_pk_fma_f32 v[76:77], v[140:141], v[156:157], v[76:77]
	v_pk_fma_f32 v[220:221], v[74:75], v[74:75], v[220:221]
	v_pk_fma_f32 v[220:221], v[76:77], v[76:77], v[220:221]
	s_waitcnt vmcnt(0)
	v_pk_add_f32 v[158:159], v[158:159], v[174:175]
	v_pk_add_f32 v[14:15], v[14:15], v[30:31]
	v_pk_add_f32 v[158:159], v[158:159], v[14:15]
	v_pk_fma_f32 v[78:79], v[142:143], v[158:159], v[78:79]
	v_pk_add_f32 v[160:161], v[160:161], v[176:177]
	v_pk_add_f32 v[16:17], v[16:17], v[32:33]
	v_pk_add_f32 v[160:161], v[160:161], v[16:17]
	v_pk_fma_f32 v[80:81], v[144:145], v[160:161], v[80:81]
	v_pk_fma_f32 v[220:221], v[78:79], v[78:79], v[220:221]
	v_pk_fma_f32 v[220:221], v[80:81], v[80:81], v[220:221]
	global_load_dwordx4 v[130:133], v179, s[40:41]
	global_load_dwordx4 v[134:137], v179, s[40:41] offset:1024
	global_load_dwordx4 v[138:141], v179, s[40:41] offset:2048
	global_load_dwordx4 v[142:145], v179, s[40:41] offset:3072
	s_mov_b64 s[68:69], s[70:71]
	global_load_dwordx4 v[146:149], v179, s[68:69] nt
	global_load_dwordx4 v[150:153], v179, s[68:69] offset:1024 nt
	global_load_dwordx4 v[154:157], v179, s[68:69] offset:2048 nt
	global_load_dwordx4 v[158:161], v179, s[68:69] offset:3072 nt
	s_add_u32 s68, s68, 0x1000000
	s_addc_u32 s69, s69, 0
	global_load_dwordx4 v[162:165], v179, s[68:69] nt
	global_load_dwordx4 v[166:169], v179, s[68:69] offset:1024 nt
	global_load_dwordx4 v[170:173], v179, s[68:69] offset:2048 nt
	global_load_dwordx4 v[174:177], v179, s[68:69] offset:3072 nt
	s_add_u32 s68, s68, 0x1000000
	s_addc_u32 s69, s69, 0
	global_load_dwordx4 v[2:5], v179, s[68:69] nt
	global_load_dwordx4 v[6:9], v179, s[68:69] offset:1024 nt
	global_load_dwordx4 v[10:13], v179, s[68:69] offset:2048 nt
	global_load_dwordx4 v[14:17], v179, s[68:69] offset:3072 nt
	s_add_u32 s68, s68, 0x1000000
	s_addc_u32 s69, s69, 0
	global_load_dwordx4 v[18:21], v179, s[68:69] nt
	global_load_dwordx4 v[22:25], v179, s[68:69] offset:1024 nt
	global_load_dwordx4 v[26:29], v179, s[68:69] offset:2048 nt
	global_load_dwordx4 v[30:33], v179, s[68:69] offset:3072 nt
	s_waitcnt vmcnt(3)
	v_pk_add_f32 v[146:147], v[146:147], v[162:163]
	v_pk_add_f32 v[2:3], v[2:3], v[18:19]
	v_pk_add_f32 v[146:147], v[146:147], v[2:3]
	v_pk_fma_f32 v[82:83], v[130:131], v[146:147], v[82:83]
	v_pk_add_f32 v[148:149], v[148:149], v[164:165]
	v_pk_add_f32 v[4:5], v[4:5], v[20:21]
	v_pk_add_f32 v[148:149], v[148:149], v[4:5]
	v_pk_fma_f32 v[84:85], v[132:133], v[148:149], v[84:85]
	v_pk_fma_f32 v[220:221], v[82:83], v[82:83], v[220:221]
	v_pk_fma_f32 v[220:221], v[84:85], v[84:85], v[220:221]
	s_waitcnt vmcnt(2)
	v_pk_add_f32 v[150:151], v[150:151], v[166:167]
	v_pk_add_f32 v[6:7], v[6:7], v[22:23]
	v_pk_add_f32 v[150:151], v[150:151], v[6:7]
	v_pk_fma_f32 v[86:87], v[134:135], v[150:151], v[86:87]
	v_pk_add_f32 v[152:153], v[152:153], v[168:169]
	v_pk_add_f32 v[8:9], v[8:9], v[24:25]
	v_pk_add_f32 v[152:153], v[152:153], v[8:9]
	v_pk_fma_f32 v[88:89], v[136:137], v[152:153], v[88:89]
	v_pk_fma_f32 v[220:221], v[86:87], v[86:87], v[220:221]
	v_pk_fma_f32 v[220:221], v[88:89], v[88:89], v[220:221]
	s_waitcnt vmcnt(1)
	v_pk_add_f32 v[154:155], v[154:155], v[170:171]
	v_pk_add_f32 v[10:11], v[10:11], v[26:27]
	v_pk_add_f32 v[154:155], v[154:155], v[10:11]
	v_pk_fma_f32 v[90:91], v[138:139], v[154:155], v[90:91]
	v_pk_add_f32 v[156:157], v[156:157], v[172:173]
	v_pk_add_f32 v[12:13], v[12:13], v[28:29]
	v_pk_add_f32 v[156:157], v[156:157], v[12:13]
	v_pk_fma_f32 v[92:93], v[140:141], v[156:157], v[92:93]
	v_pk_fma_f32 v[220:221], v[90:91], v[90:91], v[220:221]
	v_pk_fma_f32 v[220:221], v[92:93], v[92:93], v[220:221]
	s_waitcnt vmcnt(0)
	v_pk_add_f32 v[158:159], v[158:159], v[174:175]
	v_pk_add_f32 v[14:15], v[14:15], v[30:31]
	v_pk_add_f32 v[158:159], v[158:159], v[14:15]
	v_pk_fma_f32 v[94:95], v[142:143], v[158:159], v[94:95]
	v_pk_add_f32 v[160:161], v[160:161], v[176:177]
	v_pk_add_f32 v[16:17], v[16:17], v[32:33]
	v_pk_add_f32 v[160:161], v[160:161], v[16:17]
	v_pk_fma_f32 v[96:97], v[144:145], v[160:161], v[96:97]
	v_pk_fma_f32 v[220:221], v[94:95], v[94:95], v[220:221]
	v_pk_fma_f32 v[220:221], v[96:97], v[96:97], v[220:221]
	global_load_dwordx4 v[130:133], v180, s[40:41]
	global_load_dwordx4 v[134:137], v180, s[40:41] offset:1024
	global_load_dwordx4 v[138:141], v180, s[40:41] offset:2048
	global_load_dwordx4 v[142:145], v180, s[40:41] offset:3072
	s_mov_b64 s[68:69], s[70:71]
	global_load_dwordx4 v[146:149], v180, s[68:69] nt
	global_load_dwordx4 v[150:153], v180, s[68:69] offset:1024 nt
	global_load_dwordx4 v[154:157], v180, s[68:69] offset:2048 nt
	global_load_dwordx4 v[158:161], v180, s[68:69] offset:3072 nt
	s_add_u32 s68, s68, 0x1000000
	s_addc_u32 s69, s69, 0
	global_load_dwordx4 v[162:165], v180, s[68:69] nt
	global_load_dwordx4 v[166:169], v180, s[68:69] offset:1024 nt
	global_load_dwordx4 v[170:173], v180, s[68:69] offset:2048 nt
	global_load_dwordx4 v[174:177], v180, s[68:69] offset:3072 nt
	s_add_u32 s68, s68, 0x1000000
	s_addc_u32 s69, s69, 0
	global_load_dwordx4 v[2:5], v180, s[68:69] nt
	global_load_dwordx4 v[6:9], v180, s[68:69] offset:1024 nt
	global_load_dwordx4 v[10:13], v180, s[68:69] offset:2048 nt
	global_load_dwordx4 v[14:17], v180, s[68:69] offset:3072 nt
	s_add_u32 s68, s68, 0x1000000
	s_addc_u32 s69, s69, 0
	global_load_dwordx4 v[18:21], v180, s[68:69] nt
	global_load_dwordx4 v[22:25], v180, s[68:69] offset:1024 nt
	global_load_dwordx4 v[26:29], v180, s[68:69] offset:2048 nt
	global_load_dwordx4 v[30:33], v180, s[68:69] offset:3072 nt
	s_waitcnt vmcnt(3)
	v_pk_add_f32 v[146:147], v[146:147], v[162:163]
	v_pk_add_f32 v[2:3], v[2:3], v[18:19]
	v_pk_add_f32 v[146:147], v[146:147], v[2:3]
	v_pk_fma_f32 v[98:99], v[130:131], v[146:147], v[98:99]
	v_pk_add_f32 v[148:149], v[148:149], v[164:165]
	v_pk_add_f32 v[4:5], v[4:5], v[20:21]
	v_pk_add_f32 v[148:149], v[148:149], v[4:5]
	v_pk_fma_f32 v[100:101], v[132:133], v[148:149], v[100:101]
	v_pk_fma_f32 v[220:221], v[98:99], v[98:99], v[220:221]
	v_pk_fma_f32 v[220:221], v[100:101], v[100:101], v[220:221]
	s_waitcnt vmcnt(2)
	v_pk_add_f32 v[150:151], v[150:151], v[166:167]
	v_pk_add_f32 v[6:7], v[6:7], v[22:23]
	v_pk_add_f32 v[150:151], v[150:151], v[6:7]
	v_pk_fma_f32 v[102:103], v[134:135], v[150:151], v[102:103]
	v_pk_add_f32 v[152:153], v[152:153], v[168:169]
	v_pk_add_f32 v[8:9], v[8:9], v[24:25]
	v_pk_add_f32 v[152:153], v[152:153], v[8:9]
	v_pk_fma_f32 v[104:105], v[136:137], v[152:153], v[104:105]
	v_pk_fma_f32 v[220:221], v[102:103], v[102:103], v[220:221]
	v_pk_fma_f32 v[220:221], v[104:105], v[104:105], v[220:221]
	s_waitcnt vmcnt(1)
	v_pk_add_f32 v[154:155], v[154:155], v[170:171]
	v_pk_add_f32 v[10:11], v[10:11], v[26:27]
	v_pk_add_f32 v[154:155], v[154:155], v[10:11]
	v_pk_fma_f32 v[106:107], v[138:139], v[154:155], v[106:107]
	v_pk_add_f32 v[156:157], v[156:157], v[172:173]
	v_pk_add_f32 v[12:13], v[12:13], v[28:29]
	v_pk_add_f32 v[156:157], v[156:157], v[12:13]
	v_pk_fma_f32 v[108:109], v[140:141], v[156:157], v[108:109]
	v_pk_fma_f32 v[220:221], v[106:107], v[106:107], v[220:221]
	v_pk_fma_f32 v[220:221], v[108:109], v[108:109], v[220:221]
	s_waitcnt vmcnt(0)
	v_pk_add_f32 v[158:159], v[158:159], v[174:175]
	v_pk_add_f32 v[14:15], v[14:15], v[30:31]
	v_pk_add_f32 v[158:159], v[158:159], v[14:15]
	v_pk_fma_f32 v[110:111], v[142:143], v[158:159], v[110:111]
	v_pk_add_f32 v[160:161], v[160:161], v[176:177]
	v_pk_add_f32 v[16:17], v[16:17], v[32:33]
	v_pk_add_f32 v[160:161], v[160:161], v[16:17]
	v_pk_fma_f32 v[112:113], v[144:145], v[160:161], v[112:113]
	v_pk_fma_f32 v[220:221], v[110:111], v[110:111], v[220:221]
	v_pk_fma_f32 v[220:221], v[112:113], v[112:113], v[220:221]
	global_load_dwordx4 v[130:133], v181, s[40:41]
	global_load_dwordx4 v[134:137], v181, s[40:41] offset:1024
	global_load_dwordx4 v[138:141], v181, s[40:41] offset:2048
	global_load_dwordx4 v[142:145], v181, s[40:41] offset:3072
	s_mov_b64 s[68:69], s[70:71]
	global_load_dwordx4 v[146:149], v181, s[68:69] nt
	global_load_dwordx4 v[150:153], v181, s[68:69] offset:1024 nt
	global_load_dwordx4 v[154:157], v181, s[68:69] offset:2048 nt
	global_load_dwordx4 v[158:161], v181, s[68:69] offset:3072 nt
	s_add_u32 s68, s68, 0x1000000
	s_addc_u32 s69, s69, 0
	global_load_dwordx4 v[162:165], v181, s[68:69] nt
	global_load_dwordx4 v[166:169], v181, s[68:69] offset:1024 nt
	global_load_dwordx4 v[170:173], v181, s[68:69] offset:2048 nt
	global_load_dwordx4 v[174:177], v181, s[68:69] offset:3072 nt
	s_add_u32 s68, s68, 0x1000000
	s_addc_u32 s69, s69, 0
	global_load_dwordx4 v[2:5], v181, s[68:69] nt
	global_load_dwordx4 v[6:9], v181, s[68:69] offset:1024 nt
	global_load_dwordx4 v[10:13], v181, s[68:69] offset:2048 nt
	global_load_dwordx4 v[14:17], v181, s[68:69] offset:3072 nt
	s_add_u32 s68, s68, 0x1000000
	s_addc_u32 s69, s69, 0
	global_load_dwordx4 v[18:21], v181, s[68:69] nt
	global_load_dwordx4 v[22:25], v181, s[68:69] offset:1024 nt
	global_load_dwordx4 v[26:29], v181, s[68:69] offset:2048 nt
	global_load_dwordx4 v[30:33], v181, s[68:69] offset:3072 nt
	s_waitcnt vmcnt(3)
	v_pk_add_f32 v[146:147], v[146:147], v[162:163]
	v_pk_add_f32 v[2:3], v[2:3], v[18:19]
	v_pk_add_f32 v[146:147], v[146:147], v[2:3]
	v_pk_fma_f32 v[114:115], v[130:131], v[146:147], v[114:115]
	v_pk_add_f32 v[148:149], v[148:149], v[164:165]
	v_pk_add_f32 v[4:5], v[4:5], v[20:21]
	v_pk_add_f32 v[148:149], v[148:149], v[4:5]
	v_pk_fma_f32 v[116:117], v[132:133], v[148:149], v[116:117]
	v_pk_fma_f32 v[220:221], v[114:115], v[114:115], v[220:221]
	v_pk_fma_f32 v[220:221], v[116:117], v[116:117], v[220:221]
	s_waitcnt vmcnt(2)
	v_pk_add_f32 v[150:151], v[150:151], v[166:167]
	v_pk_add_f32 v[6:7], v[6:7], v[22:23]
	v_pk_add_f32 v[150:151], v[150:151], v[6:7]
	v_pk_fma_f32 v[118:119], v[134:135], v[150:151], v[118:119]
	v_pk_add_f32 v[152:153], v[152:153], v[168:169]
	v_pk_add_f32 v[8:9], v[8:9], v[24:25]
	v_pk_add_f32 v[152:153], v[152:153], v[8:9]
	v_pk_fma_f32 v[120:121], v[136:137], v[152:153], v[120:121]
	v_pk_fma_f32 v[220:221], v[118:119], v[118:119], v[220:221]
	v_pk_fma_f32 v[220:221], v[120:121], v[120:121], v[220:221]
	s_waitcnt vmcnt(1)
	v_pk_add_f32 v[154:155], v[154:155], v[170:171]
	v_pk_add_f32 v[10:11], v[10:11], v[26:27]
	v_pk_add_f32 v[154:155], v[154:155], v[10:11]
	v_pk_fma_f32 v[122:123], v[138:139], v[154:155], v[122:123]
	v_pk_add_f32 v[156:157], v[156:157], v[172:173]
	v_pk_add_f32 v[12:13], v[12:13], v[28:29]
	v_pk_add_f32 v[156:157], v[156:157], v[12:13]
	v_pk_fma_f32 v[124:125], v[140:141], v[156:157], v[124:125]
	v_pk_fma_f32 v[220:221], v[122:123], v[122:123], v[220:221]
	v_pk_fma_f32 v[220:221], v[124:125], v[124:125], v[220:221]
	s_waitcnt vmcnt(0)
	v_pk_add_f32 v[158:159], v[158:159], v[174:175]
	v_pk_add_f32 v[14:15], v[14:15], v[30:31]
	v_pk_add_f32 v[158:159], v[158:159], v[14:15]
	v_pk_fma_f32 v[126:127], v[142:143], v[158:159], v[126:127]
	v_pk_add_f32 v[160:161], v[160:161], v[176:177]
	v_pk_add_f32 v[16:17], v[16:17], v[32:33]
	v_pk_add_f32 v[160:161], v[160:161], v[16:17]
	v_pk_fma_f32 v[128:129], v[144:145], v[160:161], v[128:129]
	v_pk_fma_f32 v[220:221], v[126:127], v[126:127], v[220:221]
	v_pk_fma_f32 v[220:221], v[128:129], v[128:129], v[220:221]
	v_add_f32_e32 v217, v220, v221
	s_nop 1
	v_add_f32_dpp v217, v217, v217 row_shr:1 row_mask:0xf bank_mask:0xf bound_ctrl:1
	s_nop 1
	v_add_f32_dpp v217, v217, v217 row_shr:2 row_mask:0xf bank_mask:0xf bound_ctrl:1
	s_nop 1
	v_add_f32_dpp v217, v217, v217 row_shr:4 row_mask:0xf bank_mask:0xf bound_ctrl:1
	s_nop 1
	v_add_f32_dpp v217, v217, v217 row_shr:8 row_mask:0xf bank_mask:0xf bound_ctrl:1
	v_mov_b32_e32 v222, v195
	s_nop 1
	v_mov_b32_dpp v222, v217 row_bcast:15 row_mask:0xa bank_mask:0xf bound_ctrl:1
	v_add_f32_e32 v217, v217, v222
	v_mov_b32_e32 v222, v195
	s_nop 1
	v_mov_b32_dpp v222, v217 row_bcast:31 row_mask:0xc bank_mask:0xf bound_ctrl:1
	v_add_f32_e32 v217, v217, v222
	s_nop 1
	v_readlane_b32 s0, v217, 63
	s_nop 3
	v_fma_f32 v217, s0, v209, v202
	v_cmp_gt_f32_e32 vcc, s25, v217
	v_mul_f32_e32 v222, 0x4f800000, v217
	s_nop 1
	v_cndmask_b32_e32 v217, v217, v222, vcc
	v_sqrt_f32_e32 v222, v217
	s_nop 1
	v_add_u32_e32 v223, -1, v222
	v_fma_f32 v226, -v223, v222, v217
	v_cmp_ge_f32_e64 s[68:69], 0, v226
	v_add_u32_e32 v226, 1, v222
	s_nop 1
	v_cndmask_b32_e64 v223, v222, v223, s[68:69]
	v_fma_f32 v222, -v226, v222, v217
	v_cmp_lt_f32_e64 s[68:69], 0, v222
	s_nop 1
	v_cndmask_b32_e64 v222, v223, v226, s[68:69]
	v_mul_f32_e32 v223, 0x37800000, v222
	v_cndmask_b32_e32 v222, v222, v223, vcc
	v_cmp_class_f32_e32 vcc, v217, v203
	s_nop 1
	v_cndmask_b32_e32 v217, v222, v217, vcc
	v_div_scale_f32 v222, s[68:69], v217, v217, 1.0
	v_rcp_f32_e32 v223, v222
	s_nop 1
	v_fma_f32 v226, -v222, v223, 1.0
	v_fmac_f32_e32 v223, v226, v223
	v_div_scale_f32 v226, vcc, 1.0, v217, 1.0
	v_mul_f32_e32 v227, v226, v223
	v_fma_f32 v194, -v222, v227, v226
	v_fmac_f32_e32 v227, v194, v223
	v_fma_f32 v222, -v222, v227, v226
	s_nop 1
	v_div_fmas_f32 v222, v222, v223, v227
	v_div_fixup_f32 v200, v222, v217, 1.0
	global_load_dwordx4 v[130:133], v178, s[48:49]
	global_load_dwordx4 v[134:137], v178, s[12:13]
	global_load_dwordx4 v[138:141], v178, s[38:39]
	global_load_dwordx4 v[142:145], v178, s[48:49] offset:1024
	global_load_dwordx4 v[146:149], v178, s[12:13] offset:1024
	global_load_dwordx4 v[150:153], v178, s[38:39] offset:1024
	global_load_dwordx4 v[154:157], v178, s[48:49] offset:2048
	global_load_dwordx4 v[158:161], v178, s[12:13] offset:2048
	global_load_dwordx4 v[162:165], v178, s[38:39] offset:2048
	global_load_dwordx4 v[166:169], v178, s[48:49] offset:3072
	global_load_dwordx4 v[170:173], v178, s[12:13] offset:3072
	global_load_dwordx4 v[174:177], v178, s[38:39] offset:3072
	v_pk_mul_f32 v[66:67], v[66:67], v[200:201] op_sel_hi:[1,0]
	v_pk_mul_f32 v[68:69], v[68:69], v[200:201] op_sel_hi:[1,0]
	s_waitcnt vmcnt(11)
	v_pk_mul_f32 v[66:67], v[130:131], v[66:67]
	v_pk_mul_f32 v[68:69], v[132:133], v[68:69]
	s_waitcnt vmcnt(9)
	v_pk_add_f32 v[138:139], v[138:139], 1.0 op_sel_hi:[1,0]
	v_pk_add_f32 v[140:141], v[140:141], 1.0 op_sel_hi:[1,0]
	v_pk_fma_f32 v[66:67], v[66:67], v[138:139], v[134:135]
	v_pk_fma_f32 v[68:69], v[68:69], v[140:141], v[136:137]
	s_nop 0
	v_cvt_pk_bf16_f32 v66, v66, v67
	v_cvt_pk_bf16_f32 v67, v68, v69
	global_load_dwordx4 v[130:133], v179, s[48:49]
	global_load_dwordx4 v[134:137], v179, s[12:13]
	global_load_dwordx4 v[138:141], v179, s[38:39]
	global_store_dwordx2 v182, v[66:67], s[10:11]
	s_waitcnt lgkmcnt(6)
	ds_write_b64 v185, v[66:67]
	v_pk_mul_f32 v[70:71], v[70:71], v[200:201] op_sel_hi:[1,0]
	v_pk_mul_f32 v[72:73], v[72:73], v[200:201] op_sel_hi:[1,0]
	s_waitcnt vmcnt(12)
	v_pk_mul_f32 v[70:71], v[142:143], v[70:71]
	v_pk_mul_f32 v[72:73], v[144:145], v[72:73]
	s_waitcnt vmcnt(10)
	v_pk_add_f32 v[150:151], v[150:151], 1.0 op_sel_hi:[1,0]
	v_pk_add_f32 v[152:153], v[152:153], 1.0 op_sel_hi:[1,0]
	v_pk_fma_f32 v[70:71], v[70:71], v[150:151], v[146:147]
	v_pk_fma_f32 v[72:73], v[72:73], v[152:153], v[148:149]
	s_nop 0
	v_cvt_pk_bf16_f32 v70, v70, v71
	v_cvt_pk_bf16_f32 v71, v72, v73
	global_load_dwordx4 v[142:145], v179, s[48:49] offset:1024
	global_load_dwordx4 v[146:149], v179, s[12:13] offset:1024
	global_load_dwordx4 v[150:153], v179, s[38:39] offset:1024
	global_store_dwordx2 v182, v[70:71], s[10:11] offset:512
	s_waitcnt lgkmcnt(6)
	ds_write_b64 v185, v[70:71] offset:512
	v_pk_mul_f32 v[74:75], v[74:75], v[200:201] op_sel_hi:[1,0]
	v_pk_mul_f32 v[76:77], v[76:77], v[200:201] op_sel_hi:[1,0]
	s_waitcnt vmcnt(13)
	v_pk_mul_f32 v[74:75], v[154:155], v[74:75]
	v_pk_mul_f32 v[76:77], v[156:157], v[76:77]
	s_waitcnt vmcnt(11)
	v_pk_add_f32 v[162:163], v[162:163], 1.0 op_sel_hi:[1,0]
	v_pk_add_f32 v[164:165], v[164:165], 1.0 op_sel_hi:[1,0]
	v_pk_fma_f32 v[74:75], v[74:75], v[162:163], v[158:159]
	v_pk_fma_f32 v[76:77], v[76:77], v[164:165], v[160:161]
	s_nop 0
	v_cvt_pk_bf16_f32 v74, v74, v75
	v_cvt_pk_bf16_f32 v75, v76, v77
	global_load_dwordx4 v[154:157], v179, s[48:49] offset:2048
	global_load_dwordx4 v[158:161], v179, s[12:13] offset:2048
	global_load_dwordx4 v[162:165], v179, s[38:39] offset:2048
	global_store_dwordx2 v182, v[74:75], s[10:11] offset:1024
	s_waitcnt lgkmcnt(6)
	ds_write_b64 v185, v[74:75] offset:1024
	v_pk_mul_f32 v[78:79], v[78:79], v[200:201] op_sel_hi:[1,0]
	v_pk_mul_f32 v[80:81], v[80:81], v[200:201] op_sel_hi:[1,0]
	s_waitcnt vmcnt(14)
	v_pk_mul_f32 v[78:79], v[166:167], v[78:79]
	v_pk_mul_f32 v[80:81], v[168:169], v[80:81]
	s_waitcnt vmcnt(12)
	v_pk_add_f32 v[174:175], v[174:175], 1.0 op_sel_hi:[1,0]
	v_pk_add_f32 v[176:177], v[176:177], 1.0 op_sel_hi:[1,0]
	v_pk_fma_f32 v[78:79], v[78:79], v[174:175], v[170:171]
	v_pk_fma_f32 v[80:81], v[80:81], v[176:177], v[172:173]
	s_nop 0
	v_cvt_pk_bf16_f32 v78, v78, v79
	v_cvt_pk_bf16_f32 v79, v80, v81
	global_load_dwordx4 v[166:169], v179, s[48:49] offset:3072
	global_load_dwordx4 v[170:173], v179, s[12:13] offset:3072
	global_load_dwordx4 v[174:177], v179, s[38:39] offset:3072
	global_store_dwordx2 v182, v[78:79], s[10:11] offset:1536
	s_waitcnt lgkmcnt(6)
	ds_write_b64 v185, v[78:79] offset:1536
	v_pk_mul_f32 v[82:83], v[82:83], v[200:201] op_sel_hi:[1,0]
	v_pk_mul_f32 v[84:85], v[84:85], v[200:201] op_sel_hi:[1,0]
	s_waitcnt vmcnt(15)
	v_pk_mul_f32 v[82:83], v[130:131], v[82:83]
	v_pk_mul_f32 v[84:85], v[132:133], v[84:85]
	s_waitcnt vmcnt(13)
	v_pk_add_f32 v[138:139], v[138:139], 1.0 op_sel_hi:[1,0]
	v_pk_add_f32 v[140:141], v[140:141], 1.0 op_sel_hi:[1,0]
	v_pk_fma_f32 v[82:83], v[82:83], v[138:139], v[134:135]
	v_pk_fma_f32 v[84:85], v[84:85], v[140:141], v[136:137]
	s_nop 0
	v_cvt_pk_bf16_f32 v82, v82, v83
	v_cvt_pk_bf16_f32 v83, v84, v85
	global_load_dwordx4 v[130:133], v180, s[48:49]
	global_load_dwordx4 v[134:137], v180, s[12:13]
	global_load_dwordx4 v[138:141], v180, s[38:39]
	global_store_dwordx2 v182, v[82:83], s[10:11] offset:2048
	s_waitcnt lgkmcnt(6)
	ds_write_b64 v185, v[82:83] offset:2048
	v_pk_mul_f32 v[86:87], v[86:87], v[200:201] op_sel_hi:[1,0]
	v_pk_mul_f32 v[88:89], v[88:89], v[200:201] op_sel_hi:[1,0]
	s_waitcnt vmcnt(15)
	v_pk_mul_f32 v[86:87], v[142:143], v[86:87]
	v_pk_mul_f32 v[88:89], v[144:145], v[88:89]
	s_waitcnt vmcnt(13)
	v_pk_add_f32 v[150:151], v[150:151], 1.0 op_sel_hi:[1,0]
	v_pk_add_f32 v[152:153], v[152:153], 1.0 op_sel_hi:[1,0]
	v_pk_fma_f32 v[86:87], v[86:87], v[150:151], v[146:147]
	v_pk_fma_f32 v[88:89], v[88:89], v[152:153], v[148:149]
	s_nop 0
	v_cvt_pk_bf16_f32 v86, v86, v87
	v_cvt_pk_bf16_f32 v87, v88, v89
	global_load_dwordx4 v[142:145], v180, s[48:49] offset:1024
	global_load_dwordx4 v[146:149], v180, s[12:13] offset:1024
	global_load_dwordx4 v[150:153], v180, s[38:39] offset:1024
	global_store_dwordx2 v182, v[86:87], s[10:11] offset:2560
	s_waitcnt lgkmcnt(6)
	ds_write_b64 v185, v[86:87] offset:2560
	v_pk_mul_f32 v[90:91], v[90:91], v[200:201] op_sel_hi:[1,0]
	v_pk_mul_f32 v[92:93], v[92:93], v[200:201] op_sel_hi:[1,0]
	s_waitcnt vmcnt(15)
	v_pk_mul_f32 v[90:91], v[154:155], v[90:91]
	v_pk_mul_f32 v[92:93], v[156:157], v[92:93]
	s_waitcnt vmcnt(13)
	v_pk_add_f32 v[162:163], v[162:163], 1.0 op_sel_hi:[1,0]
	v_pk_add_f32 v[164:165], v[164:165], 1.0 op_sel_hi:[1,0]
	v_pk_fma_f32 v[90:91], v[90:91], v[162:163], v[158:159]
	v_pk_fma_f32 v[92:93], v[92:93], v[164:165], v[160:161]
	s_nop 0
	v_cvt_pk_bf16_f32 v90, v90, v91
	v_cvt_pk_bf16_f32 v91, v92, v93
	global_load_dwordx4 v[154:157], v180, s[48:49] offset:2048
	global_load_dwordx4 v[158:161], v180, s[12:13] offset:2048
	global_load_dwordx4 v[162:165], v180, s[38:39] offset:2048
	global_store_dwordx2 v182, v[90:91], s[10:11] offset:3072
	s_waitcnt lgkmcnt(6)
	ds_write_b64 v185, v[90:91] offset:3072
	v_pk_mul_f32 v[94:95], v[94:95], v[200:201] op_sel_hi:[1,0]
	v_pk_mul_f32 v[96:97], v[96:97], v[200:201] op_sel_hi:[1,0]
	s_waitcnt vmcnt(15)
	v_pk_mul_f32 v[94:95], v[166:167], v[94:95]
	v_pk_mul_f32 v[96:97], v[168:169], v[96:97]
	s_waitcnt vmcnt(13)
	v_pk_add_f32 v[174:175], v[174:175], 1.0 op_sel_hi:[1,0]
	v_pk_add_f32 v[176:177], v[176:177], 1.0 op_sel_hi:[1,0]
	v_pk_fma_f32 v[94:95], v[94:95], v[174:175], v[170:171]
	v_pk_fma_f32 v[96:97], v[96:97], v[176:177], v[172:173]
	s_nop 0
	v_cvt_pk_bf16_f32 v94, v94, v95
	v_cvt_pk_bf16_f32 v95, v96, v97
	global_load_dwordx4 v[166:169], v180, s[48:49] offset:3072
	global_load_dwordx4 v[170:173], v180, s[12:13] offset:3072
	global_load_dwordx4 v[174:177], v180, s[38:39] offset:3072
	global_store_dwordx2 v182, v[94:95], s[10:11] offset:3584
	s_waitcnt lgkmcnt(6)
	ds_write_b64 v185, v[94:95] offset:3584
	v_pk_mul_f32 v[98:99], v[98:99], v[200:201] op_sel_hi:[1,0]
	v_pk_mul_f32 v[100:101], v[100:101], v[200:201] op_sel_hi:[1,0]
	s_waitcnt vmcnt(15)
	v_pk_mul_f32 v[98:99], v[130:131], v[98:99]
	v_pk_mul_f32 v[100:101], v[132:133], v[100:101]
	s_waitcnt vmcnt(13)
	v_pk_add_f32 v[138:139], v[138:139], 1.0 op_sel_hi:[1,0]
	v_pk_add_f32 v[140:141], v[140:141], 1.0 op_sel_hi:[1,0]
	v_pk_fma_f32 v[98:99], v[98:99], v[138:139], v[134:135]
	v_pk_fma_f32 v[100:101], v[100:101], v[140:141], v[136:137]
	s_nop 0
	v_cvt_pk_bf16_f32 v98, v98, v99
	v_cvt_pk_bf16_f32 v99, v100, v101
	global_load_dwordx4 v[130:133], v181, s[48:49]
	global_load_dwordx4 v[134:137], v181, s[12:13]
	global_load_dwordx4 v[138:141], v181, s[38:39]
	global_store_dwordx2 v183, v[98:99], s[10:11]
	s_waitcnt lgkmcnt(6)
	ds_write_b64 v185, v[98:99] offset:4096
	v_pk_mul_f32 v[102:103], v[102:103], v[200:201] op_sel_hi:[1,0]
	v_pk_mul_f32 v[104:105], v[104:105], v[200:201] op_sel_hi:[1,0]
	s_waitcnt vmcnt(15)
	v_pk_mul_f32 v[102:103], v[142:143], v[102:103]
	v_pk_mul_f32 v[104:105], v[144:145], v[104:105]
	s_waitcnt vmcnt(13)
	v_pk_add_f32 v[150:151], v[150:151], 1.0 op_sel_hi:[1,0]
	v_pk_add_f32 v[152:153], v[152:153], 1.0 op_sel_hi:[1,0]
	v_pk_fma_f32 v[102:103], v[102:103], v[150:151], v[146:147]
	v_pk_fma_f32 v[104:105], v[104:105], v[152:153], v[148:149]
	s_nop 0
	v_cvt_pk_bf16_f32 v102, v102, v103
	v_cvt_pk_bf16_f32 v103, v104, v105
	global_load_dwordx4 v[142:145], v181, s[48:49] offset:1024
	global_load_dwordx4 v[146:149], v181, s[12:13] offset:1024
	global_load_dwordx4 v[150:153], v181, s[38:39] offset:1024
	global_store_dwordx2 v183, v[102:103], s[10:11] offset:512
	s_waitcnt lgkmcnt(6)
	ds_write_b64 v185, v[102:103] offset:4608
	v_pk_mul_f32 v[106:107], v[106:107], v[200:201] op_sel_hi:[1,0]
	v_pk_mul_f32 v[108:109], v[108:109], v[200:201] op_sel_hi:[1,0]
	s_waitcnt vmcnt(15)
	v_pk_mul_f32 v[106:107], v[154:155], v[106:107]
	v_pk_mul_f32 v[108:109], v[156:157], v[108:109]
	s_waitcnt vmcnt(13)
	v_pk_add_f32 v[162:163], v[162:163], 1.0 op_sel_hi:[1,0]
	v_pk_add_f32 v[164:165], v[164:165], 1.0 op_sel_hi:[1,0]
	v_pk_fma_f32 v[106:107], v[106:107], v[162:163], v[158:159]
	v_pk_fma_f32 v[108:109], v[108:109], v[164:165], v[160:161]
	s_nop 0
	v_cvt_pk_bf16_f32 v106, v106, v107
	v_cvt_pk_bf16_f32 v107, v108, v109
	global_load_dwordx4 v[154:157], v181, s[48:49] offset:2048
	global_load_dwordx4 v[158:161], v181, s[12:13] offset:2048
	global_load_dwordx4 v[162:165], v181, s[38:39] offset:2048
	global_store_dwordx2 v183, v[106:107], s[10:11] offset:1024
	s_waitcnt lgkmcnt(6)
	ds_write_b64 v185, v[106:107] offset:5120
	v_pk_mul_f32 v[110:111], v[110:111], v[200:201] op_sel_hi:[1,0]
	v_pk_mul_f32 v[112:113], v[112:113], v[200:201] op_sel_hi:[1,0]
	s_waitcnt vmcnt(15)
	v_pk_mul_f32 v[110:111], v[166:167], v[110:111]
	v_pk_mul_f32 v[112:113], v[168:169], v[112:113]
	s_waitcnt vmcnt(13)
	v_pk_add_f32 v[174:175], v[174:175], 1.0 op_sel_hi:[1,0]
	v_pk_add_f32 v[176:177], v[176:177], 1.0 op_sel_hi:[1,0]
	v_pk_fma_f32 v[110:111], v[110:111], v[174:175], v[170:171]
	v_pk_fma_f32 v[112:113], v[112:113], v[176:177], v[172:173]
	s_nop 0
	v_cvt_pk_bf16_f32 v110, v110, v111
	v_cvt_pk_bf16_f32 v111, v112, v113
	global_load_dwordx4 v[166:169], v181, s[48:49] offset:3072
	global_load_dwordx4 v[170:173], v181, s[12:13] offset:3072
	global_load_dwordx4 v[174:177], v181, s[38:39] offset:3072
	global_store_dwordx2 v183, v[110:111], s[10:11] offset:1536
	s_waitcnt lgkmcnt(6)
	ds_write_b64 v185, v[110:111] offset:5632
	v_pk_mul_f32 v[114:115], v[114:115], v[200:201] op_sel_hi:[1,0]
	v_pk_mul_f32 v[116:117], v[116:117], v[200:201] op_sel_hi:[1,0]
	s_waitcnt vmcnt(15)
	v_pk_mul_f32 v[114:115], v[130:131], v[114:115]
	v_pk_mul_f32 v[116:117], v[132:133], v[116:117]
	s_waitcnt vmcnt(13)
	v_pk_add_f32 v[138:139], v[138:139], 1.0 op_sel_hi:[1,0]
	v_pk_add_f32 v[140:141], v[140:141], 1.0 op_sel_hi:[1,0]
	v_pk_fma_f32 v[114:115], v[114:115], v[138:139], v[134:135]
	v_pk_fma_f32 v[116:117], v[116:117], v[140:141], v[136:137]
	s_nop 0
	v_cvt_pk_bf16_f32 v114, v114, v115
	v_cvt_pk_bf16_f32 v115, v116, v117
	global_store_dwordx2 v183, v[114:115], s[10:11] offset:2048
	s_waitcnt lgkmcnt(6)
	ds_write_b64 v185, v[114:115] offset:6144
	v_pk_mul_f32 v[118:119], v[118:119], v[200:201] op_sel_hi:[1,0]
	v_pk_mul_f32 v[120:121], v[120:121], v[200:201] op_sel_hi:[1,0]
	s_waitcnt vmcnt(12)
	v_pk_mul_f32 v[118:119], v[142:143], v[118:119]
	v_pk_mul_f32 v[120:121], v[144:145], v[120:121]
	s_waitcnt vmcnt(10)
	v_pk_add_f32 v[150:151], v[150:151], 1.0 op_sel_hi:[1,0]
	v_pk_add_f32 v[152:153], v[152:153], 1.0 op_sel_hi:[1,0]
	v_pk_fma_f32 v[118:119], v[118:119], v[150:151], v[146:147]
	v_pk_fma_f32 v[120:121], v[120:121], v[152:153], v[148:149]
	s_nop 0
	v_cvt_pk_bf16_f32 v118, v118, v119
	v_cvt_pk_bf16_f32 v119, v120, v121
	global_store_dwordx2 v183, v[118:119], s[10:11] offset:2560
	s_waitcnt lgkmcnt(6)
	ds_write_b64 v185, v[118:119] offset:6656
	v_pk_mul_f32 v[122:123], v[122:123], v[200:201] op_sel_hi:[1,0]
	v_pk_mul_f32 v[124:125], v[124:125], v[200:201] op_sel_hi:[1,0]
	s_waitcnt vmcnt(9)
	v_pk_mul_f32 v[122:123], v[154:155], v[122:123]
	v_pk_mul_f32 v[124:125], v[156:157], v[124:125]
	s_waitcnt vmcnt(7)
	v_pk_add_f32 v[162:163], v[162:163], 1.0 op_sel_hi:[1,0]
	v_pk_add_f32 v[164:165], v[164:165], 1.0 op_sel_hi:[1,0]
	v_pk_fma_f32 v[122:123], v[122:123], v[162:163], v[158:159]
	v_pk_fma_f32 v[124:125], v[124:125], v[164:165], v[160:161]
	s_nop 0
	v_cvt_pk_bf16_f32 v122, v122, v123
	v_cvt_pk_bf16_f32 v123, v124, v125
	global_store_dwordx2 v183, v[122:123], s[10:11] offset:3072
	s_waitcnt lgkmcnt(6)
	ds_write_b64 v185, v[122:123] offset:7168
	v_pk_mul_f32 v[126:127], v[126:127], v[200:201] op_sel_hi:[1,0]
	v_pk_mul_f32 v[128:129], v[128:129], v[200:201] op_sel_hi:[1,0]
	s_waitcnt vmcnt(6)
	v_pk_mul_f32 v[126:127], v[166:167], v[126:127]
	v_pk_mul_f32 v[128:129], v[168:169], v[128:129]
	s_waitcnt vmcnt(4)
	v_pk_add_f32 v[174:175], v[174:175], 1.0 op_sel_hi:[1,0]
	v_pk_add_f32 v[176:177], v[176:177], 1.0 op_sel_hi:[1,0]
	v_pk_fma_f32 v[126:127], v[126:127], v[174:175], v[170:171]
	v_pk_fma_f32 v[128:129], v[128:129], v[176:177], v[172:173]
	s_nop 0
	v_cvt_pk_bf16_f32 v126, v126, v127
	v_cvt_pk_bf16_f32 v127, v128, v129
	global_store_dwordx2 v183, v[126:127], s[10:11] offset:3584
	s_waitcnt lgkmcnt(6)
	ds_write_b64 v185, v[126:127] offset:7680
	global_load_dwordx4 v[2:5], v190, s[56:57]
	global_load_dwordx4 v[6:9], v190, s[56:57] offset:64
	global_load_dwordx4 v[10:13], v190, s[56:57] offset:128
	global_load_dwordx4 v[14:17], v190, s[56:57] offset:192
	global_load_dwordx4 v[18:21], v190, s[56:57] offset:256
	global_load_dwordx4 v[22:25], v190, s[56:57] offset:320
	global_load_dwordx4 v[26:29], v190, s[56:57] offset:384
	global_load_dwordx4 v[30:33], v190, s[56:57] offset:448
	global_load_dwordx4 v[34:37], v190, s[56:57] offset:512
	global_load_dwordx4 v[38:41], v190, s[56:57] offset:576
	global_load_dwordx4 v[42:45], v190, s[56:57] offset:640
	global_load_dwordx4 v[46:49], v190, s[56:57] offset:704
	global_load_dwordx4 v[50:53], v190, s[56:57] offset:768
	global_load_dwordx4 v[54:57], v190, s[56:57] offset:832
	global_load_dwordx4 v[58:61], v190, s[56:57] offset:896
	global_load_dwordx4 v[62:65], v190, s[56:57] offset:960
